# loop-edge: GEMM K-loop counter/pointer updates and exit compare moved above the loop-back s_barrier in all 10 GEMM loops
# baseline (speedup 1.0000x reference)
; #define PG8_STAGE(bufoff, gbase, voff) do { _Pragma("unroll") for (int _i = 0; _i < 2; ++_i) \
;         __builtin_amdgcn_global_load_lds((const unsigned*)((const char*)(gbase) + (voff)[_i]), (PG8_LAS unsigned*)(lds + (bufoff) + ldsw + _i * 8192), 16, 0, 0); } while (0)
; #define PG8_LDA(dst, b, h) do { _Pragma("unroll") for (int m = 0; m < 4; ++m) _Pragma("unroll") for (int k = 0; k < 2; ++k) dst[m][k] = *(const PG8_LAS bf16x8*)(lds + PG8_SA(b, h) + aoff + m * 2048 + k * 1024); } while (0)
; #define PG8_LDB(dst, b, h) do { _Pragma("unroll") for (int n = 0; n < 2; ++n) _Pragma("unroll") for (int k = 0; k < 2; ++k) dst[n][k] = *(const PG8_LAS bf16x8*)(lds + PG8_SB(b, h) + boff + n * 2048 + k * 1024); } while (0)
; #define PG8_MMA(ai, bj, At, Bt) do { __builtin_amdgcn_s_setprio(1); _Pragma("unroll") for (int m = 0; m < 4; ++m) _Pragma("unroll") for (int n = 0; n < 2; ++n) _Pragma("unroll") for (int k = 0; k < 2; ++k) \
;         acc[ai][bj][m][n] = __builtin_amdgcn_mfma_f32_16x16x32_bf16(Bt[n][k], At[m][k], acc[ai][bj][m][n], 0, 0, 0); __builtin_amdgcn_s_setprio(0); } while (0)
; #define PG8_WAIT_V(n) asm volatile("s_waitcnt vmcnt(" #n ")" ::: "memory")
; #define PG8_WAIT_L(n) asm volatile("s_waitcnt lgkmcnt(" #n ")" ::: "memory")
; template <class Epi, class Sched, bool ALIGN_EPI = false, bool SP2 = false>
; __device__ __forceinline__ void gemm_phase(PG8_LAS unsigned char* lds, const Gemm g, const Sched& S, const Epi& E) {
;     ...
;             const bool last = (t == nt - 2);
;             const char* a1 = cA + (size_t)(t + 1) * kstep;
;             const char* a2 = last ? nA : cA + (size_t)(t + 2) * kstep; const char* b2 = last ? nB : cB + (size_t)(t + 2) * kstep;
;             const char* a3 = a2 + kstep; const char* b3 = b2 + kstep;
;             if (last && has_next) S.a_ready(nxt);
;             if constexpr (SP2) {
;             PG8_LDB(B0, 0, 0); PG8_LDB(B1, 0, 1); PG8_SCHED; PG8_LDA(At, 0, 0); PG8_STAGE(PG8_SA(1, 1), a1 + hstep, voffA);
;             PG8_WAIT_V(8); PG8_WAIT_L(0); PG8_BAR; PG8_MMA(0, 0, At, B0); PG8_MMA(0, 1, At, B1); PG8_BAR; PG8_SCHED;
;             PG8_LDA(At, 0, 1); PG8_STAGE(PG8_SB(0, 0), b2, voffB); PG8_STAGE(PG8_SB(0, 1), b2 + hstep, voffB); PG8_STAGE(PG8_SA(0, 0), a2, voffA);
;             PG8_WAIT_V(8); PG8_WAIT_L(0); PG8_BAR; PG8_MMA(1, 0, At, B0); PG8_MMA(1, 1, At, B1); PG8_BAR; PG8_SCHED;
.LBB0_194:
	s_add_u32 s3, s84, 0xfffc0080
	s_addc_u32 s28, s85, -1
	s_add_i32 s29, 0, 0x10000
	s_cmp_eq_u32 s83, 12
	s_cselect_b32 s47, s2, s28
	s_cselect_b32 s46, s30, s3
	s_cselect_b32 s87, s41, s77
	s_cselect_b32 s86, s45, s69
	s_add_i32 s3, 0, 0x14000
	v_add_u32_e32 v76, s29, v162
	v_add_u32_e32 v160, s3, v162
	ds_read_b128 v[52:55], v76
	ds_read_b128 v[60:63], v76 offset:1024
	ds_read_b128 v[68:71], v76 offset:2048
	ds_read_b128 v[76:79], v76 offset:3072
	ds_read_b128 v[152:155], v160
	ds_read_b128 v[156:159], v160 offset:1024
	ds_read_b128 v[164:167], v160 offset:2048
	ds_read_b128 v[168:171], v160 offset:3072
	v_lshl_add_u64 v[160:161], s[84:85], 0, v[148:149]
	s_add_i32 m0, s57, 0xc000
	ds_read_b128 v[172:175], v163
	ds_read_b128 v[176:179], v163 offset:1024
	ds_read_b128 v[180:183], v163 offset:2048
	ds_read_b128 v[184:187], v163 offset:3072
	ds_read_b128 v[188:191], v163 offset:4096
	ds_read_b128 v[192:195], v163 offset:5120
	ds_read_b128 v[196:199], v163 offset:6144
	ds_read_b128 v[200:203], v163 offset:7168
	global_load_lds_dwordx4 v[160:161], off
	v_lshl_add_u64 v[160:161], s[84:85], 0, v[150:151]
	s_add_i32 m0, s57, 0xe000
	s_nop 0
	global_load_lds_dwordx4 v[160:161], off
	s_waitcnt vmcnt(8)
	s_waitcnt lgkmcnt(0)
	s_barrier
	s_setprio 1
	s_waitcnt lgkmcnt(0)
	v_mfma_f32_16x16x32_bf16 v[140:143], v[52:55], v[172:175], v[140:143]
	v_mfma_f32_16x16x32_bf16 v[136:139], v[68:71], v[172:175], v[136:139]
	v_mfma_f32_16x16x32_bf16 v[124:127], v[52:55], v[180:183], v[124:127]
	v_mfma_f32_16x16x32_bf16 v[120:123], v[68:71], v[180:183], v[120:123]
	v_mfma_f32_16x16x32_bf16 v[108:111], v[52:55], v[188:191], v[108:111]
	v_mfma_f32_16x16x32_bf16 v[104:107], v[68:71], v[188:191], v[104:107]
	v_mfma_f32_16x16x32_bf16 v[92:95], v[52:55], v[196:199], v[92:95]
	v_mfma_f32_16x16x32_bf16 v[88:91], v[68:71], v[196:199], v[88:91]
	v_mfma_f32_16x16x32_bf16 v[140:143], v[60:63], v[176:179], v[140:143]
	v_mfma_f32_16x16x32_bf16 v[136:139], v[76:79], v[176:179], v[136:139]
	v_mfma_f32_16x16x32_bf16 v[124:127], v[60:63], v[184:187], v[124:127]
	v_mfma_f32_16x16x32_bf16 v[120:123], v[76:79], v[184:187], v[120:123]
	v_mfma_f32_16x16x32_bf16 v[108:111], v[60:63], v[192:195], v[108:111]
	v_mfma_f32_16x16x32_bf16 v[104:107], v[76:79], v[192:195], v[104:107]
	v_mfma_f32_16x16x32_bf16 v[92:95], v[60:63], v[200:203], v[92:95]
	v_mfma_f32_16x16x32_bf16 v[88:91], v[76:79], v[200:203], v[88:91]
	s_setprio 0
	s_setprio 1
	v_mfma_f32_16x16x32_bf16 v[132:135], v[152:155], v[172:175], v[132:135]
	v_mfma_f32_16x16x32_bf16 v[128:131], v[164:167], v[172:175], v[128:131]
	v_mfma_f32_16x16x32_bf16 v[116:119], v[152:155], v[180:183], v[116:119]
	v_mfma_f32_16x16x32_bf16 v[112:115], v[164:167], v[180:183], v[112:115]
	v_mfma_f32_16x16x32_bf16 v[100:103], v[152:155], v[188:191], v[100:103]
	v_mfma_f32_16x16x32_bf16 v[96:99], v[164:167], v[188:191], v[96:99]
	v_mfma_f32_16x16x32_bf16 v[84:87], v[152:155], v[196:199], v[84:87]
	v_mfma_f32_16x16x32_bf16 v[80:83], v[164:167], v[196:199], v[80:83]
	v_mfma_f32_16x16x32_bf16 v[132:135], v[156:159], v[176:179], v[132:135]
	v_mfma_f32_16x16x32_bf16 v[128:131], v[168:171], v[176:179], v[128:131]
	v_mfma_f32_16x16x32_bf16 v[116:119], v[156:159], v[184:187], v[116:119]
	v_mfma_f32_16x16x32_bf16 v[112:115], v[168:171], v[184:187], v[112:115]
	v_mfma_f32_16x16x32_bf16 v[100:103], v[156:159], v[192:195], v[100:103]
	v_mfma_f32_16x16x32_bf16 v[96:99], v[168:171], v[192:195], v[96:99]
	v_mfma_f32_16x16x32_bf16 v[84:87], v[156:159], v[200:203], v[84:87]
	v_mfma_f32_16x16x32_bf16 v[80:83], v[168:171], v[200:203], v[80:83]
	s_setprio 0
	s_barrier
	s_add_i32 s28, s29, s50
	v_lshl_add_u64 v[160:161], s[86:87], 0, v[144:145]
	s_mov_b32 m0, s28
	ds_read_b128 v[172:175], v163 offset:16384
	ds_read_b128 v[176:179], v163 offset:17408
	ds_read_b128 v[180:183], v163 offset:18432
	ds_read_b128 v[184:187], v163 offset:19456
	ds_read_b128 v[188:191], v163 offset:20480
	ds_read_b128 v[192:195], v163 offset:21504
	ds_read_b128 v[196:199], v163 offset:22528
	ds_read_b128 v[200:203], v163 offset:23552
	global_load_lds_dwordx4 v[160:161], off
	s_add_i32 m0, s28, 0x2000
	s_add_u32 s28, s86, 0x40000
	v_lshl_add_u64 v[204:205], s[86:87], 0, v[146:147]
	s_addc_u32 s29, s87, 0
	s_add_i32 s3, s3, s50
	global_load_lds_dwordx4 v[204:205], off
	v_lshl_add_u64 v[206:207], s[28:29], 0, v[144:145]
	s_mov_b32 m0, s3
	v_lshl_add_u64 v[214:215], s[46:47], 0, v[146:147]
	global_load_lds_dwordx4 v[206:207], off
	v_lshl_add_u64 v[206:207], s[28:29], 0, v[146:147]
	s_add_i32 m0, s3, 0x2000
	s_nop 0
	global_load_lds_dwordx4 v[206:207], off
	v_lshl_add_u64 v[206:207], s[46:47], 0, v[144:145]
	s_mov_b32 m0, s57
	s_nop 0
	global_load_lds_dwordx4 v[206:207], off
	s_mov_b32 m0, s58
	s_nop 0
	global_load_lds_dwordx4 v[214:215], off
	s_waitcnt vmcnt(8)
	s_waitcnt lgkmcnt(0)
	s_barrier
; #define PG8_STAGE(bufoff, gbase, voff) do { _Pragma("unroll") for (int _i = 0; _i < 2; ++_i) \
;         __builtin_amdgcn_global_load_lds((const unsigned*)((const char*)(gbase) + (voff)[_i]), (PG8_LAS unsigned*)(lds + (bufoff) + ldsw + _i * 8192), 16, 0, 0); } while (0)
; #define PG8_LDA(dst, b, h) do { _Pragma("unroll") for (int m = 0; m < 4; ++m) _Pragma("unroll") for (int k = 0; k < 2; ++k) dst[m][k] = *(const PG8_LAS bf16x8*)(lds + PG8_SA(b, h) + aoff + m * 2048 + k * 1024); } while (0)
; #define PG8_LDB(dst, b, h) do { _Pragma("unroll") for (int n = 0; n < 2; ++n) _Pragma("unroll") for (int k = 0; k < 2; ++k) dst[n][k] = *(const PG8_LAS bf16x8*)(lds + PG8_SB(b, h) + boff + n * 2048 + k * 1024); } while (0)
; #define PG8_MMA(ai, bj, At, Bt) do { __builtin_amdgcn_s_setprio(1); _Pragma("unroll") for (int m = 0; m < 4; ++m) _Pragma("unroll") for (int n = 0; n < 2; ++n) _Pragma("unroll") for (int k = 0; k < 2; ++k) \
;         acc[ai][bj][m][n] = __builtin_amdgcn_mfma_f32_16x16x32_bf16(Bt[n][k], At[m][k], acc[ai][bj][m][n], 0, 0, 0); __builtin_amdgcn_s_setprio(0); } while (0)
; #define PG8_WAIT_V(n) asm volatile("s_waitcnt vmcnt(" #n ")" ::: "memory")
; #define PG8_WAIT_L(n) asm volatile("s_waitcnt lgkmcnt(" #n ")" ::: "memory")
; #define PG8_BAR __builtin_amdgcn_s_barrier()
; #define PG8_SCHED __builtin_amdgcn_sched_barrier(0)
; template <class Epi, class Sched, bool ALIGN_EPI = false, bool SP2 = false>
; __device__ __forceinline__ void gemm_phase(PG8_LAS unsigned char* lds, const Gemm g, const Sched& S, const Epi& E) {
;     ...
;             PG8_WAIT_V(8); PG8_WAIT_L(0); PG8_BAR; PG8_MMA(1, 0, At, B0); PG8_MMA(1, 1, At, B1); PG8_BAR; PG8_SCHED;
;             PG8_LDB(B0, 1, 0); PG8_LDB(B1, 1, 1); PG8_SCHED; PG8_LDA(At, 1, 0); PG8_STAGE(PG8_SA(0, 1), a2 + hstep, voffA);
;             PG8_WAIT_V(8); PG8_WAIT_L(0); PG8_BAR; PG8_MMA(0, 0, At, B0); PG8_MMA(0, 1, At, B1); PG8_BAR; PG8_SCHED;
	s_setprio 1
	s_waitcnt lgkmcnt(0)
	v_mfma_f32_16x16x32_bf16 v[72:75], v[52:55], v[172:175], v[72:75]
	v_mfma_f32_16x16x32_bf16 v[64:67], v[68:71], v[172:175], v[64:67]
	v_mfma_f32_16x16x32_bf16 v[44:47], v[52:55], v[180:183], v[44:47]
	v_mfma_f32_16x16x32_bf16 v[40:43], v[68:71], v[180:183], v[40:43]
	v_mfma_f32_16x16x32_bf16 v[28:31], v[52:55], v[188:191], v[28:31]
	v_mfma_f32_16x16x32_bf16 v[24:27], v[68:71], v[188:191], v[24:27]
	v_mfma_f32_16x16x32_bf16 v[12:15], v[52:55], v[196:199], v[12:15]
	v_mfma_f32_16x16x32_bf16 v[8:11], v[68:71], v[196:199], v[8:11]
	v_mfma_f32_16x16x32_bf16 v[72:75], v[60:63], v[176:179], v[72:75]
	v_mfma_f32_16x16x32_bf16 v[64:67], v[76:79], v[176:179], v[64:67]
	v_mfma_f32_16x16x32_bf16 v[44:47], v[60:63], v[184:187], v[44:47]
	v_mfma_f32_16x16x32_bf16 v[40:43], v[76:79], v[184:187], v[40:43]
	v_mfma_f32_16x16x32_bf16 v[28:31], v[60:63], v[192:195], v[28:31]
	v_mfma_f32_16x16x32_bf16 v[24:27], v[76:79], v[192:195], v[24:27]
	v_mfma_f32_16x16x32_bf16 v[12:15], v[60:63], v[200:203], v[12:15]
	v_mfma_f32_16x16x32_bf16 v[8:11], v[76:79], v[200:203], v[8:11]
	s_setprio 0
	s_setprio 1
	v_mfma_f32_16x16x32_bf16 v[48:51], v[164:167], v[172:175], v[48:51]
	v_mfma_f32_16x16x32_bf16 v[36:39], v[152:155], v[180:183], v[36:39]
	v_mfma_f32_16x16x32_bf16 v[32:35], v[164:167], v[180:183], v[32:35]
	v_mfma_f32_16x16x32_bf16 v[20:23], v[152:155], v[188:191], v[20:23]
	v_mfma_f32_16x16x32_bf16 v[16:19], v[164:167], v[188:191], v[16:19]
	v_mfma_f32_16x16x32_bf16 v[4:7], v[152:155], v[196:199], v[4:7]
	v_mfma_f32_16x16x32_bf16 v[0:3], v[164:167], v[196:199], v[0:3]
	v_mfma_f32_16x16x32_bf16 v[52:55], v[152:155], v[172:175], v[56:59]
	v_mfma_f32_16x16x32_bf16 v[48:51], v[168:171], v[176:179], v[48:51]
	v_mfma_f32_16x16x32_bf16 v[36:39], v[156:159], v[184:187], v[36:39]
	v_mfma_f32_16x16x32_bf16 v[32:35], v[168:171], v[184:187], v[32:35]
	v_mfma_f32_16x16x32_bf16 v[20:23], v[156:159], v[192:195], v[20:23]
	v_mfma_f32_16x16x32_bf16 v[16:19], v[168:171], v[192:195], v[16:19]
	v_mfma_f32_16x16x32_bf16 v[4:7], v[156:159], v[200:203], v[4:7]
	v_mfma_f32_16x16x32_bf16 v[0:3], v[168:171], v[200:203], v[0:3]
	v_mfma_f32_16x16x32_bf16 v[52:55], v[156:159], v[176:179], v[52:55]
	s_setprio 0
	s_barrier
	s_add_i32 s3, 0, 0x18000
	s_add_i32 s44, 0, 0x1c000
	v_add_u32_e32 v76, s3, v162
	v_add_u32_e32 v168, s44, v162
	ds_read_b128 v[56:59], v76
	ds_read_b128 v[60:63], v76 offset:1024
	ds_read_b128 v[68:71], v76 offset:2048
	ds_read_b128 v[76:79], v76 offset:3072
	ds_read_b128 v[152:155], v168
	ds_read_b128 v[156:159], v168 offset:1024
	ds_read_b128 v[164:167], v168 offset:2048
	ds_read_b128 v[168:171], v168 offset:3072
	s_add_u32 s28, s46, 0x40000
	s_addc_u32 s29, s47, 0
	s_mov_b32 m0, s59
	v_lshl_add_u64 v[216:217], s[28:29], 0, v[144:145]
	ds_read_b128 v[172:175], v163 offset:32768
	ds_read_b128 v[176:179], v163 offset:33792
	ds_read_b128 v[180:183], v163 offset:34816
	ds_read_b128 v[184:187], v163 offset:35840
	ds_read_b128 v[188:191], v163 offset:36864
	ds_read_b128 v[192:195], v163 offset:37888
	ds_read_b128 v[196:199], v163 offset:38912
	ds_read_b128 v[200:203], v163 offset:39936
	global_load_lds_dwordx4 v[216:217], off
	v_lshl_add_u64 v[216:217], s[28:29], 0, v[146:147]
	s_mov_b32 m0, s65
	s_nop 0
	global_load_lds_dwordx4 v[216:217], off
	s_waitcnt vmcnt(8)
	s_waitcnt lgkmcnt(0)
	s_barrier
	s_setprio 1
	s_waitcnt lgkmcnt(0)
	v_mfma_f32_16x16x32_bf16 v[140:143], v[56:59], v[172:175], v[140:143]
	v_mfma_f32_16x16x32_bf16 v[136:139], v[68:71], v[172:175], v[136:139]
	v_mfma_f32_16x16x32_bf16 v[124:127], v[56:59], v[180:183], v[124:127]
	v_mfma_f32_16x16x32_bf16 v[120:123], v[68:71], v[180:183], v[120:123]
	v_mfma_f32_16x16x32_bf16 v[108:111], v[56:59], v[188:191], v[108:111]
	v_mfma_f32_16x16x32_bf16 v[104:107], v[68:71], v[188:191], v[104:107]
	v_mfma_f32_16x16x32_bf16 v[92:95], v[56:59], v[196:199], v[92:95]
	v_mfma_f32_16x16x32_bf16 v[88:91], v[68:71], v[196:199], v[88:91]
	v_mfma_f32_16x16x32_bf16 v[140:143], v[60:63], v[176:179], v[140:143]
	v_mfma_f32_16x16x32_bf16 v[136:139], v[76:79], v[176:179], v[136:139]
	v_mfma_f32_16x16x32_bf16 v[124:127], v[60:63], v[184:187], v[124:127]
	v_mfma_f32_16x16x32_bf16 v[120:123], v[76:79], v[184:187], v[120:123]
	v_mfma_f32_16x16x32_bf16 v[108:111], v[60:63], v[192:195], v[108:111]
	v_mfma_f32_16x16x32_bf16 v[104:107], v[76:79], v[192:195], v[104:107]
	v_mfma_f32_16x16x32_bf16 v[92:95], v[60:63], v[200:203], v[92:95]
	v_mfma_f32_16x16x32_bf16 v[88:91], v[76:79], v[200:203], v[88:91]
	s_setprio 0
	s_setprio 1
	v_mfma_f32_16x16x32_bf16 v[132:135], v[152:155], v[172:175], v[132:135]
	v_mfma_f32_16x16x32_bf16 v[128:131], v[164:167], v[172:175], v[128:131]
	v_mfma_f32_16x16x32_bf16 v[116:119], v[152:155], v[180:183], v[116:119]
	v_mfma_f32_16x16x32_bf16 v[112:115], v[164:167], v[180:183], v[112:115]
	v_mfma_f32_16x16x32_bf16 v[100:103], v[152:155], v[188:191], v[100:103]
	v_mfma_f32_16x16x32_bf16 v[96:99], v[164:167], v[188:191], v[96:99]
	v_mfma_f32_16x16x32_bf16 v[84:87], v[152:155], v[196:199], v[84:87]
	v_mfma_f32_16x16x32_bf16 v[80:83], v[164:167], v[196:199], v[80:83]
	v_mfma_f32_16x16x32_bf16 v[132:135], v[156:159], v[176:179], v[132:135]
	v_mfma_f32_16x16x32_bf16 v[128:131], v[168:171], v[176:179], v[128:131]
	v_mfma_f32_16x16x32_bf16 v[116:119], v[156:159], v[184:187], v[116:119]
	v_mfma_f32_16x16x32_bf16 v[112:115], v[168:171], v[184:187], v[112:115]
	v_mfma_f32_16x16x32_bf16 v[100:103], v[156:159], v[192:195], v[100:103]
	v_mfma_f32_16x16x32_bf16 v[96:99], v[168:171], v[192:195], v[96:99]
	v_mfma_f32_16x16x32_bf16 v[84:87], v[156:159], v[200:203], v[84:87]
	v_mfma_f32_16x16x32_bf16 v[80:83], v[168:171], v[200:203], v[80:83]
	s_setprio 0
	s_barrier
; #define PG8_STAGE(bufoff, gbase, voff) do { _Pragma("unroll") for (int _i = 0; _i < 2; ++_i) \
;         __builtin_amdgcn_global_load_lds((const unsigned*)((const char*)(gbase) + (voff)[_i]), (PG8_LAS unsigned*)(lds + (bufoff) + ldsw + _i * 8192), 16, 0, 0); } while (0)
; #define PG8_LDA(dst, b, h) do { _Pragma("unroll") for (int m = 0; m < 4; ++m) _Pragma("unroll") for (int k = 0; k < 2; ++k) dst[m][k] = *(const PG8_LAS bf16x8*)(lds + PG8_SA(b, h) + aoff + m * 2048 + k * 1024); } while (0)
; #define PG8_MMA(ai, bj, At, Bt) do { __builtin_amdgcn_s_setprio(1); _Pragma("unroll") for (int m = 0; m < 4; ++m) _Pragma("unroll") for (int n = 0; n < 2; ++n) _Pragma("unroll") for (int k = 0; k < 2; ++k) \
;         acc[ai][bj][m][n] = __builtin_amdgcn_mfma_f32_16x16x32_bf16(Bt[n][k], At[m][k], acc[ai][bj][m][n], 0, 0, 0); __builtin_amdgcn_s_setprio(0); } while (0)
; #define PG8_WAIT_V(n) asm volatile("s_waitcnt vmcnt(" #n ")" ::: "memory")
; #define PG8_WAIT_L(n) asm volatile("s_waitcnt lgkmcnt(" #n ")" ::: "memory")
; #define PG8_BAR __builtin_amdgcn_s_barrier()
; #define PG8_SCHED __builtin_amdgcn_sched_barrier(0)
; template <class Epi, class Sched, bool ALIGN_EPI = false, bool SP2 = false>
; __device__ __forceinline__ void gemm_phase(PG8_LAS unsigned char* lds, const Gemm g, const Sched& S, const Epi& E) {
;     ...
;         for (int t = 0; t < nt; t += 2) {
;     ...
;             PG8_LDA(At, 1, 1); PG8_STAGE(PG8_SB(1, 0), b3, voffB); PG8_STAGE(PG8_SB(1, 1), b3 + hstep, voffB); PG8_STAGE(PG8_SA(1, 0), a3, voffA);
;             PG8_WAIT_V(8); PG8_WAIT_L(0); PG8_BAR; PG8_MMA(1, 0, At, B0); PG8_MMA(1, 1, At, B1); PG8_BAR; PG8_SCHED;
	s_add_i32 s3, s3, s50
	v_lshl_add_u64 v[160:161], v[160:161], 0, s[36:37]
	s_mov_b32 m0, s3
	ds_read_b128 v[172:175], v163 offset:49152
	ds_read_b128 v[176:179], v163 offset:50176
	ds_read_b128 v[180:183], v163 offset:51200
	ds_read_b128 v[184:187], v163 offset:52224
	ds_read_b128 v[188:191], v163 offset:53248
	ds_read_b128 v[192:195], v163 offset:54272
	ds_read_b128 v[196:199], v163 offset:55296
	ds_read_b128 v[200:203], v163 offset:56320
	global_load_lds_dwordx4 v[160:161], off
	s_add_i32 m0, s3, 0x2000
	s_add_u32 s28, s86, 0x40080
	v_lshl_add_u64 v[160:161], v[204:205], 0, s[36:37]
	s_addc_u32 s29, s87, 0
	s_add_i32 s3, s44, s50
	global_load_lds_dwordx4 v[160:161], off
	v_lshl_add_u64 v[160:161], s[28:29], 0, v[144:145]
	s_mov_b32 m0, s3
	s_nop 0
	global_load_lds_dwordx4 v[160:161], off
	v_lshl_add_u64 v[160:161], s[28:29], 0, v[146:147]
	s_add_i32 m0, s3, 0x2000
	s_nop 0
	global_load_lds_dwordx4 v[160:161], off
	v_lshl_add_u64 v[160:161], v[206:207], 0, s[36:37]
	s_mov_b32 m0, s34
	s_nop 0
	global_load_lds_dwordx4 v[160:161], off
	v_lshl_add_u64 v[160:161], v[214:215], 0, s[36:37]
	s_mov_b32 m0, s35
	s_nop 0
	global_load_lds_dwordx4 v[160:161], off
	s_waitcnt vmcnt(8)
	s_waitcnt lgkmcnt(0)
	s_barrier
	s_setprio 1
	s_waitcnt lgkmcnt(0)
	v_mfma_f32_16x16x32_bf16 v[72:75], v[56:59], v[172:175], v[72:75]
	v_mfma_f32_16x16x32_bf16 v[64:67], v[68:71], v[172:175], v[64:67]
	v_mfma_f32_16x16x32_bf16 v[44:47], v[56:59], v[180:183], v[44:47]
	v_mfma_f32_16x16x32_bf16 v[40:43], v[68:71], v[180:183], v[40:43]
	v_mfma_f32_16x16x32_bf16 v[28:31], v[56:59], v[188:191], v[28:31]
	v_mfma_f32_16x16x32_bf16 v[24:27], v[68:71], v[188:191], v[24:27]
	v_mfma_f32_16x16x32_bf16 v[12:15], v[56:59], v[196:199], v[12:15]
	v_mfma_f32_16x16x32_bf16 v[8:11], v[68:71], v[196:199], v[8:11]
	v_mfma_f32_16x16x32_bf16 v[72:75], v[60:63], v[176:179], v[72:75]
	v_mfma_f32_16x16x32_bf16 v[64:67], v[76:79], v[176:179], v[64:67]
	v_mfma_f32_16x16x32_bf16 v[44:47], v[60:63], v[184:187], v[44:47]
	v_mfma_f32_16x16x32_bf16 v[40:43], v[76:79], v[184:187], v[40:43]
	v_mfma_f32_16x16x32_bf16 v[28:31], v[60:63], v[192:195], v[28:31]
	v_mfma_f32_16x16x32_bf16 v[24:27], v[76:79], v[192:195], v[24:27]
	v_mfma_f32_16x16x32_bf16 v[12:15], v[60:63], v[200:203], v[12:15]
	v_mfma_f32_16x16x32_bf16 v[8:11], v[76:79], v[200:203], v[8:11]
	s_setprio 0
	s_setprio 1
	v_mfma_f32_16x16x32_bf16 v[52:55], v[152:155], v[172:175], v[52:55]
	v_mfma_f32_16x16x32_bf16 v[48:51], v[164:167], v[172:175], v[48:51]
	v_mfma_f32_16x16x32_bf16 v[36:39], v[152:155], v[180:183], v[36:39]
	v_mfma_f32_16x16x32_bf16 v[32:35], v[164:167], v[180:183], v[32:35]
	v_mfma_f32_16x16x32_bf16 v[20:23], v[152:155], v[188:191], v[20:23]
	v_mfma_f32_16x16x32_bf16 v[16:19], v[164:167], v[188:191], v[16:19]
	v_mfma_f32_16x16x32_bf16 v[4:7], v[152:155], v[196:199], v[4:7]
	v_mfma_f32_16x16x32_bf16 v[0:3], v[164:167], v[196:199], v[0:3]
	v_mfma_f32_16x16x32_bf16 v[56:59], v[156:159], v[176:179], v[52:55]
	v_mfma_f32_16x16x32_bf16 v[48:51], v[168:171], v[176:179], v[48:51]
	v_mfma_f32_16x16x32_bf16 v[36:39], v[156:159], v[184:187], v[36:39]
	v_mfma_f32_16x16x32_bf16 v[32:35], v[168:171], v[184:187], v[32:35]
	v_mfma_f32_16x16x32_bf16 v[20:23], v[156:159], v[192:195], v[20:23]
	v_mfma_f32_16x16x32_bf16 v[16:19], v[168:171], v[192:195], v[16:19]
	v_mfma_f32_16x16x32_bf16 v[4:7], v[156:159], v[200:203], v[4:7]
	v_mfma_f32_16x16x32_bf16 v[0:3], v[168:171], v[200:203], v[0:3]
	s_setprio 0
	s_add_i32 s83, s83, 2
	s_add_u32 s84, s84, 0x100
	s_addc_u32 s85, s85, 0
	s_add_u32 s69, s69, 0x100
	s_addc_u32 s77, s77, 0
	s_cmp_gt_u32 s83, 13
	s_barrier
	s_cbranch_scc0 .LBB0_194
	s_and_b64 vcc, exec, s[42:43]
	s_cbranch_vccz .LBB0_197
	s_barrier

; #define PG8_STAGE(bufoff, gbase, voff) do { _Pragma("unroll") for (int _i = 0; _i < 2; ++_i) \
;         __builtin_amdgcn_global_load_lds((const unsigned*)((const char*)(gbase) + (voff)[_i]), (PG8_LAS unsigned*)(lds + (bufoff) + ldsw + _i * 8192), 16, 0, 0); } while (0)
; #define PG8_LDA(dst, b, h) do { _Pragma("unroll") for (int m = 0; m < 4; ++m) _Pragma("unroll") for (int k = 0; k < 2; ++k) dst[m][k] = *(const PG8_LAS bf16x8*)(lds + PG8_SA(b, h) + aoff + m * 2048 + k * 1024); } while (0)
; #define PG8_LDB(dst, b, h) do { _Pragma("unroll") for (int n = 0; n < 2; ++n) _Pragma("unroll") for (int k = 0; k < 2; ++k) dst[n][k] = *(const PG8_LAS bf16x8*)(lds + PG8_SB(b, h) + boff + n * 2048 + k * 1024); } while (0)
; #define PG8_MMA(ai, bj, At, Bt) do { __builtin_amdgcn_s_setprio(1); _Pragma("unroll") for (int m = 0; m < 4; ++m) _Pragma("unroll") for (int n = 0; n < 2; ++n) _Pragma("unroll") for (int k = 0; k < 2; ++k) \
;         acc[ai][bj][m][n] = __builtin_amdgcn_mfma_f32_16x16x32_bf16(Bt[n][k], At[m][k], acc[ai][bj][m][n], 0, 0, 0); __builtin_amdgcn_s_setprio(0); } while (0)
; #define PG8_WAIT_V(n) asm volatile("s_waitcnt vmcnt(" #n ")" ::: "memory")
; #define PG8_WAIT_L(n) asm volatile("s_waitcnt lgkmcnt(" #n ")" ::: "memory")
; template <class Epi, class Sched, bool ALIGN_EPI = false, bool SP2 = false>
; __device__ __forceinline__ void gemm_phase(PG8_LAS unsigned char* lds, const Gemm g, const Sched& S, const Epi& E) {
;     ...
;             const bool last = (t == nt - 2);
;             const char* a1 = cA + (size_t)(t + 1) * kstep;
;             const char* a2 = last ? nA : cA + (size_t)(t + 2) * kstep; const char* b2 = last ? nB : cB + (size_t)(t + 2) * kstep;
;             const char* a3 = a2 + kstep; const char* b3 = b2 + kstep;
;             if (last && has_next) S.a_ready(nxt);
;             if constexpr (SP2) {
;             PG8_LDB(B0, 0, 0); PG8_LDB(B1, 0, 1); PG8_SCHED; PG8_LDA(At, 0, 0); PG8_STAGE(PG8_SA(1, 1), a1 + hstep, voffA);
;             PG8_WAIT_V(8); PG8_WAIT_L(0); PG8_BAR; PG8_MMA(0, 0, At, B0); PG8_MMA(0, 1, At, B1); PG8_BAR; PG8_SCHED;
;             PG8_LDA(At, 0, 1); PG8_STAGE(PG8_SB(0, 0), b2, voffB); PG8_STAGE(PG8_SB(0, 1), b2 + hstep, voffB); PG8_STAGE(PG8_SA(0, 0), a2, voffA);
;             PG8_WAIT_V(8); PG8_WAIT_L(0); PG8_BAR; PG8_MMA(1, 0, At, B0); PG8_MMA(1, 1, At, B1); PG8_BAR; PG8_SCHED;
.LBB0_340:
	s_add_u32 s3, s82, 0xffe00080
	s_addc_u32 s28, s83, -1
	s_add_i32 s29, 0, 0x10000
	s_cmp_eq_u32 s92, 60
	s_cselect_b32 s47, s30, s28
	s_cselect_b32 s46, s45, s3
	s_cselect_b32 s85, s69, s87
	s_cselect_b32 s84, s77, s86
	s_add_i32 s3, 0, 0x14000
	v_add_u32_e32 v154, s29, v140
	v_add_u32_e32 v170, s3, v140
	ds_read_b128 v[142:145], v154
	ds_read_b128 v[146:149], v154 offset:1024
	ds_read_b128 v[150:153], v154 offset:2048
	ds_read_b128 v[154:157], v154 offset:3072
	ds_read_b128 v[158:161], v170
	ds_read_b128 v[162:165], v170 offset:1024
	ds_read_b128 v[166:169], v170 offset:2048
	ds_read_b128 v[170:173], v170 offset:3072
	v_lshl_add_u64 v[206:207], s[82:83], 0, v[136:137]
	s_add_i32 m0, s41, 0xc000
	ds_read_b128 v[174:177], v141
	ds_read_b128 v[178:181], v141 offset:1024
	ds_read_b128 v[182:185], v141 offset:2048
	ds_read_b128 v[186:189], v141 offset:3072
	ds_read_b128 v[190:193], v141 offset:4096
	ds_read_b128 v[194:197], v141 offset:5120
	ds_read_b128 v[198:201], v141 offset:6144
	ds_read_b128 v[202:205], v141 offset:7168
	global_load_lds_dwordx4 v[206:207], off
	v_lshl_add_u64 v[206:207], s[82:83], 0, v[138:139]
	s_add_i32 m0, s41, 0xe000
	s_nop 0
	global_load_lds_dwordx4 v[206:207], off
	s_waitcnt vmcnt(8)
	s_waitcnt lgkmcnt(0)
	s_barrier
	s_setprio 1
	s_waitcnt lgkmcnt(0)
	v_mfma_f32_16x16x32_bf16 v[124:127], v[142:145], v[174:177], v[124:127]
	v_mfma_f32_16x16x32_bf16 v[120:123], v[150:153], v[174:177], v[120:123]
	v_mfma_f32_16x16x32_bf16 v[116:119], v[142:145], v[182:185], v[116:119]
	v_mfma_f32_16x16x32_bf16 v[112:115], v[150:153], v[182:185], v[112:115]
	v_mfma_f32_16x16x32_bf16 v[104:107], v[142:145], v[190:193], v[104:107]
	v_mfma_f32_16x16x32_bf16 v[96:99], v[150:153], v[190:193], v[96:99]
	v_mfma_f32_16x16x32_bf16 v[88:91], v[142:145], v[198:201], v[88:91]
	v_mfma_f32_16x16x32_bf16 v[80:83], v[150:153], v[198:201], v[80:83]
	v_mfma_f32_16x16x32_bf16 v[124:127], v[146:149], v[178:181], v[124:127]
	v_mfma_f32_16x16x32_bf16 v[120:123], v[154:157], v[178:181], v[120:123]
	v_mfma_f32_16x16x32_bf16 v[116:119], v[146:149], v[186:189], v[116:119]
	v_mfma_f32_16x16x32_bf16 v[112:115], v[154:157], v[186:189], v[112:115]
	v_mfma_f32_16x16x32_bf16 v[104:107], v[146:149], v[194:197], v[104:107]
	v_mfma_f32_16x16x32_bf16 v[96:99], v[154:157], v[194:197], v[96:99]
	v_mfma_f32_16x16x32_bf16 v[88:91], v[146:149], v[202:205], v[88:91]
	v_mfma_f32_16x16x32_bf16 v[80:83], v[154:157], v[202:205], v[80:83]
	s_setprio 0
	s_setprio 1
	v_mfma_f32_16x16x32_bf16 v[108:111], v[158:161], v[174:177], v[108:111]
	v_mfma_f32_16x16x32_bf16 v[100:103], v[166:169], v[174:177], v[100:103]
	v_mfma_f32_16x16x32_bf16 v[92:95], v[158:161], v[182:185], v[92:95]
	v_mfma_f32_16x16x32_bf16 v[84:87], v[166:169], v[182:185], v[84:87]
	v_mfma_f32_16x16x32_bf16 v[76:79], v[158:161], v[190:193], v[76:79]
	v_mfma_f32_16x16x32_bf16 v[72:75], v[166:169], v[190:193], v[72:75]
	v_mfma_f32_16x16x32_bf16 v[68:71], v[158:161], v[198:201], v[68:71]
	v_mfma_f32_16x16x32_bf16 v[64:67], v[166:169], v[198:201], v[64:67]
	v_mfma_f32_16x16x32_bf16 v[108:111], v[162:165], v[178:181], v[108:111]
	v_mfma_f32_16x16x32_bf16 v[100:103], v[170:173], v[178:181], v[100:103]
	v_mfma_f32_16x16x32_bf16 v[92:95], v[162:165], v[186:189], v[92:95]
	v_mfma_f32_16x16x32_bf16 v[84:87], v[170:173], v[186:189], v[84:87]
	v_mfma_f32_16x16x32_bf16 v[76:79], v[162:165], v[194:197], v[76:79]
	v_mfma_f32_16x16x32_bf16 v[72:75], v[170:173], v[194:197], v[72:75]
	v_mfma_f32_16x16x32_bf16 v[68:71], v[162:165], v[202:205], v[68:71]
	v_mfma_f32_16x16x32_bf16 v[64:67], v[170:173], v[202:205], v[64:67]
	s_setprio 0
	s_barrier
	s_add_i32 s28, s29, s34
	v_lshl_add_u64 v[206:207], s[84:85], 0, v[132:133]
	s_mov_b32 m0, s28
	ds_read_b128 v[174:177], v141 offset:16384
	ds_read_b128 v[178:181], v141 offset:17408
	ds_read_b128 v[182:185], v141 offset:18432
	ds_read_b128 v[186:189], v141 offset:19456
	ds_read_b128 v[190:193], v141 offset:20480
	ds_read_b128 v[194:197], v141 offset:21504
	ds_read_b128 v[198:201], v141 offset:22528
	ds_read_b128 v[202:205], v141 offset:23552
	global_load_lds_dwordx4 v[206:207], off
	s_add_i32 m0, s28, 0x2000
	s_add_u32 s28, s84, 0x200000
	v_lshl_add_u64 v[214:215], s[84:85], 0, v[128:129]
	s_addc_u32 s29, s85, 0
	s_add_i32 s3, s3, s34
	global_load_lds_dwordx4 v[214:215], off
	v_lshl_add_u64 v[216:217], s[28:29], 0, v[132:133]
	s_mov_b32 m0, s3
	v_lshl_add_u64 v[222:223], s[46:47], 0, v[130:131]
	global_load_lds_dwordx4 v[216:217], off
	v_lshl_add_u64 v[216:217], s[28:29], 0, v[128:129]
	s_add_i32 m0, s3, 0x2000
	s_nop 0
	global_load_lds_dwordx4 v[216:217], off
	v_lshl_add_u64 v[216:217], s[46:47], 0, v[134:135]
	s_mov_b32 m0, s41
	s_nop 0
	global_load_lds_dwordx4 v[216:217], off
	s_mov_b32 m0, s48
	s_nop 0
	global_load_lds_dwordx4 v[222:223], off
	s_waitcnt vmcnt(8)
	s_waitcnt lgkmcnt(0)
	s_barrier
; #define PG8_STAGE(bufoff, gbase, voff) do { _Pragma("unroll") for (int _i = 0; _i < 2; ++_i) \
;         __builtin_amdgcn_global_load_lds((const unsigned*)((const char*)(gbase) + (voff)[_i]), (PG8_LAS unsigned*)(lds + (bufoff) + ldsw + _i * 8192), 16, 0, 0); } while (0)
; #define PG8_LDA(dst, b, h) do { _Pragma("unroll") for (int m = 0; m < 4; ++m) _Pragma("unroll") for (int k = 0; k < 2; ++k) dst[m][k] = *(const PG8_LAS bf16x8*)(lds + PG8_SA(b, h) + aoff + m * 2048 + k * 1024); } while (0)
; #define PG8_LDB(dst, b, h) do { _Pragma("unroll") for (int n = 0; n < 2; ++n) _Pragma("unroll") for (int k = 0; k < 2; ++k) dst[n][k] = *(const PG8_LAS bf16x8*)(lds + PG8_SB(b, h) + boff + n * 2048 + k * 1024); } while (0)
; #define PG8_MMA(ai, bj, At, Bt) do { __builtin_amdgcn_s_setprio(1); _Pragma("unroll") for (int m = 0; m < 4; ++m) _Pragma("unroll") for (int n = 0; n < 2; ++n) _Pragma("unroll") for (int k = 0; k < 2; ++k) \
;         acc[ai][bj][m][n] = __builtin_amdgcn_mfma_f32_16x16x32_bf16(Bt[n][k], At[m][k], acc[ai][bj][m][n], 0, 0, 0); __builtin_amdgcn_s_setprio(0); } while (0)
; #define PG8_WAIT_V(n) asm volatile("s_waitcnt vmcnt(" #n ")" ::: "memory")
; #define PG8_WAIT_L(n) asm volatile("s_waitcnt lgkmcnt(" #n ")" ::: "memory")
; #define PG8_BAR __builtin_amdgcn_s_barrier()
; #define PG8_SCHED __builtin_amdgcn_sched_barrier(0)
; template <class Epi, class Sched, bool ALIGN_EPI = false, bool SP2 = false>
; __device__ __forceinline__ void gemm_phase(PG8_LAS unsigned char* lds, const Gemm g, const Sched& S, const Epi& E) {
;     ...
;             PG8_WAIT_V(8); PG8_WAIT_L(0); PG8_BAR; PG8_MMA(1, 0, At, B0); PG8_MMA(1, 1, At, B1); PG8_BAR; PG8_SCHED;
;             PG8_LDB(B0, 1, 0); PG8_LDB(B1, 1, 1); PG8_SCHED; PG8_LDA(At, 1, 0); PG8_STAGE(PG8_SA(0, 1), a2 + hstep, voffA);
;             PG8_WAIT_V(8); PG8_WAIT_L(0); PG8_BAR; PG8_MMA(0, 0, At, B0); PG8_MMA(0, 1, At, B1); PG8_BAR; PG8_SCHED;
	s_setprio 1
	s_waitcnt lgkmcnt(0)
	v_mfma_f32_16x16x32_bf16 v[60:63], v[142:145], v[174:177], v[60:63]
	v_mfma_f32_16x16x32_bf16 v[56:59], v[150:153], v[174:177], v[56:59]
	v_mfma_f32_16x16x32_bf16 v[52:55], v[142:145], v[182:185], v[52:55]
	v_mfma_f32_16x16x32_bf16 v[48:51], v[150:153], v[182:185], v[48:51]
	v_mfma_f32_16x16x32_bf16 v[40:43], v[142:145], v[190:193], v[40:43]
	v_mfma_f32_16x16x32_bf16 v[32:35], v[150:153], v[190:193], v[32:35]
	v_mfma_f32_16x16x32_bf16 v[24:27], v[142:145], v[198:201], v[24:27]
	v_mfma_f32_16x16x32_bf16 v[16:19], v[150:153], v[198:201], v[16:19]
	v_mfma_f32_16x16x32_bf16 v[60:63], v[146:149], v[178:181], v[60:63]
	v_mfma_f32_16x16x32_bf16 v[56:59], v[154:157], v[178:181], v[56:59]
	v_mfma_f32_16x16x32_bf16 v[52:55], v[146:149], v[186:189], v[52:55]
	v_mfma_f32_16x16x32_bf16 v[48:51], v[154:157], v[186:189], v[48:51]
	v_mfma_f32_16x16x32_bf16 v[40:43], v[146:149], v[194:197], v[40:43]
	v_mfma_f32_16x16x32_bf16 v[32:35], v[154:157], v[194:197], v[32:35]
	v_mfma_f32_16x16x32_bf16 v[24:27], v[146:149], v[202:205], v[24:27]
	v_mfma_f32_16x16x32_bf16 v[16:19], v[154:157], v[202:205], v[16:19]
	s_setprio 0
	s_setprio 1
	v_mfma_f32_16x16x32_bf16 v[44:47], v[158:161], v[174:177], v[44:47]
	v_mfma_f32_16x16x32_bf16 v[36:39], v[166:169], v[174:177], v[36:39]
	v_mfma_f32_16x16x32_bf16 v[28:31], v[158:161], v[182:185], v[28:31]
	v_mfma_f32_16x16x32_bf16 v[20:23], v[166:169], v[182:185], v[20:23]
	v_mfma_f32_16x16x32_bf16 v[12:15], v[158:161], v[190:193], v[12:15]
	v_mfma_f32_16x16x32_bf16 v[8:11], v[166:169], v[190:193], v[8:11]
	v_mfma_f32_16x16x32_bf16 v[4:7], v[158:161], v[198:201], v[4:7]
	v_mfma_f32_16x16x32_bf16 v[0:3], v[166:169], v[198:201], v[0:3]
	v_mfma_f32_16x16x32_bf16 v[44:47], v[162:165], v[178:181], v[44:47]
	v_mfma_f32_16x16x32_bf16 v[36:39], v[170:173], v[178:181], v[36:39]
	v_mfma_f32_16x16x32_bf16 v[28:31], v[162:165], v[186:189], v[28:31]
	v_mfma_f32_16x16x32_bf16 v[20:23], v[170:173], v[186:189], v[20:23]
	v_mfma_f32_16x16x32_bf16 v[12:15], v[162:165], v[194:197], v[12:15]
	v_mfma_f32_16x16x32_bf16 v[8:11], v[170:173], v[194:197], v[8:11]
	v_mfma_f32_16x16x32_bf16 v[4:7], v[162:165], v[202:205], v[4:7]
	v_mfma_f32_16x16x32_bf16 v[0:3], v[170:173], v[202:205], v[0:3]
	s_setprio 0
	s_barrier
	s_add_i32 s3, 0, 0x18000
	s_add_i32 s44, 0, 0x1c000
	v_add_u32_e32 v154, s3, v140
	v_add_u32_e32 v170, s44, v140
	ds_read_b128 v[142:145], v154
	ds_read_b128 v[146:149], v154 offset:1024
	ds_read_b128 v[150:153], v154 offset:2048
	ds_read_b128 v[154:157], v154 offset:3072
	ds_read_b128 v[158:161], v170
	ds_read_b128 v[162:165], v170 offset:1024
	ds_read_b128 v[166:169], v170 offset:2048
	ds_read_b128 v[170:173], v170 offset:3072
	s_add_u32 s28, s46, 0x200000
	s_addc_u32 s29, s47, 0
	s_mov_b32 m0, s49
	v_lshl_add_u64 v[224:225], s[28:29], 0, v[134:135]
	ds_read_b128 v[174:177], v141 offset:32768
	ds_read_b128 v[178:181], v141 offset:33792
	ds_read_b128 v[182:185], v141 offset:34816
	ds_read_b128 v[186:189], v141 offset:35840
	ds_read_b128 v[190:193], v141 offset:36864
	ds_read_b128 v[194:197], v141 offset:37888
	ds_read_b128 v[198:201], v141 offset:38912
	ds_read_b128 v[202:205], v141 offset:39936
	global_load_lds_dwordx4 v[224:225], off
	v_lshl_add_u64 v[224:225], s[28:29], 0, v[130:131]
	s_mov_b32 m0, s50
	s_nop 0
	global_load_lds_dwordx4 v[224:225], off
	s_waitcnt vmcnt(8)
	s_waitcnt lgkmcnt(0)
	s_barrier
	s_setprio 1
	s_waitcnt lgkmcnt(0)
	v_mfma_f32_16x16x32_bf16 v[124:127], v[142:145], v[174:177], v[124:127]
	v_mfma_f32_16x16x32_bf16 v[120:123], v[150:153], v[174:177], v[120:123]
	v_mfma_f32_16x16x32_bf16 v[116:119], v[142:145], v[182:185], v[116:119]
	v_mfma_f32_16x16x32_bf16 v[112:115], v[150:153], v[182:185], v[112:115]
	v_mfma_f32_16x16x32_bf16 v[104:107], v[142:145], v[190:193], v[104:107]
	v_mfma_f32_16x16x32_bf16 v[96:99], v[150:153], v[190:193], v[96:99]
	v_mfma_f32_16x16x32_bf16 v[88:91], v[142:145], v[198:201], v[88:91]
	v_mfma_f32_16x16x32_bf16 v[80:83], v[150:153], v[198:201], v[80:83]
	v_mfma_f32_16x16x32_bf16 v[124:127], v[146:149], v[178:181], v[124:127]
	v_mfma_f32_16x16x32_bf16 v[120:123], v[154:157], v[178:181], v[120:123]
	v_mfma_f32_16x16x32_bf16 v[116:119], v[146:149], v[186:189], v[116:119]
	v_mfma_f32_16x16x32_bf16 v[112:115], v[154:157], v[186:189], v[112:115]
	v_mfma_f32_16x16x32_bf16 v[104:107], v[146:149], v[194:197], v[104:107]
	v_mfma_f32_16x16x32_bf16 v[96:99], v[154:157], v[194:197], v[96:99]
	v_mfma_f32_16x16x32_bf16 v[88:91], v[146:149], v[202:205], v[88:91]
	v_mfma_f32_16x16x32_bf16 v[80:83], v[154:157], v[202:205], v[80:83]
	s_setprio 0
	s_setprio 1
	v_mfma_f32_16x16x32_bf16 v[108:111], v[158:161], v[174:177], v[108:111]
	v_mfma_f32_16x16x32_bf16 v[100:103], v[166:169], v[174:177], v[100:103]
	v_mfma_f32_16x16x32_bf16 v[92:95], v[158:161], v[182:185], v[92:95]
	v_mfma_f32_16x16x32_bf16 v[84:87], v[166:169], v[182:185], v[84:87]
	v_mfma_f32_16x16x32_bf16 v[76:79], v[158:161], v[190:193], v[76:79]
	v_mfma_f32_16x16x32_bf16 v[72:75], v[166:169], v[190:193], v[72:75]
	v_mfma_f32_16x16x32_bf16 v[68:71], v[158:161], v[198:201], v[68:71]
	v_mfma_f32_16x16x32_bf16 v[64:67], v[166:169], v[198:201], v[64:67]
	v_mfma_f32_16x16x32_bf16 v[108:111], v[162:165], v[178:181], v[108:111]
	v_mfma_f32_16x16x32_bf16 v[100:103], v[170:173], v[178:181], v[100:103]
	v_mfma_f32_16x16x32_bf16 v[92:95], v[162:165], v[186:189], v[92:95]
	v_mfma_f32_16x16x32_bf16 v[84:87], v[170:173], v[186:189], v[84:87]
	v_mfma_f32_16x16x32_bf16 v[76:79], v[162:165], v[194:197], v[76:79]
	v_mfma_f32_16x16x32_bf16 v[72:75], v[170:173], v[194:197], v[72:75]
	v_mfma_f32_16x16x32_bf16 v[68:71], v[162:165], v[202:205], v[68:71]
	v_mfma_f32_16x16x32_bf16 v[64:67], v[170:173], v[202:205], v[64:67]
	s_setprio 0
	s_barrier
; #define PG8_STAGE(bufoff, gbase, voff) do { _Pragma("unroll") for (int _i = 0; _i < 2; ++_i) \
;         __builtin_amdgcn_global_load_lds((const unsigned*)((const char*)(gbase) + (voff)[_i]), (PG8_LAS unsigned*)(lds + (bufoff) + ldsw + _i * 8192), 16, 0, 0); } while (0)
; #define PG8_LDA(dst, b, h) do { _Pragma("unroll") for (int m = 0; m < 4; ++m) _Pragma("unroll") for (int k = 0; k < 2; ++k) dst[m][k] = *(const PG8_LAS bf16x8*)(lds + PG8_SA(b, h) + aoff + m * 2048 + k * 1024); } while (0)
; #define PG8_MMA(ai, bj, At, Bt) do { __builtin_amdgcn_s_setprio(1); _Pragma("unroll") for (int m = 0; m < 4; ++m) _Pragma("unroll") for (int n = 0; n < 2; ++n) _Pragma("unroll") for (int k = 0; k < 2; ++k) \
;         acc[ai][bj][m][n] = __builtin_amdgcn_mfma_f32_16x16x32_bf16(Bt[n][k], At[m][k], acc[ai][bj][m][n], 0, 0, 0); __builtin_amdgcn_s_setprio(0); } while (0)
; #define PG8_WAIT_V(n) asm volatile("s_waitcnt vmcnt(" #n ")" ::: "memory")
; #define PG8_WAIT_L(n) asm volatile("s_waitcnt lgkmcnt(" #n ")" ::: "memory")
; #define PG8_BAR __builtin_amdgcn_s_barrier()
; #define PG8_SCHED __builtin_amdgcn_sched_barrier(0)
; template <class Epi, class Sched, bool ALIGN_EPI = false, bool SP2 = false>
; __device__ __forceinline__ void gemm_phase(PG8_LAS unsigned char* lds, const Gemm g, const Sched& S, const Epi& E) {
;     ...
;         for (int t = 0; t < nt; t += 2) {
;     ...
;             PG8_LDA(At, 1, 1); PG8_STAGE(PG8_SB(1, 0), b3, voffB); PG8_STAGE(PG8_SB(1, 1), b3 + hstep, voffB); PG8_STAGE(PG8_SA(1, 0), a3, voffA);
;             PG8_WAIT_V(8); PG8_WAIT_L(0); PG8_BAR; PG8_MMA(1, 0, At, B0); PG8_MMA(1, 1, At, B1); PG8_BAR; PG8_SCHED;
	s_add_i32 s3, s3, s34
	v_lshl_add_u64 v[206:207], v[206:207], 0, s[36:37]
	s_mov_b32 m0, s3
	ds_read_b128 v[174:177], v141 offset:49152
	ds_read_b128 v[178:181], v141 offset:50176
	ds_read_b128 v[182:185], v141 offset:51200
	ds_read_b128 v[186:189], v141 offset:52224
	ds_read_b128 v[190:193], v141 offset:53248
	ds_read_b128 v[194:197], v141 offset:54272
	ds_read_b128 v[198:201], v141 offset:55296
	ds_read_b128 v[202:205], v141 offset:56320
	global_load_lds_dwordx4 v[206:207], off
	s_add_i32 m0, s3, 0x2000
	s_add_u32 s28, s84, 0x200080
	v_lshl_add_u64 v[206:207], v[214:215], 0, s[36:37]
	s_addc_u32 s29, s85, 0
	s_add_i32 s3, s44, s34
	global_load_lds_dwordx4 v[206:207], off
	v_lshl_add_u64 v[206:207], s[28:29], 0, v[132:133]
	s_mov_b32 m0, s3
	s_nop 0
	global_load_lds_dwordx4 v[206:207], off
	v_lshl_add_u64 v[206:207], s[28:29], 0, v[128:129]
	s_add_i32 m0, s3, 0x2000
	s_nop 0
	global_load_lds_dwordx4 v[206:207], off
	v_lshl_add_u64 v[206:207], v[216:217], 0, s[36:37]
	s_mov_b32 m0, s58
	s_nop 0
	global_load_lds_dwordx4 v[206:207], off
	v_lshl_add_u64 v[206:207], v[222:223], 0, s[36:37]
	s_mov_b32 m0, s59
	s_nop 0
	global_load_lds_dwordx4 v[206:207], off
	s_waitcnt vmcnt(8)
	s_waitcnt lgkmcnt(0)
	s_barrier
	s_setprio 1
	s_waitcnt lgkmcnt(0)
	v_mfma_f32_16x16x32_bf16 v[60:63], v[142:145], v[174:177], v[60:63]
	v_mfma_f32_16x16x32_bf16 v[56:59], v[150:153], v[174:177], v[56:59]
	v_mfma_f32_16x16x32_bf16 v[52:55], v[142:145], v[182:185], v[52:55]
	v_mfma_f32_16x16x32_bf16 v[48:51], v[150:153], v[182:185], v[48:51]
	v_mfma_f32_16x16x32_bf16 v[40:43], v[142:145], v[190:193], v[40:43]
	v_mfma_f32_16x16x32_bf16 v[32:35], v[150:153], v[190:193], v[32:35]
	v_mfma_f32_16x16x32_bf16 v[24:27], v[142:145], v[198:201], v[24:27]
	v_mfma_f32_16x16x32_bf16 v[16:19], v[150:153], v[198:201], v[16:19]
	v_mfma_f32_16x16x32_bf16 v[60:63], v[146:149], v[178:181], v[60:63]
	v_mfma_f32_16x16x32_bf16 v[56:59], v[154:157], v[178:181], v[56:59]
	v_mfma_f32_16x16x32_bf16 v[52:55], v[146:149], v[186:189], v[52:55]
	v_mfma_f32_16x16x32_bf16 v[48:51], v[154:157], v[186:189], v[48:51]
	v_mfma_f32_16x16x32_bf16 v[40:43], v[146:149], v[194:197], v[40:43]
	v_mfma_f32_16x16x32_bf16 v[32:35], v[154:157], v[194:197], v[32:35]
	v_mfma_f32_16x16x32_bf16 v[24:27], v[146:149], v[202:205], v[24:27]
	v_mfma_f32_16x16x32_bf16 v[16:19], v[154:157], v[202:205], v[16:19]
	s_setprio 0
	s_setprio 1
	v_mfma_f32_16x16x32_bf16 v[44:47], v[158:161], v[174:177], v[44:47]
	v_mfma_f32_16x16x32_bf16 v[36:39], v[166:169], v[174:177], v[36:39]
	v_mfma_f32_16x16x32_bf16 v[28:31], v[158:161], v[182:185], v[28:31]
	v_mfma_f32_16x16x32_bf16 v[20:23], v[166:169], v[182:185], v[20:23]
	v_mfma_f32_16x16x32_bf16 v[12:15], v[158:161], v[190:193], v[12:15]
	v_mfma_f32_16x16x32_bf16 v[8:11], v[166:169], v[190:193], v[8:11]
	v_mfma_f32_16x16x32_bf16 v[4:7], v[158:161], v[198:201], v[4:7]
	v_mfma_f32_16x16x32_bf16 v[0:3], v[166:169], v[198:201], v[0:3]
	v_mfma_f32_16x16x32_bf16 v[44:47], v[162:165], v[178:181], v[44:47]
	v_mfma_f32_16x16x32_bf16 v[36:39], v[170:173], v[178:181], v[36:39]
	v_mfma_f32_16x16x32_bf16 v[28:31], v[162:165], v[186:189], v[28:31]
	v_mfma_f32_16x16x32_bf16 v[20:23], v[170:173], v[186:189], v[20:23]
	v_mfma_f32_16x16x32_bf16 v[12:15], v[162:165], v[194:197], v[12:15]
	v_mfma_f32_16x16x32_bf16 v[8:11], v[170:173], v[194:197], v[8:11]
	v_mfma_f32_16x16x32_bf16 v[4:7], v[162:165], v[202:205], v[4:7]
	v_mfma_f32_16x16x32_bf16 v[0:3], v[170:173], v[202:205], v[0:3]
	s_setprio 0
	s_add_i32 s92, s92, 2
	s_add_u32 s82, s82, 0x100
	s_addc_u32 s83, s83, 0
	s_add_u32 s86, s86, 0x100
	s_addc_u32 s87, s87, 0
	s_cmp_gt_u32 s92, 61
	s_barrier
	s_cbranch_scc0 .LBB0_340
	s_and_b64 vcc, exec, s[42:43]
	s_cbranch_vccz .LBB0_343
	s_barrier

; #define PG8_STAGE(bufoff, gbase, voff) do { _Pragma("unroll") for (int _i = 0; _i < 2; ++_i) \
;         __builtin_amdgcn_global_load_lds((const unsigned*)((const char*)(gbase) + (voff)[_i]), (PG8_LAS unsigned*)(lds + (bufoff) + ldsw + _i * 8192), 16, 0, 0); } while (0)
; #define PG8_LDA(dst, b, h) do { _Pragma("unroll") for (int m = 0; m < 4; ++m) _Pragma("unroll") for (int k = 0; k < 2; ++k) dst[m][k] = *(const PG8_LAS bf16x8*)(lds + PG8_SA(b, h) + aoff + m * 2048 + k * 1024); } while (0)
; #define PG8_LDB(dst, b, h) do { _Pragma("unroll") for (int n = 0; n < 2; ++n) _Pragma("unroll") for (int k = 0; k < 2; ++k) dst[n][k] = *(const PG8_LAS bf16x8*)(lds + PG8_SB(b, h) + boff + n * 2048 + k * 1024); } while (0)
; #define PG8_MMA(ai, bj, At, Bt) do { __builtin_amdgcn_s_setprio(1); _Pragma("unroll") for (int m = 0; m < 4; ++m) _Pragma("unroll") for (int n = 0; n < 2; ++n) _Pragma("unroll") for (int k = 0; k < 2; ++k) \
;         acc[ai][bj][m][n] = __builtin_amdgcn_mfma_f32_16x16x32_bf16(Bt[n][k], At[m][k], acc[ai][bj][m][n], 0, 0, 0); __builtin_amdgcn_s_setprio(0); } while (0)
; #define PG8_WAIT_V(n) asm volatile("s_waitcnt vmcnt(" #n ")" ::: "memory")
; #define PG8_WAIT_L(n) asm volatile("s_waitcnt lgkmcnt(" #n ")" ::: "memory")
; template <class Epi, class Sched, bool ALIGN_EPI = false, bool SP2 = false>
; __device__ __forceinline__ void gemm_phase(PG8_LAS unsigned char* lds, const Gemm g, const Sched& S, const Epi& E) {
;     ...
;             const bool last = (t == nt - 2);
;             const char* a1 = cA + (size_t)(t + 1) * kstep;
;             const char* a2 = last ? nA : cA + (size_t)(t + 2) * kstep; const char* b2 = last ? nB : cB + (size_t)(t + 2) * kstep;
;             const char* a3 = a2 + kstep; const char* b3 = b2 + kstep;
;             if (last && has_next) S.a_ready(nxt);
;             if constexpr (SP2) {
;             PG8_LDB(B0, 0, 0); PG8_LDB(B1, 0, 1); PG8_SCHED; PG8_LDA(At, 0, 0); PG8_STAGE(PG8_SA(1, 1), a1 + hstep, voffA);
;             PG8_WAIT_V(8); PG8_WAIT_L(0); PG8_BAR; PG8_MMA(0, 0, At, B0); PG8_MMA(0, 1, At, B1); PG8_BAR; PG8_SCHED;
;             PG8_LDA(At, 0, 1); PG8_STAGE(PG8_SB(0, 0), b2, voffB); PG8_STAGE(PG8_SB(0, 1), b2 + hstep, voffB); PG8_STAGE(PG8_SA(0, 0), a2, voffA);
;             PG8_WAIT_V(8); PG8_WAIT_L(0); PG8_BAR; PG8_MMA(1, 0, At, B0); PG8_MMA(1, 1, At, B1); PG8_BAR; PG8_SCHED;
.LBB0_381:
	s_add_u32 s3, s82, 0xfffe0080
	s_addc_u32 s28, s83, -1
	s_add_i32 s29, 0, 0x10000
	s_cmp_eq_u32 s86, 4
	s_cselect_b32 s47, s30, s28
	s_cselect_b32 s46, s45, s3
	v_add_u32_e32 v140, s29, v142
	s_cselect_b32 s85, s67, s79
	s_cselect_b32 s84, s69, s72
	s_add_i32 s3, 0, 0x14000
	ds_read_b128 v[144:147], v140
	ds_read_b128 v[148:151], v140 offset:1024
	ds_read_b128 v[152:155], v140 offset:2048
	ds_read_b128 v[156:159], v140 offset:3072
	v_add_u32_e32 v140, s3, v142
	ds_read_b128 v[160:163], v140
	ds_read_b128 v[164:167], v140 offset:1024
	ds_read_b128 v[168:171], v140 offset:2048
	ds_read_b128 v[172:175], v140 offset:3072
	v_lshl_add_u64 v[140:141], s[82:83], 0, v[136:137]
	s_add_i32 m0, s48, 0xc000
	ds_read_b128 v[176:179], v143
	ds_read_b128 v[180:183], v143 offset:1024
	ds_read_b128 v[184:187], v143 offset:2048
	ds_read_b128 v[188:191], v143 offset:3072
	ds_read_b128 v[192:195], v143 offset:4096
	ds_read_b128 v[196:199], v143 offset:5120
	ds_read_b128 v[200:203], v143 offset:6144
	ds_read_b128 v[204:207], v143 offset:7168
	global_load_lds_dwordx4 v[140:141], off
	v_lshl_add_u64 v[140:141], s[82:83], 0, v[138:139]
	s_add_i32 m0, s48, 0xe000
	s_nop 0
	global_load_lds_dwordx4 v[140:141], off
	s_waitcnt vmcnt(8)
	s_waitcnt lgkmcnt(0)
	s_barrier
	s_setprio 1
	s_waitcnt lgkmcnt(0)
	v_mfma_f32_16x16x32_bf16 v[124:127], v[144:147], v[176:179], v[124:127]
	v_mfma_f32_16x16x32_bf16 v[120:123], v[152:155], v[176:179], v[120:123]
	v_mfma_f32_16x16x32_bf16 v[116:119], v[144:147], v[184:187], v[116:119]
	v_mfma_f32_16x16x32_bf16 v[108:111], v[152:155], v[184:187], v[108:111]
	v_mfma_f32_16x16x32_bf16 v[100:103], v[144:147], v[192:195], v[100:103]
	v_mfma_f32_16x16x32_bf16 v[92:95], v[152:155], v[192:195], v[92:95]
	v_mfma_f32_16x16x32_bf16 v[84:87], v[144:147], v[200:203], v[84:87]
	v_mfma_f32_16x16x32_bf16 v[76:79], v[152:155], v[200:203], v[76:79]
	v_mfma_f32_16x16x32_bf16 v[124:127], v[148:151], v[180:183], v[124:127]
	v_mfma_f32_16x16x32_bf16 v[120:123], v[156:159], v[180:183], v[120:123]
	v_mfma_f32_16x16x32_bf16 v[116:119], v[148:151], v[188:191], v[116:119]
	v_mfma_f32_16x16x32_bf16 v[108:111], v[156:159], v[188:191], v[108:111]
	v_mfma_f32_16x16x32_bf16 v[100:103], v[148:151], v[196:199], v[100:103]
	v_mfma_f32_16x16x32_bf16 v[92:95], v[156:159], v[196:199], v[92:95]
	v_mfma_f32_16x16x32_bf16 v[84:87], v[148:151], v[204:207], v[84:87]
	v_mfma_f32_16x16x32_bf16 v[76:79], v[156:159], v[204:207], v[76:79]
	s_setprio 0
	s_setprio 1
	v_mfma_f32_16x16x32_bf16 v[112:115], v[160:163], v[176:179], v[112:115]
	v_mfma_f32_16x16x32_bf16 v[104:107], v[168:171], v[176:179], v[104:107]
	v_mfma_f32_16x16x32_bf16 v[96:99], v[160:163], v[184:187], v[96:99]
	v_mfma_f32_16x16x32_bf16 v[88:91], v[168:171], v[184:187], v[88:91]
	v_mfma_f32_16x16x32_bf16 v[80:83], v[160:163], v[192:195], v[80:83]
	v_mfma_f32_16x16x32_bf16 v[72:75], v[168:171], v[192:195], v[72:75]
	v_mfma_f32_16x16x32_bf16 v[68:71], v[160:163], v[200:203], v[68:71]
	v_mfma_f32_16x16x32_bf16 v[64:67], v[168:171], v[200:203], v[64:67]
	v_mfma_f32_16x16x32_bf16 v[112:115], v[164:167], v[180:183], v[112:115]
	v_mfma_f32_16x16x32_bf16 v[104:107], v[172:175], v[180:183], v[104:107]
	v_mfma_f32_16x16x32_bf16 v[96:99], v[164:167], v[188:191], v[96:99]
	v_mfma_f32_16x16x32_bf16 v[88:91], v[172:175], v[188:191], v[88:91]
	v_mfma_f32_16x16x32_bf16 v[80:83], v[164:167], v[196:199], v[80:83]
	v_mfma_f32_16x16x32_bf16 v[72:75], v[172:175], v[196:199], v[72:75]
	v_mfma_f32_16x16x32_bf16 v[68:71], v[164:167], v[204:207], v[68:71]
	v_mfma_f32_16x16x32_bf16 v[64:67], v[172:175], v[204:207], v[64:67]
	s_setprio 0
	s_barrier
	s_add_i32 s28, s29, s35
	v_lshl_add_u64 v[140:141], s[84:85], 0, v[130:131]
	s_mov_b32 m0, s28
	ds_read_b128 v[176:179], v143 offset:16384
	ds_read_b128 v[180:183], v143 offset:17408
	ds_read_b128 v[184:187], v143 offset:18432
	ds_read_b128 v[188:191], v143 offset:19456
	ds_read_b128 v[192:195], v143 offset:20480
	ds_read_b128 v[196:199], v143 offset:21504
	ds_read_b128 v[200:203], v143 offset:22528
	ds_read_b128 v[204:207], v143 offset:23552
	global_load_lds_dwordx4 v[140:141], off
	s_add_i32 m0, s28, 0x2000
	s_add_u32 s28, s84, 0x20000
	v_lshl_add_u64 v[214:215], s[84:85], 0, v[134:135]
	s_addc_u32 s29, s85, 0
	s_add_i32 s3, s3, s35
	global_load_lds_dwordx4 v[214:215], off
	v_lshl_add_u64 v[216:217], s[28:29], 0, v[130:131]
	s_mov_b32 m0, s3
	v_lshl_add_u64 v[222:223], s[46:47], 0, v[132:133]
	global_load_lds_dwordx4 v[216:217], off
	v_lshl_add_u64 v[216:217], s[28:29], 0, v[134:135]
	s_add_i32 m0, s3, 0x2000
	s_nop 0
	global_load_lds_dwordx4 v[216:217], off
	v_lshl_add_u64 v[216:217], s[46:47], 0, v[128:129]
	s_mov_b32 m0, s48
	s_nop 0
	global_load_lds_dwordx4 v[216:217], off
	s_mov_b32 m0, s49
	s_nop 0
	global_load_lds_dwordx4 v[222:223], off
	s_waitcnt vmcnt(8)
	s_waitcnt lgkmcnt(0)
	s_barrier
; #define PG8_STAGE(bufoff, gbase, voff) do { _Pragma("unroll") for (int _i = 0; _i < 2; ++_i) \
;         __builtin_amdgcn_global_load_lds((const unsigned*)((const char*)(gbase) + (voff)[_i]), (PG8_LAS unsigned*)(lds + (bufoff) + ldsw + _i * 8192), 16, 0, 0); } while (0)
; #define PG8_LDA(dst, b, h) do { _Pragma("unroll") for (int m = 0; m < 4; ++m) _Pragma("unroll") for (int k = 0; k < 2; ++k) dst[m][k] = *(const PG8_LAS bf16x8*)(lds + PG8_SA(b, h) + aoff + m * 2048 + k * 1024); } while (0)
; #define PG8_LDB(dst, b, h) do { _Pragma("unroll") for (int n = 0; n < 2; ++n) _Pragma("unroll") for (int k = 0; k < 2; ++k) dst[n][k] = *(const PG8_LAS bf16x8*)(lds + PG8_SB(b, h) + boff + n * 2048 + k * 1024); } while (0)
; #define PG8_MMA(ai, bj, At, Bt) do { __builtin_amdgcn_s_setprio(1); _Pragma("unroll") for (int m = 0; m < 4; ++m) _Pragma("unroll") for (int n = 0; n < 2; ++n) _Pragma("unroll") for (int k = 0; k < 2; ++k) \
;         acc[ai][bj][m][n] = __builtin_amdgcn_mfma_f32_16x16x32_bf16(Bt[n][k], At[m][k], acc[ai][bj][m][n], 0, 0, 0); __builtin_amdgcn_s_setprio(0); } while (0)
; #define PG8_WAIT_V(n) asm volatile("s_waitcnt vmcnt(" #n ")" ::: "memory")
; #define PG8_WAIT_L(n) asm volatile("s_waitcnt lgkmcnt(" #n ")" ::: "memory")
; #define PG8_BAR __builtin_amdgcn_s_barrier()
; #define PG8_SCHED __builtin_amdgcn_sched_barrier(0)
; template <class Epi, class Sched, bool ALIGN_EPI = false, bool SP2 = false>
; __device__ __forceinline__ void gemm_phase(PG8_LAS unsigned char* lds, const Gemm g, const Sched& S, const Epi& E) {
;     ...
;             PG8_WAIT_V(8); PG8_WAIT_L(0); PG8_BAR; PG8_MMA(1, 0, At, B0); PG8_MMA(1, 1, At, B1); PG8_BAR; PG8_SCHED;
;             PG8_LDB(B0, 1, 0); PG8_LDB(B1, 1, 1); PG8_SCHED; PG8_LDA(At, 1, 0); PG8_STAGE(PG8_SA(0, 1), a2 + hstep, voffA);
;             PG8_WAIT_V(8); PG8_WAIT_L(0); PG8_BAR; PG8_MMA(0, 0, At, B0); PG8_MMA(0, 1, At, B1); PG8_BAR; PG8_SCHED;
	s_setprio 1
	s_waitcnt lgkmcnt(0)
	v_mfma_f32_16x16x32_bf16 v[60:63], v[144:147], v[176:179], v[60:63]
	v_mfma_f32_16x16x32_bf16 v[56:59], v[152:155], v[176:179], v[56:59]
	v_mfma_f32_16x16x32_bf16 v[52:55], v[144:147], v[184:187], v[52:55]
	v_mfma_f32_16x16x32_bf16 v[44:47], v[152:155], v[184:187], v[44:47]
	v_mfma_f32_16x16x32_bf16 v[36:39], v[144:147], v[192:195], v[36:39]
	v_mfma_f32_16x16x32_bf16 v[28:31], v[152:155], v[192:195], v[28:31]
	v_mfma_f32_16x16x32_bf16 v[20:23], v[144:147], v[200:203], v[20:23]
	v_mfma_f32_16x16x32_bf16 v[12:15], v[152:155], v[200:203], v[12:15]
	v_mfma_f32_16x16x32_bf16 v[60:63], v[148:151], v[180:183], v[60:63]
	v_mfma_f32_16x16x32_bf16 v[56:59], v[156:159], v[180:183], v[56:59]
	v_mfma_f32_16x16x32_bf16 v[52:55], v[148:151], v[188:191], v[52:55]
	v_mfma_f32_16x16x32_bf16 v[44:47], v[156:159], v[188:191], v[44:47]
	v_mfma_f32_16x16x32_bf16 v[36:39], v[148:151], v[196:199], v[36:39]
	v_mfma_f32_16x16x32_bf16 v[28:31], v[156:159], v[196:199], v[28:31]
	v_mfma_f32_16x16x32_bf16 v[20:23], v[148:151], v[204:207], v[20:23]
	v_mfma_f32_16x16x32_bf16 v[12:15], v[156:159], v[204:207], v[12:15]
	s_setprio 0
	s_setprio 1
	v_mfma_f32_16x16x32_bf16 v[48:51], v[160:163], v[176:179], v[48:51]
	v_mfma_f32_16x16x32_bf16 v[40:43], v[168:171], v[176:179], v[40:43]
	v_mfma_f32_16x16x32_bf16 v[32:35], v[160:163], v[184:187], v[32:35]
	v_mfma_f32_16x16x32_bf16 v[24:27], v[168:171], v[184:187], v[24:27]
	v_mfma_f32_16x16x32_bf16 v[16:19], v[160:163], v[192:195], v[16:19]
	v_mfma_f32_16x16x32_bf16 v[8:11], v[168:171], v[192:195], v[8:11]
	v_mfma_f32_16x16x32_bf16 v[4:7], v[160:163], v[200:203], v[4:7]
	v_mfma_f32_16x16x32_bf16 v[0:3], v[168:171], v[200:203], v[0:3]
	v_mfma_f32_16x16x32_bf16 v[48:51], v[164:167], v[180:183], v[48:51]
	v_mfma_f32_16x16x32_bf16 v[40:43], v[172:175], v[180:183], v[40:43]
	v_mfma_f32_16x16x32_bf16 v[32:35], v[164:167], v[188:191], v[32:35]
	v_mfma_f32_16x16x32_bf16 v[24:27], v[172:175], v[188:191], v[24:27]
	v_mfma_f32_16x16x32_bf16 v[16:19], v[164:167], v[196:199], v[16:19]
	v_mfma_f32_16x16x32_bf16 v[8:11], v[172:175], v[196:199], v[8:11]
	v_mfma_f32_16x16x32_bf16 v[4:7], v[164:167], v[204:207], v[4:7]
	v_mfma_f32_16x16x32_bf16 v[0:3], v[172:175], v[204:207], v[0:3]
	s_setprio 0
	s_barrier
	s_add_i32 s3, 0, 0x18000
	s_add_i32 s44, 0, 0x1c000
	v_add_u32_e32 v156, s3, v142
	v_add_u32_e32 v172, s44, v142
	ds_read_b128 v[144:147], v156
	ds_read_b128 v[148:151], v156 offset:1024
	ds_read_b128 v[152:155], v156 offset:2048
	ds_read_b128 v[156:159], v156 offset:3072
	ds_read_b128 v[160:163], v172
	ds_read_b128 v[164:167], v172 offset:1024
	ds_read_b128 v[168:171], v172 offset:2048
	ds_read_b128 v[172:175], v172 offset:3072
	s_add_u32 s28, s46, 0x20000
	s_addc_u32 s29, s47, 0
	s_mov_b32 m0, s50
	v_lshl_add_u64 v[224:225], s[28:29], 0, v[128:129]
	ds_read_b128 v[176:179], v143 offset:32768
	ds_read_b128 v[180:183], v143 offset:33792
	ds_read_b128 v[184:187], v143 offset:34816
	ds_read_b128 v[188:191], v143 offset:35840
	ds_read_b128 v[192:195], v143 offset:36864
	ds_read_b128 v[196:199], v143 offset:37888
	ds_read_b128 v[200:203], v143 offset:38912
	ds_read_b128 v[204:207], v143 offset:39936
	global_load_lds_dwordx4 v[224:225], off
	v_lshl_add_u64 v[224:225], s[28:29], 0, v[132:133]
	s_mov_b32 m0, s57
	s_nop 0
	global_load_lds_dwordx4 v[224:225], off
	s_waitcnt vmcnt(8)
	s_waitcnt lgkmcnt(0)
	s_barrier
	s_setprio 1
	s_waitcnt lgkmcnt(0)
	v_mfma_f32_16x16x32_bf16 v[124:127], v[144:147], v[176:179], v[124:127]
	v_mfma_f32_16x16x32_bf16 v[120:123], v[152:155], v[176:179], v[120:123]
	v_mfma_f32_16x16x32_bf16 v[116:119], v[144:147], v[184:187], v[116:119]
	v_mfma_f32_16x16x32_bf16 v[108:111], v[152:155], v[184:187], v[108:111]
	v_mfma_f32_16x16x32_bf16 v[100:103], v[144:147], v[192:195], v[100:103]
	v_mfma_f32_16x16x32_bf16 v[92:95], v[152:155], v[192:195], v[92:95]
	v_mfma_f32_16x16x32_bf16 v[84:87], v[144:147], v[200:203], v[84:87]
	v_mfma_f32_16x16x32_bf16 v[76:79], v[152:155], v[200:203], v[76:79]
	v_mfma_f32_16x16x32_bf16 v[124:127], v[148:151], v[180:183], v[124:127]
	v_mfma_f32_16x16x32_bf16 v[120:123], v[156:159], v[180:183], v[120:123]
	v_mfma_f32_16x16x32_bf16 v[116:119], v[148:151], v[188:191], v[116:119]
	v_mfma_f32_16x16x32_bf16 v[108:111], v[156:159], v[188:191], v[108:111]
	v_mfma_f32_16x16x32_bf16 v[100:103], v[148:151], v[196:199], v[100:103]
	v_mfma_f32_16x16x32_bf16 v[92:95], v[156:159], v[196:199], v[92:95]
	v_mfma_f32_16x16x32_bf16 v[84:87], v[148:151], v[204:207], v[84:87]
	v_mfma_f32_16x16x32_bf16 v[76:79], v[156:159], v[204:207], v[76:79]
	s_setprio 0
	s_setprio 1
	v_mfma_f32_16x16x32_bf16 v[112:115], v[160:163], v[176:179], v[112:115]
	v_mfma_f32_16x16x32_bf16 v[104:107], v[168:171], v[176:179], v[104:107]
	v_mfma_f32_16x16x32_bf16 v[96:99], v[160:163], v[184:187], v[96:99]
	v_mfma_f32_16x16x32_bf16 v[88:91], v[168:171], v[184:187], v[88:91]
	v_mfma_f32_16x16x32_bf16 v[80:83], v[160:163], v[192:195], v[80:83]
	v_mfma_f32_16x16x32_bf16 v[72:75], v[168:171], v[192:195], v[72:75]
	v_mfma_f32_16x16x32_bf16 v[68:71], v[160:163], v[200:203], v[68:71]
	v_mfma_f32_16x16x32_bf16 v[64:67], v[168:171], v[200:203], v[64:67]
	v_mfma_f32_16x16x32_bf16 v[112:115], v[164:167], v[180:183], v[112:115]
	v_mfma_f32_16x16x32_bf16 v[104:107], v[172:175], v[180:183], v[104:107]
	v_mfma_f32_16x16x32_bf16 v[96:99], v[164:167], v[188:191], v[96:99]
	v_mfma_f32_16x16x32_bf16 v[88:91], v[172:175], v[188:191], v[88:91]
	v_mfma_f32_16x16x32_bf16 v[80:83], v[164:167], v[196:199], v[80:83]
	v_mfma_f32_16x16x32_bf16 v[72:75], v[172:175], v[196:199], v[72:75]
	v_mfma_f32_16x16x32_bf16 v[68:71], v[164:167], v[204:207], v[68:71]
	v_mfma_f32_16x16x32_bf16 v[64:67], v[172:175], v[204:207], v[64:67]
	s_setprio 0
	s_barrier
; #define PG8_STAGE(bufoff, gbase, voff) do { _Pragma("unroll") for (int _i = 0; _i < 2; ++_i) \
;         __builtin_amdgcn_global_load_lds((const unsigned*)((const char*)(gbase) + (voff)[_i]), (PG8_LAS unsigned*)(lds + (bufoff) + ldsw + _i * 8192), 16, 0, 0); } while (0)
; #define PG8_LDA(dst, b, h) do { _Pragma("unroll") for (int m = 0; m < 4; ++m) _Pragma("unroll") for (int k = 0; k < 2; ++k) dst[m][k] = *(const PG8_LAS bf16x8*)(lds + PG8_SA(b, h) + aoff + m * 2048 + k * 1024); } while (0)
; #define PG8_MMA(ai, bj, At, Bt) do { __builtin_amdgcn_s_setprio(1); _Pragma("unroll") for (int m = 0; m < 4; ++m) _Pragma("unroll") for (int n = 0; n < 2; ++n) _Pragma("unroll") for (int k = 0; k < 2; ++k) \
;         acc[ai][bj][m][n] = __builtin_amdgcn_mfma_f32_16x16x32_bf16(Bt[n][k], At[m][k], acc[ai][bj][m][n], 0, 0, 0); __builtin_amdgcn_s_setprio(0); } while (0)
; #define PG8_WAIT_V(n) asm volatile("s_waitcnt vmcnt(" #n ")" ::: "memory")
; #define PG8_WAIT_L(n) asm volatile("s_waitcnt lgkmcnt(" #n ")" ::: "memory")
; #define PG8_BAR __builtin_amdgcn_s_barrier()
; #define PG8_SCHED __builtin_amdgcn_sched_barrier(0)
; template <class Epi, class Sched, bool ALIGN_EPI = false, bool SP2 = false>
; __device__ __forceinline__ void gemm_phase(PG8_LAS unsigned char* lds, const Gemm g, const Sched& S, const Epi& E) {
;     ...
;         for (int t = 0; t < nt; t += 2) {
;     ...
;             PG8_LDA(At, 1, 1); PG8_STAGE(PG8_SB(1, 0), b3, voffB); PG8_STAGE(PG8_SB(1, 1), b3 + hstep, voffB); PG8_STAGE(PG8_SA(1, 0), a3, voffA);
;             PG8_WAIT_V(8); PG8_WAIT_L(0); PG8_BAR; PG8_MMA(1, 0, At, B0); PG8_MMA(1, 1, At, B1); PG8_BAR; PG8_SCHED;
	s_add_i32 s3, s3, s35
	v_lshl_add_u64 v[140:141], v[140:141], 0, s[36:37]
	s_mov_b32 m0, s3
	ds_read_b128 v[176:179], v143 offset:49152
	ds_read_b128 v[180:183], v143 offset:50176
	ds_read_b128 v[184:187], v143 offset:51200
	ds_read_b128 v[188:191], v143 offset:52224
	ds_read_b128 v[192:195], v143 offset:53248
	ds_read_b128 v[196:199], v143 offset:54272
	ds_read_b128 v[200:203], v143 offset:55296
	ds_read_b128 v[204:207], v143 offset:56320
	global_load_lds_dwordx4 v[140:141], off
	s_add_i32 m0, s3, 0x2000
	s_add_u32 s28, s84, 0x20080
	v_lshl_add_u64 v[140:141], v[214:215], 0, s[36:37]
	s_addc_u32 s29, s85, 0
	s_add_i32 s3, s44, s35
	global_load_lds_dwordx4 v[140:141], off
	v_lshl_add_u64 v[140:141], s[28:29], 0, v[130:131]
	s_mov_b32 m0, s3
	s_nop 0
	global_load_lds_dwordx4 v[140:141], off
	v_lshl_add_u64 v[140:141], s[28:29], 0, v[134:135]
	s_add_i32 m0, s3, 0x2000
	s_nop 0
	global_load_lds_dwordx4 v[140:141], off
	v_lshl_add_u64 v[140:141], v[216:217], 0, s[36:37]
	s_mov_b32 m0, s58
	s_nop 0
	global_load_lds_dwordx4 v[140:141], off
	v_lshl_add_u64 v[140:141], v[222:223], 0, s[36:37]
	s_mov_b32 m0, s59
	s_nop 0
	global_load_lds_dwordx4 v[140:141], off
	s_waitcnt vmcnt(8)
	s_waitcnt lgkmcnt(0)
	s_barrier
	s_setprio 1
	s_waitcnt lgkmcnt(0)
	v_mfma_f32_16x16x32_bf16 v[60:63], v[144:147], v[176:179], v[60:63]
	v_mfma_f32_16x16x32_bf16 v[56:59], v[152:155], v[176:179], v[56:59]
	v_mfma_f32_16x16x32_bf16 v[52:55], v[144:147], v[184:187], v[52:55]
	v_mfma_f32_16x16x32_bf16 v[44:47], v[152:155], v[184:187], v[44:47]
	v_mfma_f32_16x16x32_bf16 v[36:39], v[144:147], v[192:195], v[36:39]
	v_mfma_f32_16x16x32_bf16 v[28:31], v[152:155], v[192:195], v[28:31]
	v_mfma_f32_16x16x32_bf16 v[20:23], v[144:147], v[200:203], v[20:23]
	v_mfma_f32_16x16x32_bf16 v[12:15], v[152:155], v[200:203], v[12:15]
	v_mfma_f32_16x16x32_bf16 v[60:63], v[148:151], v[180:183], v[60:63]
	v_mfma_f32_16x16x32_bf16 v[56:59], v[156:159], v[180:183], v[56:59]
	v_mfma_f32_16x16x32_bf16 v[52:55], v[148:151], v[188:191], v[52:55]
	v_mfma_f32_16x16x32_bf16 v[44:47], v[156:159], v[188:191], v[44:47]
	v_mfma_f32_16x16x32_bf16 v[36:39], v[148:151], v[196:199], v[36:39]
	v_mfma_f32_16x16x32_bf16 v[28:31], v[156:159], v[196:199], v[28:31]
	v_mfma_f32_16x16x32_bf16 v[20:23], v[148:151], v[204:207], v[20:23]
	v_mfma_f32_16x16x32_bf16 v[12:15], v[156:159], v[204:207], v[12:15]
	s_setprio 0
	s_setprio 1
	v_mfma_f32_16x16x32_bf16 v[48:51], v[160:163], v[176:179], v[48:51]
	v_mfma_f32_16x16x32_bf16 v[40:43], v[168:171], v[176:179], v[40:43]
	v_mfma_f32_16x16x32_bf16 v[32:35], v[160:163], v[184:187], v[32:35]
	v_mfma_f32_16x16x32_bf16 v[24:27], v[168:171], v[184:187], v[24:27]
	v_mfma_f32_16x16x32_bf16 v[16:19], v[160:163], v[192:195], v[16:19]
	v_mfma_f32_16x16x32_bf16 v[8:11], v[168:171], v[192:195], v[8:11]
	v_mfma_f32_16x16x32_bf16 v[4:7], v[160:163], v[200:203], v[4:7]
	v_mfma_f32_16x16x32_bf16 v[0:3], v[168:171], v[200:203], v[0:3]
	v_mfma_f32_16x16x32_bf16 v[48:51], v[164:167], v[180:183], v[48:51]
	v_mfma_f32_16x16x32_bf16 v[40:43], v[172:175], v[180:183], v[40:43]
	v_mfma_f32_16x16x32_bf16 v[32:35], v[164:167], v[188:191], v[32:35]
	v_mfma_f32_16x16x32_bf16 v[24:27], v[172:175], v[188:191], v[24:27]
	v_mfma_f32_16x16x32_bf16 v[16:19], v[164:167], v[196:199], v[16:19]
	v_mfma_f32_16x16x32_bf16 v[8:11], v[172:175], v[196:199], v[8:11]
	v_mfma_f32_16x16x32_bf16 v[4:7], v[164:167], v[204:207], v[4:7]
	v_mfma_f32_16x16x32_bf16 v[0:3], v[172:175], v[204:207], v[0:3]
	s_setprio 0
	s_add_i32 s86, s86, 2
	s_add_u32 s82, s82, 0x100
	s_addc_u32 s83, s83, 0
	s_add_u32 s72, s72, 0x100
	s_addc_u32 s79, s79, 0
	s_cmp_gt_u32 s86, 5
	s_barrier
	s_cbranch_scc0 .LBB0_381
	s_and_b64 vcc, exec, s[38:39]
	s_brev_b32 s44, 60
	s_cbranch_vccz .LBB0_384
	s_barrier

; #define PG8_STAGE(bufoff, gbase, voff) do { _Pragma("unroll") for (int _i = 0; _i < 2; ++_i) \
;         __builtin_amdgcn_global_load_lds((const unsigned*)((const char*)(gbase) + (voff)[_i]), (PG8_LAS unsigned*)(lds + (bufoff) + ldsw + _i * 8192), 16, 0, 0); } while (0)
; #define PG8_LDA(dst, b, h) do { _Pragma("unroll") for (int m = 0; m < 4; ++m) _Pragma("unroll") for (int k = 0; k < 2; ++k) dst[m][k] = *(const PG8_LAS bf16x8*)(lds + PG8_SA(b, h) + aoff + m * 2048 + k * 1024); } while (0)
; #define PG8_LDB(dst, b, h) do { _Pragma("unroll") for (int n = 0; n < 2; ++n) _Pragma("unroll") for (int k = 0; k < 2; ++k) dst[n][k] = *(const PG8_LAS bf16x8*)(lds + PG8_SB(b, h) + boff + n * 2048 + k * 1024); } while (0)
; #define PG8_MMA(ai, bj, At, Bt) do { __builtin_amdgcn_s_setprio(1); _Pragma("unroll") for (int m = 0; m < 4; ++m) _Pragma("unroll") for (int n = 0; n < 2; ++n) _Pragma("unroll") for (int k = 0; k < 2; ++k) \
;         acc[ai][bj][m][n] = __builtin_amdgcn_mfma_f32_16x16x32_bf16(Bt[n][k], At[m][k], acc[ai][bj][m][n], 0, 0, 0); __builtin_amdgcn_s_setprio(0); } while (0)
; #define PG8_WAIT_V(n) asm volatile("s_waitcnt vmcnt(" #n ")" ::: "memory")
; #define PG8_WAIT_L(n) asm volatile("s_waitcnt lgkmcnt(" #n ")" ::: "memory")
; template <class Epi, class Sched, bool ALIGN_EPI = false, bool SP2 = false>
; __device__ __forceinline__ void gemm_phase(PG8_LAS unsigned char* lds, const Gemm g, const Sched& S, const Epi& E) {
;     ...
;             const bool last = (t == nt - 2);
;             const char* a1 = cA + (size_t)(t + 1) * kstep;
;             const char* a2 = last ? nA : cA + (size_t)(t + 2) * kstep; const char* b2 = last ? nB : cB + (size_t)(t + 2) * kstep;
;             const char* a3 = a2 + kstep; const char* b3 = b2 + kstep;
;             if (last && has_next) S.a_ready(nxt);
;             if constexpr (SP2) {
;             PG8_LDB(B0, 0, 0); PG8_LDB(B1, 0, 1); PG8_SCHED; PG8_LDA(At, 0, 0); PG8_STAGE(PG8_SA(1, 1), a1 + hstep, voffA);
;             PG8_WAIT_V(8); PG8_WAIT_L(0); PG8_BAR; PG8_MMA(0, 0, At, B0); PG8_MMA(0, 1, At, B1); PG8_BAR; PG8_SCHED;
;             PG8_LDA(At, 0, 1); PG8_STAGE(PG8_SB(0, 0), b2, voffB); PG8_STAGE(PG8_SB(0, 1), b2 + hstep, voffB); PG8_STAGE(PG8_SA(0, 0), a2, voffA);
;             PG8_WAIT_V(8); PG8_WAIT_L(0); PG8_BAR; PG8_MMA(1, 0, At, B0); PG8_MMA(1, 1, At, B1); PG8_BAR; PG8_SCHED;
.LBB0_463:
	s_add_u32 s3, s78, 0xfffc0080
	s_addc_u32 s28, s79, -1
	s_add_i32 s29, 0, 0x10000
	s_cmp_eq_u32 s65, 12
	s_cselect_b32 s47, s27, s28
	s_cselect_b32 s46, s30, s3
	s_cselect_b32 s81, s34, s45
	s_cselect_b32 s80, s35, s43
	s_add_i32 s3, 0, 0x14000
	v_add_u32_e32 v52, s29, v161
	v_add_u32_e32 v158, s3, v161
	ds_read_b128 v[32:35], v52
	ds_read_b128 v[36:39], v52 offset:1024
	ds_read_b128 v[48:51], v52 offset:2048
	ds_read_b128 v[52:55], v52 offset:3072
	ds_read_b128 v[154:157], v158
	ds_read_b128 v[166:169], v158 offset:1024
	ds_read_b128 v[170:173], v158 offset:2048
	ds_read_b128 v[174:177], v158 offset:3072
	v_lshl_add_u64 v[158:159], s[78:79], 0, v[150:151]
	s_add_i32 m0, s77, 0xc000
	ds_read_b128 v[178:181], v164
	ds_read_b128 v[182:185], v164 offset:1024
	ds_read_b128 v[186:189], v164 offset:2048
	ds_read_b128 v[190:193], v164 offset:3072
	ds_read_b128 v[194:197], v164 offset:4096
	ds_read_b128 v[198:201], v164 offset:5120
	ds_read_b128 v[202:205], v164 offset:6144
	ds_read_b128 v[222:225], v164 offset:7168
	global_load_lds_dwordx4 v[158:159], off
	v_lshl_add_u64 v[158:159], s[78:79], 0, v[152:153]
	s_add_i32 m0, s77, 0xe000
	s_nop 0
	global_load_lds_dwordx4 v[158:159], off
	s_waitcnt vmcnt(8)
	s_waitcnt lgkmcnt(0)
	s_barrier
	s_setprio 1
	s_waitcnt lgkmcnt(0)
	v_mfma_f32_16x16x32_bf16 v[140:143], v[32:35], v[178:181], v[140:143]
	v_mfma_f32_16x16x32_bf16 v[136:139], v[48:51], v[178:181], v[136:139]
	v_mfma_f32_16x16x32_bf16 v[124:127], v[32:35], v[186:189], v[124:127]
	v_mfma_f32_16x16x32_bf16 v[120:123], v[48:51], v[186:189], v[120:123]
	v_mfma_f32_16x16x32_bf16 v[108:111], v[32:35], v[194:197], v[108:111]
	v_mfma_f32_16x16x32_bf16 v[104:107], v[48:51], v[194:197], v[104:107]
	v_mfma_f32_16x16x32_bf16 v[92:95], v[32:35], v[202:205], v[92:95]
	v_mfma_f32_16x16x32_bf16 v[88:91], v[48:51], v[202:205], v[88:91]
	v_mfma_f32_16x16x32_bf16 v[140:143], v[36:39], v[182:185], v[140:143]
	v_mfma_f32_16x16x32_bf16 v[136:139], v[52:55], v[182:185], v[136:139]
	v_mfma_f32_16x16x32_bf16 v[124:127], v[36:39], v[190:193], v[124:127]
	v_mfma_f32_16x16x32_bf16 v[120:123], v[52:55], v[190:193], v[120:123]
	v_mfma_f32_16x16x32_bf16 v[108:111], v[36:39], v[198:201], v[108:111]
	v_mfma_f32_16x16x32_bf16 v[104:107], v[52:55], v[198:201], v[104:107]
	v_mfma_f32_16x16x32_bf16 v[92:95], v[36:39], v[222:225], v[92:95]
	v_mfma_f32_16x16x32_bf16 v[88:91], v[52:55], v[222:225], v[88:91]
	s_setprio 0
	s_setprio 1
	v_mfma_f32_16x16x32_bf16 v[132:135], v[154:157], v[178:181], v[132:135]
	v_mfma_f32_16x16x32_bf16 v[128:131], v[170:173], v[178:181], v[128:131]
	v_mfma_f32_16x16x32_bf16 v[116:119], v[154:157], v[186:189], v[116:119]
	v_mfma_f32_16x16x32_bf16 v[112:115], v[170:173], v[186:189], v[112:115]
	v_mfma_f32_16x16x32_bf16 v[100:103], v[154:157], v[194:197], v[100:103]
	v_mfma_f32_16x16x32_bf16 v[96:99], v[170:173], v[194:197], v[96:99]
	v_mfma_f32_16x16x32_bf16 v[84:87], v[154:157], v[202:205], v[84:87]
	v_mfma_f32_16x16x32_bf16 v[80:83], v[170:173], v[202:205], v[80:83]
	v_mfma_f32_16x16x32_bf16 v[132:135], v[166:169], v[182:185], v[132:135]
	v_mfma_f32_16x16x32_bf16 v[128:131], v[174:177], v[182:185], v[128:131]
	v_mfma_f32_16x16x32_bf16 v[116:119], v[166:169], v[190:193], v[116:119]
	v_mfma_f32_16x16x32_bf16 v[112:115], v[174:177], v[190:193], v[112:115]
	v_mfma_f32_16x16x32_bf16 v[100:103], v[166:169], v[198:201], v[100:103]
	v_mfma_f32_16x16x32_bf16 v[96:99], v[174:177], v[198:201], v[96:99]
	v_mfma_f32_16x16x32_bf16 v[84:87], v[166:169], v[222:225], v[84:87]
	v_mfma_f32_16x16x32_bf16 v[80:83], v[174:177], v[222:225], v[80:83]
	s_setprio 0
	s_barrier
	s_add_i32 s28, s29, s82
	v_lshl_add_u64 v[158:159], s[80:81], 0, v[208:209]
	s_mov_b32 m0, s28
	ds_read_b128 v[178:181], v164 offset:16384
	ds_read_b128 v[182:185], v164 offset:17408
	ds_read_b128 v[186:189], v164 offset:18432
	ds_read_b128 v[190:193], v164 offset:19456
	ds_read_b128 v[194:197], v164 offset:20480
	ds_read_b128 v[198:201], v164 offset:21504
	ds_read_b128 v[202:205], v164 offset:22528
	ds_read_b128 v[222:225], v164 offset:23552
	global_load_lds_dwordx4 v[158:159], off
	s_add_i32 m0, s28, 0x2000
	s_add_u32 s28, s80, 0x40000
	v_lshl_add_u64 v[162:163], s[80:81], 0, v[144:145]
	s_addc_u32 s29, s81, 0
	s_add_i32 s3, s3, s82
	global_load_lds_dwordx4 v[162:163], off
	v_lshl_add_u64 v[206:207], s[28:29], 0, v[208:209]
	s_mov_b32 m0, s3
	v_lshl_add_u64 v[214:215], s[46:47], 0, v[146:147]
	global_load_lds_dwordx4 v[206:207], off
	v_lshl_add_u64 v[206:207], s[28:29], 0, v[144:145]
	s_add_i32 m0, s3, 0x2000
	s_nop 0
	global_load_lds_dwordx4 v[206:207], off
	v_lshl_add_u64 v[206:207], s[46:47], 0, v[148:149]
	s_mov_b32 m0, s77
	s_nop 0
	global_load_lds_dwordx4 v[206:207], off
	s_mov_b32 m0, s84
	s_nop 0
	global_load_lds_dwordx4 v[214:215], off
	s_waitcnt vmcnt(8)
	s_waitcnt lgkmcnt(0)
	s_barrier
; #define PG8_STAGE(bufoff, gbase, voff) do { _Pragma("unroll") for (int _i = 0; _i < 2; ++_i) \
;         __builtin_amdgcn_global_load_lds((const unsigned*)((const char*)(gbase) + (voff)[_i]), (PG8_LAS unsigned*)(lds + (bufoff) + ldsw + _i * 8192), 16, 0, 0); } while (0)
; #define PG8_LDA(dst, b, h) do { _Pragma("unroll") for (int m = 0; m < 4; ++m) _Pragma("unroll") for (int k = 0; k < 2; ++k) dst[m][k] = *(const PG8_LAS bf16x8*)(lds + PG8_SA(b, h) + aoff + m * 2048 + k * 1024); } while (0)
; #define PG8_LDB(dst, b, h) do { _Pragma("unroll") for (int n = 0; n < 2; ++n) _Pragma("unroll") for (int k = 0; k < 2; ++k) dst[n][k] = *(const PG8_LAS bf16x8*)(lds + PG8_SB(b, h) + boff + n * 2048 + k * 1024); } while (0)
; #define PG8_MMA(ai, bj, At, Bt) do { __builtin_amdgcn_s_setprio(1); _Pragma("unroll") for (int m = 0; m < 4; ++m) _Pragma("unroll") for (int n = 0; n < 2; ++n) _Pragma("unroll") for (int k = 0; k < 2; ++k) \
;         acc[ai][bj][m][n] = __builtin_amdgcn_mfma_f32_16x16x32_bf16(Bt[n][k], At[m][k], acc[ai][bj][m][n], 0, 0, 0); __builtin_amdgcn_s_setprio(0); } while (0)
; #define PG8_WAIT_V(n) asm volatile("s_waitcnt vmcnt(" #n ")" ::: "memory")
; #define PG8_WAIT_L(n) asm volatile("s_waitcnt lgkmcnt(" #n ")" ::: "memory")
; #define PG8_BAR __builtin_amdgcn_s_barrier()
; #define PG8_SCHED __builtin_amdgcn_sched_barrier(0)
; template <class Epi, class Sched, bool ALIGN_EPI = false, bool SP2 = false>
; __device__ __forceinline__ void gemm_phase(PG8_LAS unsigned char* lds, const Gemm g, const Sched& S, const Epi& E) {
;     ...
;             PG8_WAIT_V(8); PG8_WAIT_L(0); PG8_BAR; PG8_MMA(1, 0, At, B0); PG8_MMA(1, 1, At, B1); PG8_BAR; PG8_SCHED;
;             PG8_LDB(B0, 1, 0); PG8_LDB(B1, 1, 1); PG8_SCHED; PG8_LDA(At, 1, 0); PG8_STAGE(PG8_SA(0, 1), a2 + hstep, voffA);
;             PG8_WAIT_V(8); PG8_WAIT_L(0); PG8_BAR; PG8_MMA(0, 0, At, B0); PG8_MMA(0, 1, At, B1); PG8_BAR; PG8_SCHED;
	s_setprio 1
	s_waitcnt lgkmcnt(0)
	v_mfma_f32_16x16x32_bf16 v[76:79], v[32:35], v[178:181], v[76:79]
	v_mfma_f32_16x16x32_bf16 v[72:75], v[48:51], v[178:181], v[72:75]
	v_mfma_f32_16x16x32_bf16 v[60:63], v[32:35], v[186:189], v[60:63]
	v_mfma_f32_16x16x32_bf16 v[56:59], v[48:51], v[186:189], v[56:59]
	v_mfma_f32_16x16x32_bf16 v[28:31], v[32:35], v[194:197], v[28:31]
	v_mfma_f32_16x16x32_bf16 v[24:27], v[48:51], v[194:197], v[24:27]
	v_mfma_f32_16x16x32_bf16 v[12:15], v[32:35], v[202:205], v[12:15]
	v_mfma_f32_16x16x32_bf16 v[8:11], v[48:51], v[202:205], v[8:11]
	v_mfma_f32_16x16x32_bf16 v[76:79], v[36:39], v[182:185], v[76:79]
	v_mfma_f32_16x16x32_bf16 v[72:75], v[52:55], v[182:185], v[72:75]
	v_mfma_f32_16x16x32_bf16 v[60:63], v[36:39], v[190:193], v[60:63]
	v_mfma_f32_16x16x32_bf16 v[56:59], v[52:55], v[190:193], v[56:59]
	v_mfma_f32_16x16x32_bf16 v[28:31], v[36:39], v[198:201], v[28:31]
	v_mfma_f32_16x16x32_bf16 v[24:27], v[52:55], v[198:201], v[24:27]
	v_mfma_f32_16x16x32_bf16 v[12:15], v[36:39], v[222:225], v[12:15]
	v_mfma_f32_16x16x32_bf16 v[8:11], v[52:55], v[222:225], v[8:11]
	s_setprio 0
	s_setprio 1
	v_mfma_f32_16x16x32_bf16 v[44:47], v[154:157], v[186:189], v[44:47]
	v_mfma_f32_16x16x32_bf16 v[40:43], v[170:173], v[186:189], v[40:43]
	v_mfma_f32_16x16x32_bf16 v[20:23], v[154:157], v[194:197], v[20:23]
	v_mfma_f32_16x16x32_bf16 v[16:19], v[170:173], v[194:197], v[16:19]
	v_mfma_f32_16x16x32_bf16 v[4:7], v[154:157], v[202:205], v[4:7]
	v_mfma_f32_16x16x32_bf16 v[0:3], v[170:173], v[202:205], v[0:3]
	v_mfma_f32_16x16x32_bf16 v[32:35], v[154:157], v[178:181], v[68:71]
	v_mfma_f32_16x16x32_bf16 v[36:39], v[170:173], v[178:181], v[64:67]
	v_mfma_f32_16x16x32_bf16 v[44:47], v[166:169], v[190:193], v[44:47]
	v_mfma_f32_16x16x32_bf16 v[40:43], v[174:177], v[190:193], v[40:43]
	v_mfma_f32_16x16x32_bf16 v[20:23], v[166:169], v[198:201], v[20:23]
	v_mfma_f32_16x16x32_bf16 v[16:19], v[174:177], v[198:201], v[16:19]
	v_mfma_f32_16x16x32_bf16 v[4:7], v[166:169], v[222:225], v[4:7]
	v_mfma_f32_16x16x32_bf16 v[0:3], v[174:177], v[222:225], v[0:3]
	v_mfma_f32_16x16x32_bf16 v[32:35], v[166:169], v[182:185], v[32:35]
	v_mfma_f32_16x16x32_bf16 v[36:39], v[174:177], v[182:185], v[36:39]
	s_setprio 0
	s_barrier
	s_add_i32 s3, 0, 0x18000
	s_add_i32 s44, 0, 0x1c000
	v_add_u32_e32 v68, s3, v161
	v_add_u32_e32 v160, s44, v161
	ds_read_b128 v[48:51], v68
	ds_read_b128 v[52:55], v68 offset:1024
	ds_read_b128 v[64:67], v68 offset:2048
	ds_read_b128 v[68:71], v68 offset:3072
	ds_read_b128 v[154:157], v160
	ds_read_b128 v[166:169], v160 offset:1024
	ds_read_b128 v[170:173], v160 offset:2048
	ds_read_b128 v[174:177], v160 offset:3072
	s_add_u32 s28, s46, 0x40000
	s_addc_u32 s29, s47, 0
	s_mov_b32 m0, s85
	v_lshl_add_u64 v[216:217], s[28:29], 0, v[148:149]
	ds_read_b128 v[178:181], v164 offset:32768
	ds_read_b128 v[182:185], v164 offset:33792
	ds_read_b128 v[186:189], v164 offset:34816
	ds_read_b128 v[190:193], v164 offset:35840
	ds_read_b128 v[194:197], v164 offset:36864
	ds_read_b128 v[198:201], v164 offset:37888
	ds_read_b128 v[202:205], v164 offset:38912
	ds_read_b128 v[222:225], v164 offset:39936
	global_load_lds_dwordx4 v[216:217], off
	v_lshl_add_u64 v[216:217], s[28:29], 0, v[146:147]
	s_mov_b32 m0, s86
	s_nop 0
	global_load_lds_dwordx4 v[216:217], off
	s_waitcnt vmcnt(8)
	s_waitcnt lgkmcnt(0)
	s_barrier
	s_setprio 1
	s_waitcnt lgkmcnt(0)
	v_mfma_f32_16x16x32_bf16 v[140:143], v[48:51], v[178:181], v[140:143]
	v_mfma_f32_16x16x32_bf16 v[136:139], v[64:67], v[178:181], v[136:139]
	v_mfma_f32_16x16x32_bf16 v[124:127], v[48:51], v[186:189], v[124:127]
	v_mfma_f32_16x16x32_bf16 v[120:123], v[64:67], v[186:189], v[120:123]
	v_mfma_f32_16x16x32_bf16 v[108:111], v[48:51], v[194:197], v[108:111]
	v_mfma_f32_16x16x32_bf16 v[104:107], v[64:67], v[194:197], v[104:107]
	v_mfma_f32_16x16x32_bf16 v[92:95], v[48:51], v[202:205], v[92:95]
	v_mfma_f32_16x16x32_bf16 v[88:91], v[64:67], v[202:205], v[88:91]
	v_mfma_f32_16x16x32_bf16 v[140:143], v[52:55], v[182:185], v[140:143]
	v_mfma_f32_16x16x32_bf16 v[136:139], v[68:71], v[182:185], v[136:139]
	v_mfma_f32_16x16x32_bf16 v[124:127], v[52:55], v[190:193], v[124:127]
	v_mfma_f32_16x16x32_bf16 v[120:123], v[68:71], v[190:193], v[120:123]
	v_mfma_f32_16x16x32_bf16 v[108:111], v[52:55], v[198:201], v[108:111]
	v_mfma_f32_16x16x32_bf16 v[104:107], v[68:71], v[198:201], v[104:107]
	v_mfma_f32_16x16x32_bf16 v[92:95], v[52:55], v[222:225], v[92:95]
	v_mfma_f32_16x16x32_bf16 v[88:91], v[68:71], v[222:225], v[88:91]
	s_setprio 0
	s_setprio 1
	v_mfma_f32_16x16x32_bf16 v[132:135], v[154:157], v[178:181], v[132:135]
	v_mfma_f32_16x16x32_bf16 v[128:131], v[170:173], v[178:181], v[128:131]
	v_mfma_f32_16x16x32_bf16 v[116:119], v[154:157], v[186:189], v[116:119]
	v_mfma_f32_16x16x32_bf16 v[112:115], v[170:173], v[186:189], v[112:115]
	v_mfma_f32_16x16x32_bf16 v[100:103], v[154:157], v[194:197], v[100:103]
	v_mfma_f32_16x16x32_bf16 v[96:99], v[170:173], v[194:197], v[96:99]
	v_mfma_f32_16x16x32_bf16 v[84:87], v[154:157], v[202:205], v[84:87]
	v_mfma_f32_16x16x32_bf16 v[80:83], v[170:173], v[202:205], v[80:83]
	v_mfma_f32_16x16x32_bf16 v[132:135], v[166:169], v[182:185], v[132:135]
	v_mfma_f32_16x16x32_bf16 v[128:131], v[174:177], v[182:185], v[128:131]
	v_mfma_f32_16x16x32_bf16 v[116:119], v[166:169], v[190:193], v[116:119]
	v_mfma_f32_16x16x32_bf16 v[112:115], v[174:177], v[190:193], v[112:115]
	v_mfma_f32_16x16x32_bf16 v[100:103], v[166:169], v[198:201], v[100:103]
	v_mfma_f32_16x16x32_bf16 v[96:99], v[174:177], v[198:201], v[96:99]
	v_mfma_f32_16x16x32_bf16 v[84:87], v[166:169], v[222:225], v[84:87]
	v_mfma_f32_16x16x32_bf16 v[80:83], v[174:177], v[222:225], v[80:83]
	s_setprio 0
	s_barrier
; #define PG8_STAGE(bufoff, gbase, voff) do { _Pragma("unroll") for (int _i = 0; _i < 2; ++_i) \
;         __builtin_amdgcn_global_load_lds((const unsigned*)((const char*)(gbase) + (voff)[_i]), (PG8_LAS unsigned*)(lds + (bufoff) + ldsw + _i * 8192), 16, 0, 0); } while (0)
; #define PG8_LDA(dst, b, h) do { _Pragma("unroll") for (int m = 0; m < 4; ++m) _Pragma("unroll") for (int k = 0; k < 2; ++k) dst[m][k] = *(const PG8_LAS bf16x8*)(lds + PG8_SA(b, h) + aoff + m * 2048 + k * 1024); } while (0)
; #define PG8_MMA(ai, bj, At, Bt) do { __builtin_amdgcn_s_setprio(1); _Pragma("unroll") for (int m = 0; m < 4; ++m) _Pragma("unroll") for (int n = 0; n < 2; ++n) _Pragma("unroll") for (int k = 0; k < 2; ++k) \
;         acc[ai][bj][m][n] = __builtin_amdgcn_mfma_f32_16x16x32_bf16(Bt[n][k], At[m][k], acc[ai][bj][m][n], 0, 0, 0); __builtin_amdgcn_s_setprio(0); } while (0)
; #define PG8_WAIT_V(n) asm volatile("s_waitcnt vmcnt(" #n ")" ::: "memory")
; #define PG8_WAIT_L(n) asm volatile("s_waitcnt lgkmcnt(" #n ")" ::: "memory")
; #define PG8_BAR __builtin_amdgcn_s_barrier()
; #define PG8_SCHED __builtin_amdgcn_sched_barrier(0)
; template <class Epi, class Sched, bool ALIGN_EPI = false, bool SP2 = false>
; __device__ __forceinline__ void gemm_phase(PG8_LAS unsigned char* lds, const Gemm g, const Sched& S, const Epi& E) {
;     ...
;         for (int t = 0; t < nt; t += 2) {
;     ...
;             PG8_LDA(At, 1, 1); PG8_STAGE(PG8_SB(1, 0), b3, voffB); PG8_STAGE(PG8_SB(1, 1), b3 + hstep, voffB); PG8_STAGE(PG8_SA(1, 0), a3, voffA);
;             PG8_WAIT_V(8); PG8_WAIT_L(0); PG8_BAR; PG8_MMA(1, 0, At, B0); PG8_MMA(1, 1, At, B1); PG8_BAR; PG8_SCHED;
	s_add_i32 s3, s3, s82
	v_lshl_add_u64 v[158:159], v[158:159], 0, s[36:37]
	s_mov_b32 m0, s3
	ds_read_b128 v[178:181], v164 offset:49152
	ds_read_b128 v[182:185], v164 offset:50176
	ds_read_b128 v[186:189], v164 offset:51200
	ds_read_b128 v[190:193], v164 offset:52224
	ds_read_b128 v[194:197], v164 offset:53248
	ds_read_b128 v[198:201], v164 offset:54272
	ds_read_b128 v[202:205], v164 offset:55296
	ds_read_b128 v[222:225], v164 offset:56320
	global_load_lds_dwordx4 v[158:159], off
	s_add_i32 m0, s3, 0x2000
	s_add_u32 s28, s80, 0x40080
	v_lshl_add_u64 v[158:159], v[162:163], 0, s[36:37]
	s_addc_u32 s29, s81, 0
	s_add_i32 s3, s44, s82
	global_load_lds_dwordx4 v[158:159], off
	v_lshl_add_u64 v[158:159], s[28:29], 0, v[208:209]
	s_mov_b32 m0, s3
	s_nop 0
	global_load_lds_dwordx4 v[158:159], off
	v_lshl_add_u64 v[158:159], s[28:29], 0, v[144:145]
	s_add_i32 m0, s3, 0x2000
	s_nop 0
	global_load_lds_dwordx4 v[158:159], off
	v_lshl_add_u64 v[158:159], v[206:207], 0, s[36:37]
	s_mov_b32 m0, s59
	s_nop 0
	global_load_lds_dwordx4 v[158:159], off
	v_lshl_add_u64 v[158:159], v[214:215], 0, s[36:37]
	s_mov_b32 m0, s50
	s_nop 0
	global_load_lds_dwordx4 v[158:159], off
	s_waitcnt vmcnt(8)
	s_waitcnt lgkmcnt(0)
	s_barrier
	s_setprio 1
	s_waitcnt lgkmcnt(0)
	v_mfma_f32_16x16x32_bf16 v[76:79], v[48:51], v[178:181], v[76:79]
	v_mfma_f32_16x16x32_bf16 v[72:75], v[64:67], v[178:181], v[72:75]
	v_mfma_f32_16x16x32_bf16 v[60:63], v[48:51], v[186:189], v[60:63]
	v_mfma_f32_16x16x32_bf16 v[56:59], v[64:67], v[186:189], v[56:59]
	v_mfma_f32_16x16x32_bf16 v[28:31], v[48:51], v[194:197], v[28:31]
	v_mfma_f32_16x16x32_bf16 v[24:27], v[64:67], v[194:197], v[24:27]
	v_mfma_f32_16x16x32_bf16 v[12:15], v[48:51], v[202:205], v[12:15]
	v_mfma_f32_16x16x32_bf16 v[8:11], v[64:67], v[202:205], v[8:11]
	v_mfma_f32_16x16x32_bf16 v[76:79], v[52:55], v[182:185], v[76:79]
	v_mfma_f32_16x16x32_bf16 v[72:75], v[68:71], v[182:185], v[72:75]
	v_mfma_f32_16x16x32_bf16 v[60:63], v[52:55], v[190:193], v[60:63]
	v_mfma_f32_16x16x32_bf16 v[56:59], v[68:71], v[190:193], v[56:59]
	v_mfma_f32_16x16x32_bf16 v[28:31], v[52:55], v[198:201], v[28:31]
	v_mfma_f32_16x16x32_bf16 v[24:27], v[68:71], v[198:201], v[24:27]
	v_mfma_f32_16x16x32_bf16 v[12:15], v[52:55], v[222:225], v[12:15]
	v_mfma_f32_16x16x32_bf16 v[8:11], v[68:71], v[222:225], v[8:11]
	s_setprio 0
	s_setprio 1
	v_mfma_f32_16x16x32_bf16 v[32:35], v[154:157], v[178:181], v[32:35]
	v_mfma_f32_16x16x32_bf16 v[68:71], v[166:169], v[182:185], v[32:35]
	v_mfma_f32_16x16x32_bf16 v[32:35], v[170:173], v[178:181], v[36:39]
	v_mfma_f32_16x16x32_bf16 v[64:67], v[174:177], v[182:185], v[32:35]
	v_mfma_f32_16x16x32_bf16 v[32:35], v[154:157], v[186:189], v[44:47]
	v_mfma_f32_16x16x32_bf16 v[44:47], v[166:169], v[190:193], v[32:35]
	v_mfma_f32_16x16x32_bf16 v[32:35], v[170:173], v[186:189], v[40:43]
	v_mfma_f32_16x16x32_bf16 v[20:23], v[154:157], v[194:197], v[20:23]
	v_mfma_f32_16x16x32_bf16 v[16:19], v[170:173], v[194:197], v[16:19]
	v_mfma_f32_16x16x32_bf16 v[4:7], v[154:157], v[202:205], v[4:7]
	v_mfma_f32_16x16x32_bf16 v[0:3], v[170:173], v[202:205], v[0:3]
	v_mfma_f32_16x16x32_bf16 v[40:43], v[174:177], v[190:193], v[32:35]
	v_mfma_f32_16x16x32_bf16 v[20:23], v[166:169], v[198:201], v[20:23]
	v_mfma_f32_16x16x32_bf16 v[16:19], v[174:177], v[198:201], v[16:19]
	v_mfma_f32_16x16x32_bf16 v[4:7], v[166:169], v[222:225], v[4:7]
	v_mfma_f32_16x16x32_bf16 v[0:3], v[174:177], v[222:225], v[0:3]
	s_setprio 0
	s_add_i32 s65, s65, 2
	s_add_u32 s78, s78, 0x100
	s_addc_u32 s79, s79, 0
	s_add_u32 s43, s43, 0x100
	s_addc_u32 s45, s45, 0
	s_cmp_gt_u32 s65, 13
	s_barrier
	s_cbranch_scc0 .LBB0_463
	s_and_b64 vcc, exec, s[40:41]
	s_cbranch_vccz .LBB0_466
	s_barrier

; #define PG8_STAGE(bufoff, gbase, voff) do { _Pragma("unroll") for (int _i = 0; _i < 2; ++_i) \
;         __builtin_amdgcn_global_load_lds((const unsigned*)((const char*)(gbase) + (voff)[_i]), (PG8_LAS unsigned*)(lds + (bufoff) + ldsw + _i * 8192), 16, 0, 0); } while (0)
; #define PG8_LDA(dst, b, h) do { _Pragma("unroll") for (int m = 0; m < 4; ++m) _Pragma("unroll") for (int k = 0; k < 2; ++k) dst[m][k] = *(const PG8_LAS bf16x8*)(lds + PG8_SA(b, h) + aoff + m * 2048 + k * 1024); } while (0)
; #define PG8_LDB(dst, b, h) do { _Pragma("unroll") for (int n = 0; n < 2; ++n) _Pragma("unroll") for (int k = 0; k < 2; ++k) dst[n][k] = *(const PG8_LAS bf16x8*)(lds + PG8_SB(b, h) + boff + n * 2048 + k * 1024); } while (0)
; #define PG8_MMA(ai, bj, At, Bt) do { __builtin_amdgcn_s_setprio(1); _Pragma("unroll") for (int m = 0; m < 4; ++m) _Pragma("unroll") for (int n = 0; n < 2; ++n) _Pragma("unroll") for (int k = 0; k < 2; ++k) \
;         acc[ai][bj][m][n] = __builtin_amdgcn_mfma_f32_16x16x32_bf16(Bt[n][k], At[m][k], acc[ai][bj][m][n], 0, 0, 0); __builtin_amdgcn_s_setprio(0); } while (0)
; #define PG8_WAIT_V(n) asm volatile("s_waitcnt vmcnt(" #n ")" ::: "memory")
; #define PG8_WAIT_L(n) asm volatile("s_waitcnt lgkmcnt(" #n ")" ::: "memory")
; template <class Epi, class Sched, bool ALIGN_EPI = false, bool SP2 = false>
; __device__ __forceinline__ void gemm_phase(PG8_LAS unsigned char* lds, const Gemm g, const Sched& S, const Epi& E) {
;     ...
;             const bool last = (t == nt - 2);
;             const char* a1 = cA + (size_t)(t + 1) * kstep;
;             const char* a2 = last ? nA : cA + (size_t)(t + 2) * kstep; const char* b2 = last ? nB : cB + (size_t)(t + 2) * kstep;
;             const char* a3 = a2 + kstep; const char* b3 = b2 + kstep;
;             if (last && has_next) S.a_ready(nxt);
;             if constexpr (SP2) {
;             PG8_LDB(B0, 0, 0); PG8_LDB(B1, 0, 1); PG8_SCHED; PG8_LDA(At, 0, 0); PG8_STAGE(PG8_SA(1, 1), a1 + hstep, voffA);
;             PG8_WAIT_V(8); PG8_WAIT_L(0); PG8_BAR; PG8_MMA(0, 0, At, B0); PG8_MMA(0, 1, At, B1); PG8_BAR; PG8_SCHED;
;             PG8_LDA(At, 0, 1); PG8_STAGE(PG8_SB(0, 0), b2, voffB); PG8_STAGE(PG8_SB(0, 1), b2 + hstep, voffB); PG8_STAGE(PG8_SA(0, 0), a2, voffA);
;             PG8_WAIT_V(8); PG8_WAIT_L(0); PG8_BAR; PG8_MMA(1, 0, At, B0); PG8_MMA(1, 1, At, B1); PG8_BAR; PG8_SCHED;
.LBB0_481:
	s_add_u32 s3, s80, 0xfffc0080
	s_addc_u32 s28, s81, -1
	s_add_i32 s29, 0, 0x10000
	s_cmp_eq_u32 s84, 12
	s_cselect_b32 s47, s30, s28
	s_cselect_b32 s46, s41, s3
	v_add_u32_e32 v148, s29, v149
	s_cselect_b32 s83, s43, s69
	s_cselect_b32 s82, s45, s67
	s_add_i32 s3, 0, 0x14000
	ds_read_b128 v[128:131], v148
	ds_read_b128 v[132:135], v148 offset:1024
	ds_read_b128 v[150:153], v148 offset:2048
	ds_read_b128 v[154:157], v148 offset:3072
	v_add_u32_e32 v148, s3, v149
	ds_read_b128 v[158:161], v148
	ds_read_b128 v[162:165], v148 offset:1024
	ds_read_b128 v[166:169], v148 offset:2048
	ds_read_b128 v[170:173], v148 offset:3072
	v_lshl_add_u64 v[214:215], s[80:81], 0, v[144:145]
	s_add_i32 m0, s49, 0xc000
	ds_read_b128 v[176:179], v174
	ds_read_b128 v[180:183], v174 offset:1024
	ds_read_b128 v[184:187], v174 offset:2048
	ds_read_b128 v[188:191], v174 offset:3072
	ds_read_b128 v[192:195], v174 offset:4096
	ds_read_b128 v[196:199], v174 offset:5120
	ds_read_b128 v[200:203], v174 offset:6144
	ds_read_b128 v[204:207], v174 offset:7168
	global_load_lds_dwordx4 v[214:215], off
	v_lshl_add_u64 v[214:215], s[80:81], 0, v[146:147]
	s_add_i32 m0, s49, 0xe000
	s_nop 0
	global_load_lds_dwordx4 v[214:215], off
	s_waitcnt vmcnt(8)
	s_waitcnt lgkmcnt(0)
	s_barrier
	s_setprio 1
	s_waitcnt lgkmcnt(0)
	v_mfma_f32_16x16x32_bf16 v[124:127], v[128:131], v[176:179], v[124:127]
	v_mfma_f32_16x16x32_bf16 v[120:123], v[150:153], v[176:179], v[120:123]
	v_mfma_f32_16x16x32_bf16 v[108:111], v[128:131], v[184:187], v[108:111]
	v_mfma_f32_16x16x32_bf16 v[104:107], v[150:153], v[184:187], v[104:107]
	v_mfma_f32_16x16x32_bf16 v[92:95], v[128:131], v[192:195], v[92:95]
	v_mfma_f32_16x16x32_bf16 v[88:91], v[150:153], v[192:195], v[88:91]
	v_mfma_f32_16x16x32_bf16 v[76:79], v[128:131], v[200:203], v[76:79]
	v_mfma_f32_16x16x32_bf16 v[72:75], v[150:153], v[200:203], v[72:75]
	v_mfma_f32_16x16x32_bf16 v[124:127], v[132:135], v[180:183], v[124:127]
	v_mfma_f32_16x16x32_bf16 v[120:123], v[154:157], v[180:183], v[120:123]
	v_mfma_f32_16x16x32_bf16 v[108:111], v[132:135], v[188:191], v[108:111]
	v_mfma_f32_16x16x32_bf16 v[104:107], v[154:157], v[188:191], v[104:107]
	v_mfma_f32_16x16x32_bf16 v[92:95], v[132:135], v[196:199], v[92:95]
	v_mfma_f32_16x16x32_bf16 v[88:91], v[154:157], v[196:199], v[88:91]
	v_mfma_f32_16x16x32_bf16 v[76:79], v[132:135], v[204:207], v[76:79]
	v_mfma_f32_16x16x32_bf16 v[72:75], v[154:157], v[204:207], v[72:75]
	s_setprio 0
	s_setprio 1
	v_mfma_f32_16x16x32_bf16 v[116:119], v[158:161], v[176:179], v[116:119]
	v_mfma_f32_16x16x32_bf16 v[112:115], v[166:169], v[176:179], v[112:115]
	v_mfma_f32_16x16x32_bf16 v[100:103], v[158:161], v[184:187], v[100:103]
	v_mfma_f32_16x16x32_bf16 v[96:99], v[166:169], v[184:187], v[96:99]
	v_mfma_f32_16x16x32_bf16 v[84:87], v[158:161], v[192:195], v[84:87]
	v_mfma_f32_16x16x32_bf16 v[80:83], v[166:169], v[192:195], v[80:83]
	v_mfma_f32_16x16x32_bf16 v[68:71], v[158:161], v[200:203], v[68:71]
	v_mfma_f32_16x16x32_bf16 v[64:67], v[166:169], v[200:203], v[64:67]
	v_mfma_f32_16x16x32_bf16 v[116:119], v[162:165], v[180:183], v[116:119]
	v_mfma_f32_16x16x32_bf16 v[112:115], v[170:173], v[180:183], v[112:115]
	v_mfma_f32_16x16x32_bf16 v[100:103], v[162:165], v[188:191], v[100:103]
	v_mfma_f32_16x16x32_bf16 v[96:99], v[170:173], v[188:191], v[96:99]
	v_mfma_f32_16x16x32_bf16 v[84:87], v[162:165], v[196:199], v[84:87]
	v_mfma_f32_16x16x32_bf16 v[80:83], v[170:173], v[196:199], v[80:83]
	v_mfma_f32_16x16x32_bf16 v[68:71], v[162:165], v[204:207], v[68:71]
	v_mfma_f32_16x16x32_bf16 v[64:67], v[170:173], v[204:207], v[64:67]
	s_setprio 0
	s_barrier
	s_add_i32 s28, s29, s34
	v_lshl_add_u64 v[214:215], s[82:83], 0, v[138:139]
	s_mov_b32 m0, s28
	ds_read_b128 v[176:179], v174 offset:16384
	ds_read_b128 v[180:183], v174 offset:17408
	ds_read_b128 v[184:187], v174 offset:18432
	ds_read_b128 v[188:191], v174 offset:19456
	ds_read_b128 v[192:195], v174 offset:20480
	ds_read_b128 v[196:199], v174 offset:21504
	ds_read_b128 v[200:203], v174 offset:22528
	ds_read_b128 v[204:207], v174 offset:23552
	global_load_lds_dwordx4 v[214:215], off
	s_add_i32 m0, s28, 0x2000
	s_add_u32 s28, s82, 0x40000
	v_lshl_add_u64 v[216:217], s[82:83], 0, v[142:143]
	s_addc_u32 s29, s83, 0
	s_add_i32 s3, s3, s34
	global_load_lds_dwordx4 v[216:217], off
	v_lshl_add_u64 v[222:223], s[28:29], 0, v[138:139]
	s_mov_b32 m0, s3
	v_lshl_add_u64 v[224:225], s[46:47], 0, v[140:141]
	global_load_lds_dwordx4 v[222:223], off
	v_lshl_add_u64 v[222:223], s[28:29], 0, v[142:143]
	s_add_i32 m0, s3, 0x2000
	s_nop 0
	global_load_lds_dwordx4 v[222:223], off
	v_lshl_add_u64 v[222:223], s[46:47], 0, v[136:137]
	s_mov_b32 m0, s49
	s_nop 0
	global_load_lds_dwordx4 v[222:223], off
	s_mov_b32 m0, s50
	s_nop 0
	global_load_lds_dwordx4 v[224:225], off
	s_waitcnt vmcnt(8)
	s_waitcnt lgkmcnt(0)
	s_barrier
; #define PG8_STAGE(bufoff, gbase, voff) do { _Pragma("unroll") for (int _i = 0; _i < 2; ++_i) \
;         __builtin_amdgcn_global_load_lds((const unsigned*)((const char*)(gbase) + (voff)[_i]), (PG8_LAS unsigned*)(lds + (bufoff) + ldsw + _i * 8192), 16, 0, 0); } while (0)
; #define PG8_LDA(dst, b, h) do { _Pragma("unroll") for (int m = 0; m < 4; ++m) _Pragma("unroll") for (int k = 0; k < 2; ++k) dst[m][k] = *(const PG8_LAS bf16x8*)(lds + PG8_SA(b, h) + aoff + m * 2048 + k * 1024); } while (0)
; #define PG8_LDB(dst, b, h) do { _Pragma("unroll") for (int n = 0; n < 2; ++n) _Pragma("unroll") for (int k = 0; k < 2; ++k) dst[n][k] = *(const PG8_LAS bf16x8*)(lds + PG8_SB(b, h) + boff + n * 2048 + k * 1024); } while (0)
; #define PG8_MMA(ai, bj, At, Bt) do { __builtin_amdgcn_s_setprio(1); _Pragma("unroll") for (int m = 0; m < 4; ++m) _Pragma("unroll") for (int n = 0; n < 2; ++n) _Pragma("unroll") for (int k = 0; k < 2; ++k) \
;         acc[ai][bj][m][n] = __builtin_amdgcn_mfma_f32_16x16x32_bf16(Bt[n][k], At[m][k], acc[ai][bj][m][n], 0, 0, 0); __builtin_amdgcn_s_setprio(0); } while (0)
; #define PG8_WAIT_V(n) asm volatile("s_waitcnt vmcnt(" #n ")" ::: "memory")
; #define PG8_WAIT_L(n) asm volatile("s_waitcnt lgkmcnt(" #n ")" ::: "memory")
; #define PG8_BAR __builtin_amdgcn_s_barrier()
; #define PG8_SCHED __builtin_amdgcn_sched_barrier(0)
; template <class Epi, class Sched, bool ALIGN_EPI = false, bool SP2 = false>
; __device__ __forceinline__ void gemm_phase(PG8_LAS unsigned char* lds, const Gemm g, const Sched& S, const Epi& E) {
;     ...
;             PG8_WAIT_V(8); PG8_WAIT_L(0); PG8_BAR; PG8_MMA(1, 0, At, B0); PG8_MMA(1, 1, At, B1); PG8_BAR; PG8_SCHED;
;             PG8_LDB(B0, 1, 0); PG8_LDB(B1, 1, 1); PG8_SCHED; PG8_LDA(At, 1, 0); PG8_STAGE(PG8_SA(0, 1), a2 + hstep, voffA);
;             PG8_WAIT_V(8); PG8_WAIT_L(0); PG8_BAR; PG8_MMA(0, 0, At, B0); PG8_MMA(0, 1, At, B1); PG8_BAR; PG8_SCHED;
	s_setprio 1
	s_waitcnt lgkmcnt(0)
	v_mfma_f32_16x16x32_bf16 v[60:63], v[128:131], v[176:179], v[60:63]
	v_mfma_f32_16x16x32_bf16 v[56:59], v[150:153], v[176:179], v[56:59]
	v_mfma_f32_16x16x32_bf16 v[44:47], v[128:131], v[184:187], v[44:47]
	v_mfma_f32_16x16x32_bf16 v[40:43], v[150:153], v[184:187], v[40:43]
	v_mfma_f32_16x16x32_bf16 v[28:31], v[128:131], v[192:195], v[28:31]
	v_mfma_f32_16x16x32_bf16 v[24:27], v[150:153], v[192:195], v[24:27]
	v_mfma_f32_16x16x32_bf16 v[12:15], v[128:131], v[200:203], v[12:15]
	v_mfma_f32_16x16x32_bf16 v[8:11], v[150:153], v[200:203], v[8:11]
	v_mfma_f32_16x16x32_bf16 v[60:63], v[132:135], v[180:183], v[60:63]
	v_mfma_f32_16x16x32_bf16 v[56:59], v[154:157], v[180:183], v[56:59]
	v_mfma_f32_16x16x32_bf16 v[44:47], v[132:135], v[188:191], v[44:47]
	v_mfma_f32_16x16x32_bf16 v[40:43], v[154:157], v[188:191], v[40:43]
	v_mfma_f32_16x16x32_bf16 v[28:31], v[132:135], v[196:199], v[28:31]
	v_mfma_f32_16x16x32_bf16 v[24:27], v[154:157], v[196:199], v[24:27]
	v_mfma_f32_16x16x32_bf16 v[12:15], v[132:135], v[204:207], v[12:15]
	v_mfma_f32_16x16x32_bf16 v[8:11], v[154:157], v[204:207], v[8:11]
	s_setprio 0
	s_setprio 1
	v_mfma_f32_16x16x32_bf16 v[52:55], v[158:161], v[176:179], v[52:55]
	v_mfma_f32_16x16x32_bf16 v[48:51], v[166:169], v[176:179], v[48:51]
	v_mfma_f32_16x16x32_bf16 v[36:39], v[158:161], v[184:187], v[36:39]
	v_mfma_f32_16x16x32_bf16 v[32:35], v[166:169], v[184:187], v[32:35]
	v_mfma_f32_16x16x32_bf16 v[20:23], v[158:161], v[192:195], v[20:23]
	v_mfma_f32_16x16x32_bf16 v[16:19], v[166:169], v[192:195], v[16:19]
	v_mfma_f32_16x16x32_bf16 v[4:7], v[158:161], v[200:203], v[4:7]
	v_mfma_f32_16x16x32_bf16 v[0:3], v[166:169], v[200:203], v[0:3]
	v_mfma_f32_16x16x32_bf16 v[52:55], v[162:165], v[180:183], v[52:55]
	v_mfma_f32_16x16x32_bf16 v[48:51], v[170:173], v[180:183], v[48:51]
	v_mfma_f32_16x16x32_bf16 v[36:39], v[162:165], v[188:191], v[36:39]
	v_mfma_f32_16x16x32_bf16 v[32:35], v[170:173], v[188:191], v[32:35]
	v_mfma_f32_16x16x32_bf16 v[20:23], v[162:165], v[196:199], v[20:23]
	v_mfma_f32_16x16x32_bf16 v[16:19], v[170:173], v[196:199], v[16:19]
	v_mfma_f32_16x16x32_bf16 v[4:7], v[162:165], v[204:207], v[4:7]
	v_mfma_f32_16x16x32_bf16 v[0:3], v[170:173], v[204:207], v[0:3]
	s_setprio 0
	s_barrier
	s_add_i32 s3, 0, 0x18000
	v_add_u32_e32 v148, s3, v149
	s_add_i32 s44, 0, 0x1c000
	ds_read_b128 v[128:131], v148
	ds_read_b128 v[132:135], v148 offset:1024
	ds_read_b128 v[150:153], v148 offset:2048
	ds_read_b128 v[154:157], v148 offset:3072
	v_add_u32_e32 v148, s44, v149
	ds_read_b128 v[158:161], v148
	ds_read_b128 v[162:165], v148 offset:1024
	ds_read_b128 v[166:169], v148 offset:2048
	ds_read_b128 v[170:173], v148 offset:3072
	s_add_u32 s28, s46, 0x40000
	s_addc_u32 s29, s47, 0
	s_mov_b32 m0, s55
	v_lshl_add_u64 v[226:227], s[28:29], 0, v[136:137]
	ds_read_b128 v[176:179], v174 offset:32768
	ds_read_b128 v[180:183], v174 offset:33792
	ds_read_b128 v[184:187], v174 offset:34816
	ds_read_b128 v[188:191], v174 offset:35840
	ds_read_b128 v[192:195], v174 offset:36864
	ds_read_b128 v[196:199], v174 offset:37888
	ds_read_b128 v[200:203], v174 offset:38912
	ds_read_b128 v[204:207], v174 offset:39936
	global_load_lds_dwordx4 v[226:227], off
	v_lshl_add_u64 v[226:227], s[28:29], 0, v[140:141]
	s_mov_b32 m0, s56
	s_nop 0
	global_load_lds_dwordx4 v[226:227], off
	s_waitcnt vmcnt(8)
	s_waitcnt lgkmcnt(0)
	s_barrier
	s_setprio 1
	s_waitcnt lgkmcnt(0)
	v_mfma_f32_16x16x32_bf16 v[124:127], v[128:131], v[176:179], v[124:127]
	v_mfma_f32_16x16x32_bf16 v[120:123], v[150:153], v[176:179], v[120:123]
	v_mfma_f32_16x16x32_bf16 v[108:111], v[128:131], v[184:187], v[108:111]
	v_mfma_f32_16x16x32_bf16 v[104:107], v[150:153], v[184:187], v[104:107]
	v_mfma_f32_16x16x32_bf16 v[92:95], v[128:131], v[192:195], v[92:95]
	v_mfma_f32_16x16x32_bf16 v[88:91], v[150:153], v[192:195], v[88:91]
	v_mfma_f32_16x16x32_bf16 v[76:79], v[128:131], v[200:203], v[76:79]
	v_mfma_f32_16x16x32_bf16 v[72:75], v[150:153], v[200:203], v[72:75]
	v_mfma_f32_16x16x32_bf16 v[124:127], v[132:135], v[180:183], v[124:127]
	v_mfma_f32_16x16x32_bf16 v[120:123], v[154:157], v[180:183], v[120:123]
	v_mfma_f32_16x16x32_bf16 v[108:111], v[132:135], v[188:191], v[108:111]
	v_mfma_f32_16x16x32_bf16 v[104:107], v[154:157], v[188:191], v[104:107]
	v_mfma_f32_16x16x32_bf16 v[92:95], v[132:135], v[196:199], v[92:95]
	v_mfma_f32_16x16x32_bf16 v[88:91], v[154:157], v[196:199], v[88:91]
	v_mfma_f32_16x16x32_bf16 v[76:79], v[132:135], v[204:207], v[76:79]
	v_mfma_f32_16x16x32_bf16 v[72:75], v[154:157], v[204:207], v[72:75]
	s_setprio 0
	s_setprio 1
	v_mfma_f32_16x16x32_bf16 v[116:119], v[158:161], v[176:179], v[116:119]
	v_mfma_f32_16x16x32_bf16 v[112:115], v[166:169], v[176:179], v[112:115]
	v_mfma_f32_16x16x32_bf16 v[100:103], v[158:161], v[184:187], v[100:103]
	v_mfma_f32_16x16x32_bf16 v[96:99], v[166:169], v[184:187], v[96:99]
	v_mfma_f32_16x16x32_bf16 v[84:87], v[158:161], v[192:195], v[84:87]
	v_mfma_f32_16x16x32_bf16 v[80:83], v[166:169], v[192:195], v[80:83]
	v_mfma_f32_16x16x32_bf16 v[68:71], v[158:161], v[200:203], v[68:71]
	v_mfma_f32_16x16x32_bf16 v[64:67], v[166:169], v[200:203], v[64:67]
	v_mfma_f32_16x16x32_bf16 v[116:119], v[162:165], v[180:183], v[116:119]
	v_mfma_f32_16x16x32_bf16 v[112:115], v[170:173], v[180:183], v[112:115]
	v_mfma_f32_16x16x32_bf16 v[100:103], v[162:165], v[188:191], v[100:103]
	v_mfma_f32_16x16x32_bf16 v[96:99], v[170:173], v[188:191], v[96:99]
	v_mfma_f32_16x16x32_bf16 v[84:87], v[162:165], v[196:199], v[84:87]
	v_mfma_f32_16x16x32_bf16 v[80:83], v[170:173], v[196:199], v[80:83]
	v_mfma_f32_16x16x32_bf16 v[68:71], v[162:165], v[204:207], v[68:71]
	v_mfma_f32_16x16x32_bf16 v[64:67], v[170:173], v[204:207], v[64:67]
	s_setprio 0
	s_barrier
; #define PG8_STAGE(bufoff, gbase, voff) do { _Pragma("unroll") for (int _i = 0; _i < 2; ++_i) \
;         __builtin_amdgcn_global_load_lds((const unsigned*)((const char*)(gbase) + (voff)[_i]), (PG8_LAS unsigned*)(lds + (bufoff) + ldsw + _i * 8192), 16, 0, 0); } while (0)
; #define PG8_LDA(dst, b, h) do { _Pragma("unroll") for (int m = 0; m < 4; ++m) _Pragma("unroll") for (int k = 0; k < 2; ++k) dst[m][k] = *(const PG8_LAS bf16x8*)(lds + PG8_SA(b, h) + aoff + m * 2048 + k * 1024); } while (0)
; #define PG8_MMA(ai, bj, At, Bt) do { __builtin_amdgcn_s_setprio(1); _Pragma("unroll") for (int m = 0; m < 4; ++m) _Pragma("unroll") for (int n = 0; n < 2; ++n) _Pragma("unroll") for (int k = 0; k < 2; ++k) \
;         acc[ai][bj][m][n] = __builtin_amdgcn_mfma_f32_16x16x32_bf16(Bt[n][k], At[m][k], acc[ai][bj][m][n], 0, 0, 0); __builtin_amdgcn_s_setprio(0); } while (0)
; #define PG8_WAIT_V(n) asm volatile("s_waitcnt vmcnt(" #n ")" ::: "memory")
; #define PG8_WAIT_L(n) asm volatile("s_waitcnt lgkmcnt(" #n ")" ::: "memory")
; #define PG8_BAR __builtin_amdgcn_s_barrier()
; #define PG8_SCHED __builtin_amdgcn_sched_barrier(0)
; template <class Epi, class Sched, bool ALIGN_EPI = false, bool SP2 = false>
; __device__ __forceinline__ void gemm_phase(PG8_LAS unsigned char* lds, const Gemm g, const Sched& S, const Epi& E) {
;     ...
;         for (int t = 0; t < nt; t += 2) {
;     ...
;             PG8_LDA(At, 1, 1); PG8_STAGE(PG8_SB(1, 0), b3, voffB); PG8_STAGE(PG8_SB(1, 1), b3 + hstep, voffB); PG8_STAGE(PG8_SA(1, 0), a3, voffA);
;             PG8_WAIT_V(8); PG8_WAIT_L(0); PG8_BAR; PG8_MMA(1, 0, At, B0); PG8_MMA(1, 1, At, B1); PG8_BAR; PG8_SCHED;
	s_add_i32 s3, s3, s34
	v_lshl_add_u64 v[214:215], v[214:215], 0, s[36:37]
	s_mov_b32 m0, s3
	ds_read_b128 v[176:179], v174 offset:49152
	ds_read_b128 v[180:183], v174 offset:50176
	ds_read_b128 v[184:187], v174 offset:51200
	ds_read_b128 v[188:191], v174 offset:52224
	ds_read_b128 v[192:195], v174 offset:53248
	ds_read_b128 v[196:199], v174 offset:54272
	ds_read_b128 v[200:203], v174 offset:55296
	ds_read_b128 v[204:207], v174 offset:56320
	global_load_lds_dwordx4 v[214:215], off
	s_add_i32 m0, s3, 0x2000
	s_add_u32 s28, s82, 0x40080
	v_lshl_add_u64 v[214:215], v[216:217], 0, s[36:37]
	s_addc_u32 s29, s83, 0
	s_add_i32 s3, s44, s34
	global_load_lds_dwordx4 v[214:215], off
	v_lshl_add_u64 v[214:215], s[28:29], 0, v[138:139]
	s_mov_b32 m0, s3
	s_nop 0
	global_load_lds_dwordx4 v[214:215], off
	v_lshl_add_u64 v[214:215], s[28:29], 0, v[142:143]
	s_add_i32 m0, s3, 0x2000
	s_nop 0
	global_load_lds_dwordx4 v[214:215], off
	v_lshl_add_u64 v[214:215], v[222:223], 0, s[36:37]
	s_mov_b32 m0, s59
	s_nop 0
	global_load_lds_dwordx4 v[214:215], off
	v_lshl_add_u64 v[214:215], v[224:225], 0, s[36:37]
	s_mov_b32 m0, s72
	s_nop 0
	global_load_lds_dwordx4 v[214:215], off
	s_waitcnt vmcnt(8)
	s_waitcnt lgkmcnt(0)
	s_barrier
	s_setprio 1
	s_waitcnt lgkmcnt(0)
	v_mfma_f32_16x16x32_bf16 v[60:63], v[128:131], v[176:179], v[60:63]
	v_mfma_f32_16x16x32_bf16 v[56:59], v[150:153], v[176:179], v[56:59]
	v_mfma_f32_16x16x32_bf16 v[44:47], v[128:131], v[184:187], v[44:47]
	v_mfma_f32_16x16x32_bf16 v[40:43], v[150:153], v[184:187], v[40:43]
	v_mfma_f32_16x16x32_bf16 v[28:31], v[128:131], v[192:195], v[28:31]
	v_mfma_f32_16x16x32_bf16 v[24:27], v[150:153], v[192:195], v[24:27]
	v_mfma_f32_16x16x32_bf16 v[12:15], v[128:131], v[200:203], v[12:15]
	v_mfma_f32_16x16x32_bf16 v[8:11], v[150:153], v[200:203], v[8:11]
	v_mfma_f32_16x16x32_bf16 v[60:63], v[132:135], v[180:183], v[60:63]
	v_mfma_f32_16x16x32_bf16 v[56:59], v[154:157], v[180:183], v[56:59]
	v_mfma_f32_16x16x32_bf16 v[44:47], v[132:135], v[188:191], v[44:47]
	v_mfma_f32_16x16x32_bf16 v[40:43], v[154:157], v[188:191], v[40:43]
	v_mfma_f32_16x16x32_bf16 v[28:31], v[132:135], v[196:199], v[28:31]
	v_mfma_f32_16x16x32_bf16 v[24:27], v[154:157], v[196:199], v[24:27]
	v_mfma_f32_16x16x32_bf16 v[12:15], v[132:135], v[204:207], v[12:15]
	v_mfma_f32_16x16x32_bf16 v[8:11], v[154:157], v[204:207], v[8:11]
	s_setprio 0
	s_setprio 1
	v_mfma_f32_16x16x32_bf16 v[52:55], v[158:161], v[176:179], v[52:55]
	v_mfma_f32_16x16x32_bf16 v[48:51], v[166:169], v[176:179], v[48:51]
	v_mfma_f32_16x16x32_bf16 v[36:39], v[158:161], v[184:187], v[36:39]
	v_mfma_f32_16x16x32_bf16 v[32:35], v[166:169], v[184:187], v[32:35]
	v_mfma_f32_16x16x32_bf16 v[20:23], v[158:161], v[192:195], v[20:23]
	v_mfma_f32_16x16x32_bf16 v[16:19], v[166:169], v[192:195], v[16:19]
	v_mfma_f32_16x16x32_bf16 v[4:7], v[158:161], v[200:203], v[4:7]
	v_mfma_f32_16x16x32_bf16 v[0:3], v[166:169], v[200:203], v[0:3]
	v_mfma_f32_16x16x32_bf16 v[52:55], v[162:165], v[180:183], v[52:55]
	v_mfma_f32_16x16x32_bf16 v[48:51], v[170:173], v[180:183], v[48:51]
	v_mfma_f32_16x16x32_bf16 v[36:39], v[162:165], v[188:191], v[36:39]
	v_mfma_f32_16x16x32_bf16 v[32:35], v[170:173], v[188:191], v[32:35]
	v_mfma_f32_16x16x32_bf16 v[20:23], v[162:165], v[196:199], v[20:23]
	v_mfma_f32_16x16x32_bf16 v[16:19], v[170:173], v[196:199], v[16:19]
	v_mfma_f32_16x16x32_bf16 v[4:7], v[162:165], v[204:207], v[4:7]
	v_mfma_f32_16x16x32_bf16 v[0:3], v[170:173], v[204:207], v[0:3]
	s_setprio 0
	s_add_i32 s84, s84, 2
	s_add_u32 s80, s80, 0x100
	s_addc_u32 s81, s81, 0
	s_add_u32 s67, s67, 0x100
	s_addc_u32 s69, s69, 0
	s_cmp_gt_u32 s84, 13
	s_barrier
	s_cbranch_scc0 .LBB0_481
	s_and_b64 vcc, exec, s[64:65]
	s_cbranch_vccz .LBB0_484
	s_barrier

; #define PG8_STAGE(bufoff, gbase, voff) do { _Pragma("unroll") for (int _i = 0; _i < 2; ++_i) \
;         __builtin_amdgcn_global_load_lds((const unsigned*)((const char*)(gbase) + (voff)[_i]), (PG8_LAS unsigned*)(lds + (bufoff) + ldsw + _i * 8192), 16, 0, 0); } while (0)
; #define PG8_LDA(dst, b, h) do { _Pragma("unroll") for (int m = 0; m < 4; ++m) _Pragma("unroll") for (int k = 0; k < 2; ++k) dst[m][k] = *(const PG8_LAS bf16x8*)(lds + PG8_SA(b, h) + aoff + m * 2048 + k * 1024); } while (0)
; #define PG8_LDB(dst, b, h) do { _Pragma("unroll") for (int n = 0; n < 2; ++n) _Pragma("unroll") for (int k = 0; k < 2; ++k) dst[n][k] = *(const PG8_LAS bf16x8*)(lds + PG8_SB(b, h) + boff + n * 2048 + k * 1024); } while (0)
; #define PG8_MMA(ai, bj, At, Bt) do { __builtin_amdgcn_s_setprio(1); _Pragma("unroll") for (int m = 0; m < 4; ++m) _Pragma("unroll") for (int n = 0; n < 2; ++n) _Pragma("unroll") for (int k = 0; k < 2; ++k) \
;         acc[ai][bj][m][n] = __builtin_amdgcn_mfma_f32_16x16x32_bf16(Bt[n][k], At[m][k], acc[ai][bj][m][n], 0, 0, 0); __builtin_amdgcn_s_setprio(0); } while (0)
; #define PG8_WAIT_V(n) asm volatile("s_waitcnt vmcnt(" #n ")" ::: "memory")
; #define PG8_WAIT_L(n) asm volatile("s_waitcnt lgkmcnt(" #n ")" ::: "memory")
; template <class Epi, class Sched, bool ALIGN_EPI = false, bool SP2 = false>
; __device__ __forceinline__ void gemm_phase(PG8_LAS unsigned char* lds, const Gemm g, const Sched& S, const Epi& E) {
;     ...
;             const bool last = (t == nt - 2);
;             const char* a1 = cA + (size_t)(t + 1) * kstep;
;             const char* a2 = last ? nA : cA + (size_t)(t + 2) * kstep; const char* b2 = last ? nB : cB + (size_t)(t + 2) * kstep;
;             const char* a3 = a2 + kstep; const char* b3 = b2 + kstep;
;             if (last && has_next) S.a_ready(nxt);
;             if constexpr (SP2) {
;             PG8_LDB(B0, 0, 0); PG8_LDB(B1, 0, 1); PG8_SCHED; PG8_LDA(At, 0, 0); PG8_STAGE(PG8_SA(1, 1), a1 + hstep, voffA);
;             PG8_WAIT_V(8); PG8_WAIT_L(0); PG8_BAR; PG8_MMA(0, 0, At, B0); PG8_MMA(0, 1, At, B1); PG8_BAR; PG8_SCHED;
;             PG8_LDA(At, 0, 1); PG8_STAGE(PG8_SB(0, 0), b2, voffB); PG8_STAGE(PG8_SB(0, 1), b2 + hstep, voffB); PG8_STAGE(PG8_SA(0, 0), a2, voffA);
;             PG8_WAIT_V(8); PG8_WAIT_L(0); PG8_BAR; PG8_MMA(1, 0, At, B0); PG8_MMA(1, 1, At, B1); PG8_BAR; PG8_SCHED;
.LBB0_541:
	s_add_i32 s72, s45, 2
	s_add_u32 s3, s40, 0x80
	s_addc_u32 s28, s41, 0
	s_add_i32 s44, 0, 0x10000
	s_cmp_eq_u32 s34, s45
	s_cselect_b32 s47, s1, s28
	s_cselect_b32 s46, s0, s3
	s_cselect_b32 s29, s79, s43
	s_cselect_b32 s28, s78, s30
	s_add_i32 s3, 0, 0x14000
	v_add_u32_e32 v140, s44, v251
	v_add_u32_e32 v156, s3, v251
	ds_read_b128 v[128:131], v140
	ds_read_b128 v[132:135], v140 offset:1024
	ds_read_b128 v[136:139], v140 offset:2048
	ds_read_b128 v[140:143], v140 offset:3072
	ds_read_b128 v[144:147], v156
	ds_read_b128 v[148:151], v156 offset:1024
	ds_read_b128 v[152:155], v156 offset:2048
	ds_read_b128 v[156:159], v156 offset:3072
	v_lshl_add_u64 v[192:193], s[40:41], 0, v[228:229]
	s_add_i32 m0, s75, 0xc000
	ds_read_b128 v[160:163], v214
	ds_read_b128 v[164:167], v214 offset:1024
	ds_read_b128 v[168:171], v214 offset:2048
	ds_read_b128 v[172:175], v214 offset:3072
	ds_read_b128 v[176:179], v214 offset:4096
	ds_read_b128 v[180:183], v214 offset:5120
	ds_read_b128 v[184:187], v214 offset:6144
	ds_read_b128 v[188:191], v214 offset:7168
	global_load_lds_dwordx4 v[192:193], off
	v_lshl_add_u64 v[192:193], s[40:41], 0, v[230:231]
	s_add_i32 m0, s75, 0xe000
	s_nop 0
	global_load_lds_dwordx4 v[192:193], off
	s_waitcnt vmcnt(8)
	s_waitcnt lgkmcnt(0)
	s_barrier
	s_setprio 1
	s_waitcnt lgkmcnt(0)
	v_mfma_f32_16x16x32_bf16 v[124:127], v[128:131], v[160:163], v[124:127]
	v_mfma_f32_16x16x32_bf16 v[120:123], v[136:139], v[160:163], v[120:123]
	v_mfma_f32_16x16x32_bf16 v[116:119], v[128:131], v[168:171], v[116:119]
	v_mfma_f32_16x16x32_bf16 v[112:115], v[136:139], v[168:171], v[112:115]
	v_mfma_f32_16x16x32_bf16 v[108:111], v[128:131], v[176:179], v[108:111]
	v_mfma_f32_16x16x32_bf16 v[104:107], v[136:139], v[176:179], v[104:107]
	v_mfma_f32_16x16x32_bf16 v[100:103], v[128:131], v[184:187], v[100:103]
	v_mfma_f32_16x16x32_bf16 v[96:99], v[136:139], v[184:187], v[96:99]
	v_mfma_f32_16x16x32_bf16 v[124:127], v[132:135], v[164:167], v[124:127]
	v_mfma_f32_16x16x32_bf16 v[120:123], v[140:143], v[164:167], v[120:123]
	v_mfma_f32_16x16x32_bf16 v[116:119], v[132:135], v[172:175], v[116:119]
	v_mfma_f32_16x16x32_bf16 v[112:115], v[140:143], v[172:175], v[112:115]
	v_mfma_f32_16x16x32_bf16 v[108:111], v[132:135], v[180:183], v[108:111]
	v_mfma_f32_16x16x32_bf16 v[104:107], v[140:143], v[180:183], v[104:107]
	v_mfma_f32_16x16x32_bf16 v[100:103], v[132:135], v[188:191], v[100:103]
	v_mfma_f32_16x16x32_bf16 v[96:99], v[140:143], v[188:191], v[96:99]
	s_setprio 0
	s_setprio 1
	v_mfma_f32_16x16x32_bf16 v[92:95], v[144:147], v[160:163], v[92:95]
	v_mfma_f32_16x16x32_bf16 v[88:91], v[152:155], v[160:163], v[88:91]
	v_mfma_f32_16x16x32_bf16 v[84:87], v[144:147], v[168:171], v[84:87]
	v_mfma_f32_16x16x32_bf16 v[80:83], v[152:155], v[168:171], v[80:83]
	v_mfma_f32_16x16x32_bf16 v[76:79], v[144:147], v[176:179], v[76:79]
	v_mfma_f32_16x16x32_bf16 v[72:75], v[152:155], v[176:179], v[72:75]
	v_mfma_f32_16x16x32_bf16 v[68:71], v[144:147], v[184:187], v[68:71]
	v_mfma_f32_16x16x32_bf16 v[64:67], v[152:155], v[184:187], v[64:67]
	v_mfma_f32_16x16x32_bf16 v[92:95], v[148:151], v[164:167], v[92:95]
	v_mfma_f32_16x16x32_bf16 v[88:91], v[156:159], v[164:167], v[88:91]
	v_mfma_f32_16x16x32_bf16 v[84:87], v[148:151], v[172:175], v[84:87]
	v_mfma_f32_16x16x32_bf16 v[80:83], v[156:159], v[172:175], v[80:83]
	v_mfma_f32_16x16x32_bf16 v[76:79], v[148:151], v[180:183], v[76:79]
	v_mfma_f32_16x16x32_bf16 v[72:75], v[156:159], v[180:183], v[72:75]
	v_mfma_f32_16x16x32_bf16 v[68:71], v[148:151], v[188:191], v[68:71]
	v_mfma_f32_16x16x32_bf16 v[64:67], v[156:159], v[188:191], v[64:67]
	s_setprio 0
	s_barrier
	s_add_i32 s44, s44, s63
	v_lshl_add_u64 v[192:193], s[28:29], 0, v[208:209]
	s_mov_b32 m0, s44
	ds_read_b128 v[160:163], v214 offset:16384
	ds_read_b128 v[164:167], v214 offset:17408
	ds_read_b128 v[168:171], v214 offset:18432
	ds_read_b128 v[172:175], v214 offset:19456
	ds_read_b128 v[176:179], v214 offset:20480
	ds_read_b128 v[180:183], v214 offset:21504
	ds_read_b128 v[184:187], v214 offset:22528
	ds_read_b128 v[188:191], v214 offset:23552
	global_load_lds_dwordx4 v[192:193], off
	s_add_i32 m0, s44, 0x2000
	v_lshl_add_u64 v[194:195], s[28:29], 0, v[226:227]
	s_add_u32 s28, s28, s66
	s_addc_u32 s29, s29, 0
	s_add_i32 s3, s3, s63
	global_load_lds_dwordx4 v[194:195], off
	v_lshl_add_u64 v[196:197], s[28:29], 0, v[208:209]
	s_mov_b32 m0, s3
	v_lshl_add_u64 v[198:199], s[28:29], 0, v[226:227]
	global_load_lds_dwordx4 v[196:197], off
	s_add_i32 m0, s3, 0x2000
	v_lshl_add_u64 v[200:201], s[46:47], 0, v[222:223]
	global_load_lds_dwordx4 v[198:199], off
	s_mov_b32 m0, s75
	v_lshl_add_u64 v[202:203], s[46:47], 0, v[224:225]
	global_load_lds_dwordx4 v[200:201], off
	s_mov_b32 m0, s50
	s_nop 0
	global_load_lds_dwordx4 v[202:203], off
	s_waitcnt vmcnt(8)
	s_waitcnt lgkmcnt(0)
	s_barrier
; #define PG8_STAGE(bufoff, gbase, voff) do { _Pragma("unroll") for (int _i = 0; _i < 2; ++_i) \
;         __builtin_amdgcn_global_load_lds((const unsigned*)((const char*)(gbase) + (voff)[_i]), (PG8_LAS unsigned*)(lds + (bufoff) + ldsw + _i * 8192), 16, 0, 0); } while (0)
; #define PG8_LDA(dst, b, h) do { _Pragma("unroll") for (int m = 0; m < 4; ++m) _Pragma("unroll") for (int k = 0; k < 2; ++k) dst[m][k] = *(const PG8_LAS bf16x8*)(lds + PG8_SA(b, h) + aoff + m * 2048 + k * 1024); } while (0)
; #define PG8_LDB(dst, b, h) do { _Pragma("unroll") for (int n = 0; n < 2; ++n) _Pragma("unroll") for (int k = 0; k < 2; ++k) dst[n][k] = *(const PG8_LAS bf16x8*)(lds + PG8_SB(b, h) + boff + n * 2048 + k * 1024); } while (0)
; #define PG8_MMA(ai, bj, At, Bt) do { __builtin_amdgcn_s_setprio(1); _Pragma("unroll") for (int m = 0; m < 4; ++m) _Pragma("unroll") for (int n = 0; n < 2; ++n) _Pragma("unroll") for (int k = 0; k < 2; ++k) \
;         acc[ai][bj][m][n] = __builtin_amdgcn_mfma_f32_16x16x32_bf16(Bt[n][k], At[m][k], acc[ai][bj][m][n], 0, 0, 0); __builtin_amdgcn_s_setprio(0); } while (0)
; #define PG8_WAIT_V(n) asm volatile("s_waitcnt vmcnt(" #n ")" ::: "memory")
; #define PG8_WAIT_L(n) asm volatile("s_waitcnt lgkmcnt(" #n ")" ::: "memory")
; #define PG8_BAR __builtin_amdgcn_s_barrier()
; #define PG8_SCHED __builtin_amdgcn_sched_barrier(0)
; template <class Epi, class Sched, bool ALIGN_EPI = false, bool SP2 = false>
; __device__ __forceinline__ void gemm_phase(PG8_LAS unsigned char* lds, const Gemm g, const Sched& S, const Epi& E) {
;     ...
;             PG8_WAIT_V(8); PG8_WAIT_L(0); PG8_BAR; PG8_MMA(1, 0, At, B0); PG8_MMA(1, 1, At, B1); PG8_BAR; PG8_SCHED;
;             PG8_LDB(B0, 1, 0); PG8_LDB(B1, 1, 1); PG8_SCHED; PG8_LDA(At, 1, 0); PG8_STAGE(PG8_SA(0, 1), a2 + hstep, voffA);
;             PG8_WAIT_V(8); PG8_WAIT_L(0); PG8_BAR; PG8_MMA(0, 0, At, B0); PG8_MMA(0, 1, At, B1); PG8_BAR; PG8_SCHED;
	s_setprio 1
	s_waitcnt lgkmcnt(0)
	v_mfma_f32_16x16x32_bf16 v[60:63], v[128:131], v[160:163], v[60:63]
	v_mfma_f32_16x16x32_bf16 v[56:59], v[136:139], v[160:163], v[56:59]
	v_mfma_f32_16x16x32_bf16 v[52:55], v[128:131], v[168:171], v[52:55]
	v_mfma_f32_16x16x32_bf16 v[48:51], v[136:139], v[168:171], v[48:51]
	v_mfma_f32_16x16x32_bf16 v[44:47], v[128:131], v[176:179], v[44:47]
	v_mfma_f32_16x16x32_bf16 v[40:43], v[136:139], v[176:179], v[40:43]
	v_mfma_f32_16x16x32_bf16 v[36:39], v[128:131], v[184:187], v[36:39]
	v_mfma_f32_16x16x32_bf16 v[32:35], v[136:139], v[184:187], v[32:35]
	v_mfma_f32_16x16x32_bf16 v[60:63], v[132:135], v[164:167], v[60:63]
	v_mfma_f32_16x16x32_bf16 v[56:59], v[140:143], v[164:167], v[56:59]
	v_mfma_f32_16x16x32_bf16 v[52:55], v[132:135], v[172:175], v[52:55]
	v_mfma_f32_16x16x32_bf16 v[48:51], v[140:143], v[172:175], v[48:51]
	v_mfma_f32_16x16x32_bf16 v[44:47], v[132:135], v[180:183], v[44:47]
	v_mfma_f32_16x16x32_bf16 v[40:43], v[140:143], v[180:183], v[40:43]
	v_mfma_f32_16x16x32_bf16 v[36:39], v[132:135], v[188:191], v[36:39]
	v_mfma_f32_16x16x32_bf16 v[32:35], v[140:143], v[188:191], v[32:35]
	s_setprio 0
	s_setprio 1
	v_mfma_f32_16x16x32_bf16 v[28:31], v[144:147], v[160:163], v[28:31]
	v_mfma_f32_16x16x32_bf16 v[24:27], v[152:155], v[160:163], v[24:27]
	v_mfma_f32_16x16x32_bf16 v[20:23], v[144:147], v[168:171], v[20:23]
	v_mfma_f32_16x16x32_bf16 v[16:19], v[152:155], v[168:171], v[16:19]
	v_mfma_f32_16x16x32_bf16 v[12:15], v[144:147], v[176:179], v[12:15]
	v_mfma_f32_16x16x32_bf16 v[8:11], v[152:155], v[176:179], v[8:11]
	v_mfma_f32_16x16x32_bf16 v[4:7], v[144:147], v[184:187], v[4:7]
	v_mfma_f32_16x16x32_bf16 v[0:3], v[152:155], v[184:187], v[0:3]
	v_mfma_f32_16x16x32_bf16 v[28:31], v[148:151], v[164:167], v[28:31]
	v_mfma_f32_16x16x32_bf16 v[24:27], v[156:159], v[164:167], v[24:27]
	v_mfma_f32_16x16x32_bf16 v[20:23], v[148:151], v[172:175], v[20:23]
	v_mfma_f32_16x16x32_bf16 v[16:19], v[156:159], v[172:175], v[16:19]
	v_mfma_f32_16x16x32_bf16 v[12:15], v[148:151], v[180:183], v[12:15]
	v_mfma_f32_16x16x32_bf16 v[8:11], v[156:159], v[180:183], v[8:11]
	v_mfma_f32_16x16x32_bf16 v[4:7], v[148:151], v[188:191], v[4:7]
	v_mfma_f32_16x16x32_bf16 v[0:3], v[156:159], v[188:191], v[0:3]
	s_setprio 0
	s_barrier
	s_add_i32 s3, 0, 0x18000
	s_add_i32 s44, 0, 0x1c000
	v_add_u32_e32 v140, s3, v251
	v_add_u32_e32 v156, s44, v251
	ds_read_b128 v[128:131], v140
	ds_read_b128 v[132:135], v140 offset:1024
	ds_read_b128 v[136:139], v140 offset:2048
	ds_read_b128 v[140:143], v140 offset:3072
	ds_read_b128 v[144:147], v156
	ds_read_b128 v[148:151], v156 offset:1024
	ds_read_b128 v[152:155], v156 offset:2048
	ds_read_b128 v[156:159], v156 offset:3072
	s_add_u32 s28, s46, s66
	s_addc_u32 s29, s47, 0
	s_mov_b32 m0, s68
	v_lshl_add_u64 v[204:205], s[28:29], 0, v[222:223]
	ds_read_b128 v[160:163], v214 offset:32768
	ds_read_b128 v[164:167], v214 offset:33792
	ds_read_b128 v[168:171], v214 offset:34816
	ds_read_b128 v[172:175], v214 offset:35840
	ds_read_b128 v[176:179], v214 offset:36864
	ds_read_b128 v[180:183], v214 offset:37888
	ds_read_b128 v[184:187], v214 offset:38912
	ds_read_b128 v[188:191], v214 offset:39936
	global_load_lds_dwordx4 v[204:205], off
	v_lshl_add_u64 v[204:205], s[28:29], 0, v[224:225]
	s_mov_b32 m0, s69
	s_nop 0
	global_load_lds_dwordx4 v[204:205], off
	s_waitcnt vmcnt(8)
	s_waitcnt lgkmcnt(0)
	s_barrier
	s_setprio 1
	s_waitcnt lgkmcnt(0)
	v_mfma_f32_16x16x32_bf16 v[124:127], v[128:131], v[160:163], v[124:127]
	v_mfma_f32_16x16x32_bf16 v[120:123], v[136:139], v[160:163], v[120:123]
	v_mfma_f32_16x16x32_bf16 v[116:119], v[128:131], v[168:171], v[116:119]
	v_mfma_f32_16x16x32_bf16 v[112:115], v[136:139], v[168:171], v[112:115]
	v_mfma_f32_16x16x32_bf16 v[108:111], v[128:131], v[176:179], v[108:111]
	v_mfma_f32_16x16x32_bf16 v[104:107], v[136:139], v[176:179], v[104:107]
	v_mfma_f32_16x16x32_bf16 v[100:103], v[128:131], v[184:187], v[100:103]
	v_mfma_f32_16x16x32_bf16 v[96:99], v[136:139], v[184:187], v[96:99]
	v_mfma_f32_16x16x32_bf16 v[124:127], v[132:135], v[164:167], v[124:127]
	v_mfma_f32_16x16x32_bf16 v[120:123], v[140:143], v[164:167], v[120:123]
	v_mfma_f32_16x16x32_bf16 v[116:119], v[132:135], v[172:175], v[116:119]
	v_mfma_f32_16x16x32_bf16 v[112:115], v[140:143], v[172:175], v[112:115]
	v_mfma_f32_16x16x32_bf16 v[108:111], v[132:135], v[180:183], v[108:111]
	v_mfma_f32_16x16x32_bf16 v[104:107], v[140:143], v[180:183], v[104:107]
	v_mfma_f32_16x16x32_bf16 v[100:103], v[132:135], v[188:191], v[100:103]
	v_mfma_f32_16x16x32_bf16 v[96:99], v[140:143], v[188:191], v[96:99]
	s_setprio 0
	s_setprio 1
	v_mfma_f32_16x16x32_bf16 v[92:95], v[144:147], v[160:163], v[92:95]
	v_mfma_f32_16x16x32_bf16 v[88:91], v[152:155], v[160:163], v[88:91]
	v_mfma_f32_16x16x32_bf16 v[84:87], v[144:147], v[168:171], v[84:87]
	v_mfma_f32_16x16x32_bf16 v[80:83], v[152:155], v[168:171], v[80:83]
	v_mfma_f32_16x16x32_bf16 v[76:79], v[144:147], v[176:179], v[76:79]
	v_mfma_f32_16x16x32_bf16 v[72:75], v[152:155], v[176:179], v[72:75]
	v_mfma_f32_16x16x32_bf16 v[68:71], v[144:147], v[184:187], v[68:71]
	v_mfma_f32_16x16x32_bf16 v[64:67], v[152:155], v[184:187], v[64:67]
	v_mfma_f32_16x16x32_bf16 v[92:95], v[148:151], v[164:167], v[92:95]
	v_mfma_f32_16x16x32_bf16 v[88:91], v[156:159], v[164:167], v[88:91]
	v_mfma_f32_16x16x32_bf16 v[84:87], v[148:151], v[172:175], v[84:87]
	v_mfma_f32_16x16x32_bf16 v[80:83], v[156:159], v[172:175], v[80:83]
	v_mfma_f32_16x16x32_bf16 v[76:79], v[148:151], v[180:183], v[76:79]
	v_mfma_f32_16x16x32_bf16 v[72:75], v[156:159], v[180:183], v[72:75]
	v_mfma_f32_16x16x32_bf16 v[68:71], v[148:151], v[188:191], v[68:71]
	v_mfma_f32_16x16x32_bf16 v[64:67], v[156:159], v[188:191], v[64:67]
	s_setprio 0
	s_barrier
; #define PG8_STAGE(bufoff, gbase, voff) do { _Pragma("unroll") for (int _i = 0; _i < 2; ++_i) \
;         __builtin_amdgcn_global_load_lds((const unsigned*)((const char*)(gbase) + (voff)[_i]), (PG8_LAS unsigned*)(lds + (bufoff) + ldsw + _i * 8192), 16, 0, 0); } while (0)
; #define PG8_LDA(dst, b, h) do { _Pragma("unroll") for (int m = 0; m < 4; ++m) _Pragma("unroll") for (int k = 0; k < 2; ++k) dst[m][k] = *(const PG8_LAS bf16x8*)(lds + PG8_SA(b, h) + aoff + m * 2048 + k * 1024); } while (0)
; #define PG8_MMA(ai, bj, At, Bt) do { __builtin_amdgcn_s_setprio(1); _Pragma("unroll") for (int m = 0; m < 4; ++m) _Pragma("unroll") for (int n = 0; n < 2; ++n) _Pragma("unroll") for (int k = 0; k < 2; ++k) \
;         acc[ai][bj][m][n] = __builtin_amdgcn_mfma_f32_16x16x32_bf16(Bt[n][k], At[m][k], acc[ai][bj][m][n], 0, 0, 0); __builtin_amdgcn_s_setprio(0); } while (0)
; #define PG8_WAIT_V(n) asm volatile("s_waitcnt vmcnt(" #n ")" ::: "memory")
; #define PG8_WAIT_L(n) asm volatile("s_waitcnt lgkmcnt(" #n ")" ::: "memory")
; #define PG8_BAR __builtin_amdgcn_s_barrier()
; #define PG8_SCHED __builtin_amdgcn_sched_barrier(0)
; template <class Epi, class Sched, bool ALIGN_EPI = false, bool SP2 = false>
; __device__ __forceinline__ void gemm_phase(PG8_LAS unsigned char* lds, const Gemm g, const Sched& S, const Epi& E) {
;     ...
;         for (int t = 0; t < nt; t += 2) {
;     ...
;             PG8_LDA(At, 1, 1); PG8_STAGE(PG8_SB(1, 0), b3, voffB); PG8_STAGE(PG8_SB(1, 1), b3 + hstep, voffB); PG8_STAGE(PG8_SA(1, 0), a3, voffA);
;             PG8_WAIT_V(8); PG8_WAIT_L(0); PG8_BAR; PG8_MMA(1, 0, At, B0); PG8_MMA(1, 1, At, B1); PG8_BAR; PG8_SCHED;
	s_add_i32 s3, s3, s63
	v_lshl_add_u64 v[192:193], v[192:193], 0, s[36:37]
	s_mov_b32 m0, s3
	ds_read_b128 v[160:163], v214 offset:49152
	ds_read_b128 v[164:167], v214 offset:50176
	ds_read_b128 v[168:171], v214 offset:51200
	ds_read_b128 v[172:175], v214 offset:52224
	ds_read_b128 v[176:179], v214 offset:53248
	ds_read_b128 v[180:183], v214 offset:54272
	ds_read_b128 v[184:187], v214 offset:55296
	ds_read_b128 v[188:191], v214 offset:56320
	global_load_lds_dwordx4 v[192:193], off
	v_lshl_add_u64 v[192:193], v[194:195], 0, s[36:37]
	s_add_i32 m0, s3, 0x2000
	s_add_i32 s3, s44, s63
	global_load_lds_dwordx4 v[192:193], off
	v_lshl_add_u64 v[192:193], v[196:197], 0, s[36:37]
	s_mov_b32 m0, s3
	s_nop 0
	global_load_lds_dwordx4 v[192:193], off
	v_lshl_add_u64 v[192:193], v[198:199], 0, s[36:37]
	s_add_i32 m0, s3, 0x2000
	s_nop 0
	global_load_lds_dwordx4 v[192:193], off
	v_lshl_add_u64 v[192:193], v[200:201], 0, s[36:37]
	s_mov_b32 m0, s27
	s_nop 0
	global_load_lds_dwordx4 v[192:193], off
	v_lshl_add_u64 v[192:193], v[202:203], 0, s[36:37]
	s_mov_b32 m0, s92
	s_nop 0
	global_load_lds_dwordx4 v[192:193], off
	s_waitcnt vmcnt(8)
	s_waitcnt lgkmcnt(0)
	s_barrier
	s_setprio 1
	s_waitcnt lgkmcnt(0)
	v_mfma_f32_16x16x32_bf16 v[60:63], v[128:131], v[160:163], v[60:63]
	v_mfma_f32_16x16x32_bf16 v[56:59], v[136:139], v[160:163], v[56:59]
	v_mfma_f32_16x16x32_bf16 v[52:55], v[128:131], v[168:171], v[52:55]
	v_mfma_f32_16x16x32_bf16 v[48:51], v[136:139], v[168:171], v[48:51]
	v_mfma_f32_16x16x32_bf16 v[44:47], v[128:131], v[176:179], v[44:47]
	v_mfma_f32_16x16x32_bf16 v[40:43], v[136:139], v[176:179], v[40:43]
	v_mfma_f32_16x16x32_bf16 v[36:39], v[128:131], v[184:187], v[36:39]
	v_mfma_f32_16x16x32_bf16 v[32:35], v[136:139], v[184:187], v[32:35]
	v_mfma_f32_16x16x32_bf16 v[60:63], v[132:135], v[164:167], v[60:63]
	v_mfma_f32_16x16x32_bf16 v[56:59], v[140:143], v[164:167], v[56:59]
	v_mfma_f32_16x16x32_bf16 v[52:55], v[132:135], v[172:175], v[52:55]
	v_mfma_f32_16x16x32_bf16 v[48:51], v[140:143], v[172:175], v[48:51]
	v_mfma_f32_16x16x32_bf16 v[44:47], v[132:135], v[180:183], v[44:47]
	v_mfma_f32_16x16x32_bf16 v[40:43], v[140:143], v[180:183], v[40:43]
	v_mfma_f32_16x16x32_bf16 v[36:39], v[132:135], v[188:191], v[36:39]
	v_mfma_f32_16x16x32_bf16 v[32:35], v[140:143], v[188:191], v[32:35]
	s_setprio 0
	s_setprio 1
	v_mfma_f32_16x16x32_bf16 v[28:31], v[144:147], v[160:163], v[28:31]
	v_mfma_f32_16x16x32_bf16 v[24:27], v[152:155], v[160:163], v[24:27]
	v_mfma_f32_16x16x32_bf16 v[20:23], v[144:147], v[168:171], v[20:23]
	v_mfma_f32_16x16x32_bf16 v[16:19], v[152:155], v[168:171], v[16:19]
	v_mfma_f32_16x16x32_bf16 v[12:15], v[144:147], v[176:179], v[12:15]
	v_mfma_f32_16x16x32_bf16 v[8:11], v[152:155], v[176:179], v[8:11]
	v_mfma_f32_16x16x32_bf16 v[4:7], v[144:147], v[184:187], v[4:7]
	v_mfma_f32_16x16x32_bf16 v[0:3], v[152:155], v[184:187], v[0:3]
	v_mfma_f32_16x16x32_bf16 v[28:31], v[148:151], v[164:167], v[28:31]
	v_mfma_f32_16x16x32_bf16 v[24:27], v[156:159], v[164:167], v[24:27]
	v_mfma_f32_16x16x32_bf16 v[20:23], v[148:151], v[172:175], v[20:23]
	v_mfma_f32_16x16x32_bf16 v[16:19], v[156:159], v[172:175], v[16:19]
	v_mfma_f32_16x16x32_bf16 v[12:15], v[148:151], v[180:183], v[12:15]
	v_mfma_f32_16x16x32_bf16 v[8:11], v[156:159], v[180:183], v[8:11]
	v_mfma_f32_16x16x32_bf16 v[4:7], v[148:151], v[188:191], v[4:7]
	v_mfma_f32_16x16x32_bf16 v[0:3], v[156:159], v[188:191], v[0:3]
	s_setprio 0
	s_add_u32 s40, s40, 0x100
	s_addc_u32 s41, s41, 0
	s_add_u32 s30, s30, 0x100
	s_addc_u32 s43, s43, 0
	s_cmp_ge_u32 s72, s35
	s_mov_b32 s45, s72
	s_barrier
	s_cbranch_scc0 .LBB0_541
	s_and_b64 vcc, exec, s[76:77]
	s_cbranch_vccz .LBB0_544
	s_barrier

; #define PG8_STAGE(bufoff, gbase, voff) do { _Pragma("unroll") for (int _i = 0; _i < 2; ++_i) \
;         __builtin_amdgcn_global_load_lds((const unsigned*)((const char*)(gbase) + (voff)[_i]), (PG8_LAS unsigned*)(lds + (bufoff) + ldsw + _i * 8192), 16, 0, 0); } while (0)
; #define PG8_LDA(dst, b, h) do { _Pragma("unroll") for (int m = 0; m < 4; ++m) _Pragma("unroll") for (int k = 0; k < 2; ++k) dst[m][k] = *(const PG8_LAS bf16x8*)(lds + PG8_SA(b, h) + aoff + m * 2048 + k * 1024); } while (0)
; #define PG8_LDB(dst, b, h) do { _Pragma("unroll") for (int n = 0; n < 2; ++n) _Pragma("unroll") for (int k = 0; k < 2; ++k) dst[n][k] = *(const PG8_LAS bf16x8*)(lds + PG8_SB(b, h) + boff + n * 2048 + k * 1024); } while (0)
; #define PG8_MMA(ai, bj, At, Bt) do { __builtin_amdgcn_s_setprio(1); _Pragma("unroll") for (int m = 0; m < 4; ++m) _Pragma("unroll") for (int n = 0; n < 2; ++n) _Pragma("unroll") for (int k = 0; k < 2; ++k) \
;         acc[ai][bj][m][n] = __builtin_amdgcn_mfma_f32_16x16x32_bf16(Bt[n][k], At[m][k], acc[ai][bj][m][n], 0, 0, 0); __builtin_amdgcn_s_setprio(0); } while (0)
; #define PG8_WAIT_V(n) asm volatile("s_waitcnt vmcnt(" #n ")" ::: "memory")
; #define PG8_WAIT_L(n) asm volatile("s_waitcnt lgkmcnt(" #n ")" ::: "memory")
; template <class Epi, class Sched, bool ALIGN_EPI = false, bool SP2 = false>
; __device__ __forceinline__ void gemm_phase(PG8_LAS unsigned char* lds, const Gemm g, const Sched& S, const Epi& E) {
;     ...
;             const bool last = (t == nt - 2);
;             const char* a1 = cA + (size_t)(t + 1) * kstep;
;             const char* a2 = last ? nA : cA + (size_t)(t + 2) * kstep; const char* b2 = last ? nB : cB + (size_t)(t + 2) * kstep;
;             const char* a3 = a2 + kstep; const char* b3 = b2 + kstep;
;             if (last && has_next) S.a_ready(nxt);
;             if constexpr (SP2) {
;             PG8_LDB(B0, 0, 0); PG8_LDB(B1, 0, 1); PG8_SCHED; PG8_LDA(At, 0, 0); PG8_STAGE(PG8_SA(1, 1), a1 + hstep, voffA);
;             PG8_WAIT_V(8); PG8_WAIT_L(0); PG8_BAR; PG8_MMA(0, 0, At, B0); PG8_MMA(0, 1, At, B1); PG8_BAR; PG8_SCHED;
;             PG8_LDA(At, 0, 1); PG8_STAGE(PG8_SB(0, 0), b2, voffB); PG8_STAGE(PG8_SB(0, 1), b2 + hstep, voffB); PG8_STAGE(PG8_SA(0, 0), a2, voffA);
;             PG8_WAIT_V(8); PG8_WAIT_L(0); PG8_BAR; PG8_MMA(1, 0, At, B0); PG8_MMA(1, 1, At, B1); PG8_BAR; PG8_SCHED;
.LBB0_621:
	s_add_i32 s91, s46, 2
	s_add_u32 s66, s64, 0x100
	s_addc_u32 s67, s65, 0
	s_add_i32 s3, 0, 0x10000
	s_cmp_eq_u32 s92, s46
	s_cselect_b32 s47, s55, s67
	s_cselect_b32 s46, s54, s66
	s_cselect_b32 s69, s63, vcc_hi
	s_cselect_b32 s68, s62, vcc_lo
	s_add_i32 s44, 0, 0x14000
	v_add_u32_e32 v154, s3, v140
	v_add_u32_e32 v170, s44, v140
	ds_read_b128 v[142:145], v154
	ds_read_b128 v[146:149], v154 offset:1024
	ds_read_b128 v[150:153], v154 offset:2048
	ds_read_b128 v[154:157], v154 offset:3072
	ds_read_b128 v[158:161], v170
	ds_read_b128 v[162:165], v170 offset:1024
	ds_read_b128 v[166:169], v170 offset:2048
	ds_read_b128 v[170:173], v170 offset:3072
	v_lshl_add_u64 v[206:207], s[64:65], 0, v[136:137]
	s_add_i32 m0, s75, 0xc000
	ds_read_b128 v[174:177], v141
	ds_read_b128 v[178:181], v141 offset:1024
	ds_read_b128 v[182:185], v141 offset:2048
	ds_read_b128 v[186:189], v141 offset:3072
	ds_read_b128 v[190:193], v141 offset:4096
	ds_read_b128 v[194:197], v141 offset:5120
	ds_read_b128 v[198:201], v141 offset:6144
	ds_read_b128 v[202:205], v141 offset:7168
	global_load_lds_dwordx4 v[206:207], off
	v_lshl_add_u64 v[206:207], s[64:65], 0, v[138:139]
	s_add_i32 m0, s75, 0xe000
	s_nop 0
	global_load_lds_dwordx4 v[206:207], off
	s_waitcnt vmcnt(8)
	s_waitcnt lgkmcnt(0)
	s_barrier
	s_setprio 1
	s_waitcnt lgkmcnt(0)
	v_mfma_f32_16x16x32_bf16 v[124:127], v[142:145], v[174:177], v[124:127]
	v_mfma_f32_16x16x32_bf16 v[120:123], v[150:153], v[174:177], v[120:123]
	v_mfma_f32_16x16x32_bf16 v[116:119], v[142:145], v[182:185], v[116:119]
	v_mfma_f32_16x16x32_bf16 v[112:115], v[150:153], v[182:185], v[112:115]
	v_mfma_f32_16x16x32_bf16 v[108:111], v[142:145], v[190:193], v[108:111]
	v_mfma_f32_16x16x32_bf16 v[100:103], v[150:153], v[190:193], v[100:103]
	v_mfma_f32_16x16x32_bf16 v[92:95], v[142:145], v[198:201], v[92:95]
	v_mfma_f32_16x16x32_bf16 v[84:87], v[150:153], v[198:201], v[84:87]
	v_mfma_f32_16x16x32_bf16 v[124:127], v[146:149], v[178:181], v[124:127]
	v_mfma_f32_16x16x32_bf16 v[120:123], v[154:157], v[178:181], v[120:123]
	v_mfma_f32_16x16x32_bf16 v[116:119], v[146:149], v[186:189], v[116:119]
	v_mfma_f32_16x16x32_bf16 v[112:115], v[154:157], v[186:189], v[112:115]
	v_mfma_f32_16x16x32_bf16 v[108:111], v[146:149], v[194:197], v[108:111]
	v_mfma_f32_16x16x32_bf16 v[100:103], v[154:157], v[194:197], v[100:103]
	v_mfma_f32_16x16x32_bf16 v[92:95], v[146:149], v[202:205], v[92:95]
	v_mfma_f32_16x16x32_bf16 v[84:87], v[154:157], v[202:205], v[84:87]
	s_setprio 0
	s_setprio 1
	v_mfma_f32_16x16x32_bf16 v[104:107], v[158:161], v[174:177], v[104:107]
	v_mfma_f32_16x16x32_bf16 v[96:99], v[166:169], v[174:177], v[96:99]
	v_mfma_f32_16x16x32_bf16 v[88:91], v[158:161], v[182:185], v[88:91]
	v_mfma_f32_16x16x32_bf16 v[80:83], v[166:169], v[182:185], v[80:83]
	v_mfma_f32_16x16x32_bf16 v[76:79], v[158:161], v[190:193], v[76:79]
	v_mfma_f32_16x16x32_bf16 v[72:75], v[166:169], v[190:193], v[72:75]
	v_mfma_f32_16x16x32_bf16 v[68:71], v[158:161], v[198:201], v[68:71]
	v_mfma_f32_16x16x32_bf16 v[64:67], v[166:169], v[198:201], v[64:67]
	v_mfma_f32_16x16x32_bf16 v[104:107], v[162:165], v[178:181], v[104:107]
	v_mfma_f32_16x16x32_bf16 v[96:99], v[170:173], v[178:181], v[96:99]
	v_mfma_f32_16x16x32_bf16 v[88:91], v[162:165], v[186:189], v[88:91]
	v_mfma_f32_16x16x32_bf16 v[80:83], v[170:173], v[186:189], v[80:83]
	v_mfma_f32_16x16x32_bf16 v[76:79], v[162:165], v[194:197], v[76:79]
	v_mfma_f32_16x16x32_bf16 v[72:75], v[170:173], v[194:197], v[72:75]
	v_mfma_f32_16x16x32_bf16 v[68:71], v[162:165], v[202:205], v[68:71]
	v_mfma_f32_16x16x32_bf16 v[64:67], v[170:173], v[202:205], v[64:67]
	s_setprio 0
	s_barrier
	s_add_i32 s3, s3, s61
	v_lshl_add_u64 v[206:207], s[68:69], 0, v[132:133]
	s_mov_b32 m0, s3
	ds_read_b128 v[174:177], v141 offset:16384
	ds_read_b128 v[178:181], v141 offset:17408
	ds_read_b128 v[182:185], v141 offset:18432
	ds_read_b128 v[186:189], v141 offset:19456
	ds_read_b128 v[190:193], v141 offset:20480
	ds_read_b128 v[194:197], v141 offset:21504
	ds_read_b128 v[198:201], v141 offset:22528
	ds_read_b128 v[202:205], v141 offset:23552
	global_load_lds_dwordx4 v[206:207], off
	s_add_i32 m0, s3, 0x2000
	s_add_u32 s28, s68, 0xb0000
	v_lshl_add_u64 v[214:215], s[68:69], 0, v[128:129]
	s_addc_u32 s29, s69, 0
	s_add_i32 s3, s44, s61
	global_load_lds_dwordx4 v[214:215], off
	v_lshl_add_u64 v[216:217], s[28:29], 0, v[132:133]
	s_mov_b32 m0, s3
	v_lshl_add_u64 v[222:223], s[46:47], 0, v[130:131]
	global_load_lds_dwordx4 v[216:217], off
	v_lshl_add_u64 v[216:217], s[28:29], 0, v[128:129]
	s_add_i32 m0, s3, 0x2000
	s_nop 0
	global_load_lds_dwordx4 v[216:217], off
	v_lshl_add_u64 v[216:217], s[46:47], 0, v[134:135]
	s_mov_b32 m0, s75
	s_nop 0
	global_load_lds_dwordx4 v[216:217], off
	s_mov_b32 m0, s76
	s_nop 0
	global_load_lds_dwordx4 v[222:223], off
	s_waitcnt vmcnt(8)
	s_waitcnt lgkmcnt(0)
	s_barrier
; #define PG8_STAGE(bufoff, gbase, voff) do { _Pragma("unroll") for (int _i = 0; _i < 2; ++_i) \
;         __builtin_amdgcn_global_load_lds((const unsigned*)((const char*)(gbase) + (voff)[_i]), (PG8_LAS unsigned*)(lds + (bufoff) + ldsw + _i * 8192), 16, 0, 0); } while (0)
; #define PG8_LDA(dst, b, h) do { _Pragma("unroll") for (int m = 0; m < 4; ++m) _Pragma("unroll") for (int k = 0; k < 2; ++k) dst[m][k] = *(const PG8_LAS bf16x8*)(lds + PG8_SA(b, h) + aoff + m * 2048 + k * 1024); } while (0)
; #define PG8_LDB(dst, b, h) do { _Pragma("unroll") for (int n = 0; n < 2; ++n) _Pragma("unroll") for (int k = 0; k < 2; ++k) dst[n][k] = *(const PG8_LAS bf16x8*)(lds + PG8_SB(b, h) + boff + n * 2048 + k * 1024); } while (0)
; #define PG8_MMA(ai, bj, At, Bt) do { __builtin_amdgcn_s_setprio(1); _Pragma("unroll") for (int m = 0; m < 4; ++m) _Pragma("unroll") for (int n = 0; n < 2; ++n) _Pragma("unroll") for (int k = 0; k < 2; ++k) \
;         acc[ai][bj][m][n] = __builtin_amdgcn_mfma_f32_16x16x32_bf16(Bt[n][k], At[m][k], acc[ai][bj][m][n], 0, 0, 0); __builtin_amdgcn_s_setprio(0); } while (0)
; #define PG8_WAIT_V(n) asm volatile("s_waitcnt vmcnt(" #n ")" ::: "memory")
; #define PG8_WAIT_L(n) asm volatile("s_waitcnt lgkmcnt(" #n ")" ::: "memory")
; #define PG8_BAR __builtin_amdgcn_s_barrier()
; #define PG8_SCHED __builtin_amdgcn_sched_barrier(0)
; template <class Epi, class Sched, bool ALIGN_EPI = false, bool SP2 = false>
; __device__ __forceinline__ void gemm_phase(PG8_LAS unsigned char* lds, const Gemm g, const Sched& S, const Epi& E) {
;     ...
;             PG8_WAIT_V(8); PG8_WAIT_L(0); PG8_BAR; PG8_MMA(1, 0, At, B0); PG8_MMA(1, 1, At, B1); PG8_BAR; PG8_SCHED;
;             PG8_LDB(B0, 1, 0); PG8_LDB(B1, 1, 1); PG8_SCHED; PG8_LDA(At, 1, 0); PG8_STAGE(PG8_SA(0, 1), a2 + hstep, voffA);
;             PG8_WAIT_V(8); PG8_WAIT_L(0); PG8_BAR; PG8_MMA(0, 0, At, B0); PG8_MMA(0, 1, At, B1); PG8_BAR; PG8_SCHED;
	s_setprio 1
	s_waitcnt lgkmcnt(0)
	v_mfma_f32_16x16x32_bf16 v[60:63], v[142:145], v[174:177], v[60:63]
	v_mfma_f32_16x16x32_bf16 v[56:59], v[150:153], v[174:177], v[56:59]
	v_mfma_f32_16x16x32_bf16 v[52:55], v[142:145], v[182:185], v[52:55]
	v_mfma_f32_16x16x32_bf16 v[48:51], v[150:153], v[182:185], v[48:51]
	v_mfma_f32_16x16x32_bf16 v[40:43], v[142:145], v[190:193], v[40:43]
	v_mfma_f32_16x16x32_bf16 v[32:35], v[150:153], v[190:193], v[32:35]
	v_mfma_f32_16x16x32_bf16 v[24:27], v[142:145], v[198:201], v[24:27]
	v_mfma_f32_16x16x32_bf16 v[16:19], v[150:153], v[198:201], v[16:19]
	v_mfma_f32_16x16x32_bf16 v[60:63], v[146:149], v[178:181], v[60:63]
	v_mfma_f32_16x16x32_bf16 v[56:59], v[154:157], v[178:181], v[56:59]
	v_mfma_f32_16x16x32_bf16 v[52:55], v[146:149], v[186:189], v[52:55]
	v_mfma_f32_16x16x32_bf16 v[48:51], v[154:157], v[186:189], v[48:51]
	v_mfma_f32_16x16x32_bf16 v[40:43], v[146:149], v[194:197], v[40:43]
	v_mfma_f32_16x16x32_bf16 v[32:35], v[154:157], v[194:197], v[32:35]
	v_mfma_f32_16x16x32_bf16 v[24:27], v[146:149], v[202:205], v[24:27]
	v_mfma_f32_16x16x32_bf16 v[16:19], v[154:157], v[202:205], v[16:19]
	s_setprio 0
	s_setprio 1
	v_mfma_f32_16x16x32_bf16 v[44:47], v[158:161], v[174:177], v[44:47]
	v_mfma_f32_16x16x32_bf16 v[36:39], v[166:169], v[174:177], v[36:39]
	v_mfma_f32_16x16x32_bf16 v[28:31], v[158:161], v[182:185], v[28:31]
	v_mfma_f32_16x16x32_bf16 v[20:23], v[166:169], v[182:185], v[20:23]
	v_mfma_f32_16x16x32_bf16 v[12:15], v[158:161], v[190:193], v[12:15]
	v_mfma_f32_16x16x32_bf16 v[8:11], v[166:169], v[190:193], v[8:11]
	v_mfma_f32_16x16x32_bf16 v[4:7], v[158:161], v[198:201], v[4:7]
	v_mfma_f32_16x16x32_bf16 v[0:3], v[166:169], v[198:201], v[0:3]
	v_mfma_f32_16x16x32_bf16 v[44:47], v[162:165], v[178:181], v[44:47]
	v_mfma_f32_16x16x32_bf16 v[36:39], v[170:173], v[178:181], v[36:39]
	v_mfma_f32_16x16x32_bf16 v[28:31], v[162:165], v[186:189], v[28:31]
	v_mfma_f32_16x16x32_bf16 v[20:23], v[170:173], v[186:189], v[20:23]
	v_mfma_f32_16x16x32_bf16 v[12:15], v[162:165], v[194:197], v[12:15]
	v_mfma_f32_16x16x32_bf16 v[8:11], v[170:173], v[194:197], v[8:11]
	v_mfma_f32_16x16x32_bf16 v[4:7], v[162:165], v[202:205], v[4:7]
	v_mfma_f32_16x16x32_bf16 v[0:3], v[170:173], v[202:205], v[0:3]
	s_setprio 0
	s_barrier
	s_add_i32 s3, 0, 0x18000
	s_add_i32 s44, 0, 0x1c000
	v_add_u32_e32 v154, s3, v140
	v_add_u32_e32 v170, s44, v140
	ds_read_b128 v[142:145], v154
	ds_read_b128 v[146:149], v154 offset:1024
	ds_read_b128 v[150:153], v154 offset:2048
	ds_read_b128 v[154:157], v154 offset:3072
	ds_read_b128 v[158:161], v170
	ds_read_b128 v[162:165], v170 offset:1024
	ds_read_b128 v[166:169], v170 offset:2048
	ds_read_b128 v[170:173], v170 offset:3072
	s_add_u32 s28, s46, 0xb0000
	s_addc_u32 s29, s47, 0
	s_mov_b32 m0, s77
	v_lshl_add_u64 v[224:225], s[28:29], 0, v[134:135]
	ds_read_b128 v[174:177], v141 offset:32768
	ds_read_b128 v[178:181], v141 offset:33792
	ds_read_b128 v[182:185], v141 offset:34816
	ds_read_b128 v[186:189], v141 offset:35840
	ds_read_b128 v[190:193], v141 offset:36864
	ds_read_b128 v[194:197], v141 offset:37888
	ds_read_b128 v[198:201], v141 offset:38912
	ds_read_b128 v[202:205], v141 offset:39936
	global_load_lds_dwordx4 v[224:225], off
	v_lshl_add_u64 v[224:225], s[28:29], 0, v[130:131]
	s_mov_b32 m0, s78
	s_nop 0
	global_load_lds_dwordx4 v[224:225], off
	s_waitcnt vmcnt(8)
	s_waitcnt lgkmcnt(0)
	s_barrier
	s_setprio 1
	s_waitcnt lgkmcnt(0)
	v_mfma_f32_16x16x32_bf16 v[124:127], v[142:145], v[174:177], v[124:127]
	v_mfma_f32_16x16x32_bf16 v[120:123], v[150:153], v[174:177], v[120:123]
	v_mfma_f32_16x16x32_bf16 v[116:119], v[142:145], v[182:185], v[116:119]
	v_mfma_f32_16x16x32_bf16 v[112:115], v[150:153], v[182:185], v[112:115]
	v_mfma_f32_16x16x32_bf16 v[108:111], v[142:145], v[190:193], v[108:111]
	v_mfma_f32_16x16x32_bf16 v[100:103], v[150:153], v[190:193], v[100:103]
	v_mfma_f32_16x16x32_bf16 v[92:95], v[142:145], v[198:201], v[92:95]
	v_mfma_f32_16x16x32_bf16 v[84:87], v[150:153], v[198:201], v[84:87]
	v_mfma_f32_16x16x32_bf16 v[124:127], v[146:149], v[178:181], v[124:127]
	v_mfma_f32_16x16x32_bf16 v[120:123], v[154:157], v[178:181], v[120:123]
	v_mfma_f32_16x16x32_bf16 v[116:119], v[146:149], v[186:189], v[116:119]
	v_mfma_f32_16x16x32_bf16 v[112:115], v[154:157], v[186:189], v[112:115]
	v_mfma_f32_16x16x32_bf16 v[108:111], v[146:149], v[194:197], v[108:111]
	v_mfma_f32_16x16x32_bf16 v[100:103], v[154:157], v[194:197], v[100:103]
	v_mfma_f32_16x16x32_bf16 v[92:95], v[146:149], v[202:205], v[92:95]
	v_mfma_f32_16x16x32_bf16 v[84:87], v[154:157], v[202:205], v[84:87]
	s_setprio 0
	s_setprio 1
	v_mfma_f32_16x16x32_bf16 v[104:107], v[158:161], v[174:177], v[104:107]
	v_mfma_f32_16x16x32_bf16 v[96:99], v[166:169], v[174:177], v[96:99]
	v_mfma_f32_16x16x32_bf16 v[88:91], v[158:161], v[182:185], v[88:91]
	v_mfma_f32_16x16x32_bf16 v[80:83], v[166:169], v[182:185], v[80:83]
	v_mfma_f32_16x16x32_bf16 v[76:79], v[158:161], v[190:193], v[76:79]
	v_mfma_f32_16x16x32_bf16 v[72:75], v[166:169], v[190:193], v[72:75]
	v_mfma_f32_16x16x32_bf16 v[68:71], v[158:161], v[198:201], v[68:71]
	v_mfma_f32_16x16x32_bf16 v[64:67], v[166:169], v[198:201], v[64:67]
	v_mfma_f32_16x16x32_bf16 v[104:107], v[162:165], v[178:181], v[104:107]
	v_mfma_f32_16x16x32_bf16 v[96:99], v[170:173], v[178:181], v[96:99]
	v_mfma_f32_16x16x32_bf16 v[88:91], v[162:165], v[186:189], v[88:91]
	v_mfma_f32_16x16x32_bf16 v[80:83], v[170:173], v[186:189], v[80:83]
	v_mfma_f32_16x16x32_bf16 v[76:79], v[162:165], v[194:197], v[76:79]
	v_mfma_f32_16x16x32_bf16 v[72:75], v[170:173], v[194:197], v[72:75]
	v_mfma_f32_16x16x32_bf16 v[68:71], v[162:165], v[202:205], v[68:71]
	v_mfma_f32_16x16x32_bf16 v[64:67], v[170:173], v[202:205], v[64:67]
	s_setprio 0
	s_barrier
; #define PG8_STAGE(bufoff, gbase, voff) do { _Pragma("unroll") for (int _i = 0; _i < 2; ++_i) \
;         __builtin_amdgcn_global_load_lds((const unsigned*)((const char*)(gbase) + (voff)[_i]), (PG8_LAS unsigned*)(lds + (bufoff) + ldsw + _i * 8192), 16, 0, 0); } while (0)
; #define PG8_LDA(dst, b, h) do { _Pragma("unroll") for (int m = 0; m < 4; ++m) _Pragma("unroll") for (int k = 0; k < 2; ++k) dst[m][k] = *(const PG8_LAS bf16x8*)(lds + PG8_SA(b, h) + aoff + m * 2048 + k * 1024); } while (0)
; #define PG8_MMA(ai, bj, At, Bt) do { __builtin_amdgcn_s_setprio(1); _Pragma("unroll") for (int m = 0; m < 4; ++m) _Pragma("unroll") for (int n = 0; n < 2; ++n) _Pragma("unroll") for (int k = 0; k < 2; ++k) \
;         acc[ai][bj][m][n] = __builtin_amdgcn_mfma_f32_16x16x32_bf16(Bt[n][k], At[m][k], acc[ai][bj][m][n], 0, 0, 0); __builtin_amdgcn_s_setprio(0); } while (0)
; #define PG8_WAIT_V(n) asm volatile("s_waitcnt vmcnt(" #n ")" ::: "memory")
; #define PG8_WAIT_L(n) asm volatile("s_waitcnt lgkmcnt(" #n ")" ::: "memory")
; #define PG8_BAR __builtin_amdgcn_s_barrier()
; #define PG8_SCHED __builtin_amdgcn_sched_barrier(0)
; template <class Epi, class Sched, bool ALIGN_EPI = false, bool SP2 = false>
; __device__ __forceinline__ void gemm_phase(PG8_LAS unsigned char* lds, const Gemm g, const Sched& S, const Epi& E) {
;     ...
;         for (int t = 0; t < nt; t += 2) {
;     ...
;             PG8_LDA(At, 1, 1); PG8_STAGE(PG8_SB(1, 0), b3, voffB); PG8_STAGE(PG8_SB(1, 1), b3 + hstep, voffB); PG8_STAGE(PG8_SA(1, 0), a3, voffA);
;             PG8_WAIT_V(8); PG8_WAIT_L(0); PG8_BAR; PG8_MMA(1, 0, At, B0); PG8_MMA(1, 1, At, B1); PG8_BAR; PG8_SCHED;
	s_add_i32 s3, s3, s61
	v_lshl_add_u64 v[206:207], v[206:207], 0, s[36:37]
	s_mov_b32 m0, s3
	ds_read_b128 v[174:177], v141 offset:49152
	ds_read_b128 v[178:181], v141 offset:50176
	ds_read_b128 v[182:185], v141 offset:51200
	ds_read_b128 v[186:189], v141 offset:52224
	ds_read_b128 v[190:193], v141 offset:53248
	ds_read_b128 v[194:197], v141 offset:54272
	ds_read_b128 v[198:201], v141 offset:55296
	ds_read_b128 v[202:205], v141 offset:56320
	global_load_lds_dwordx4 v[206:207], off
	s_add_i32 m0, s3, 0x2000
	s_add_u32 s28, s68, 0xb0080
	v_lshl_add_u64 v[206:207], v[214:215], 0, s[36:37]
	s_addc_u32 s29, s69, 0
	s_add_i32 s3, s44, s61
	global_load_lds_dwordx4 v[206:207], off
	v_lshl_add_u64 v[206:207], s[28:29], 0, v[132:133]
	s_mov_b32 m0, s3
	s_nop 0
	global_load_lds_dwordx4 v[206:207], off
	v_lshl_add_u64 v[206:207], s[28:29], 0, v[128:129]
	s_add_i32 m0, s3, 0x2000
	s_nop 0
	global_load_lds_dwordx4 v[206:207], off
	v_lshl_add_u64 v[206:207], v[216:217], 0, s[36:37]
	s_mov_b32 m0, s83
	s_nop 0
	global_load_lds_dwordx4 v[206:207], off
	v_lshl_add_u64 v[206:207], v[222:223], 0, s[36:37]
	s_mov_b32 m0, s84
	s_nop 0
	global_load_lds_dwordx4 v[206:207], off
	s_waitcnt vmcnt(8)
	s_waitcnt lgkmcnt(0)
	s_barrier
	s_setprio 1
	s_waitcnt lgkmcnt(0)
	v_mfma_f32_16x16x32_bf16 v[60:63], v[142:145], v[174:177], v[60:63]
	v_mfma_f32_16x16x32_bf16 v[56:59], v[150:153], v[174:177], v[56:59]
	v_mfma_f32_16x16x32_bf16 v[52:55], v[142:145], v[182:185], v[52:55]
	v_mfma_f32_16x16x32_bf16 v[48:51], v[150:153], v[182:185], v[48:51]
	v_mfma_f32_16x16x32_bf16 v[40:43], v[142:145], v[190:193], v[40:43]
	v_mfma_f32_16x16x32_bf16 v[32:35], v[150:153], v[190:193], v[32:35]
	v_mfma_f32_16x16x32_bf16 v[24:27], v[142:145], v[198:201], v[24:27]
	v_mfma_f32_16x16x32_bf16 v[16:19], v[150:153], v[198:201], v[16:19]
	v_mfma_f32_16x16x32_bf16 v[60:63], v[146:149], v[178:181], v[60:63]
	v_mfma_f32_16x16x32_bf16 v[56:59], v[154:157], v[178:181], v[56:59]
	v_mfma_f32_16x16x32_bf16 v[52:55], v[146:149], v[186:189], v[52:55]
	v_mfma_f32_16x16x32_bf16 v[48:51], v[154:157], v[186:189], v[48:51]
	v_mfma_f32_16x16x32_bf16 v[40:43], v[146:149], v[194:197], v[40:43]
	v_mfma_f32_16x16x32_bf16 v[32:35], v[154:157], v[194:197], v[32:35]
	v_mfma_f32_16x16x32_bf16 v[24:27], v[146:149], v[202:205], v[24:27]
	v_mfma_f32_16x16x32_bf16 v[16:19], v[154:157], v[202:205], v[16:19]
	s_setprio 0
	s_setprio 1
	v_mfma_f32_16x16x32_bf16 v[44:47], v[158:161], v[174:177], v[44:47]
	v_mfma_f32_16x16x32_bf16 v[36:39], v[166:169], v[174:177], v[36:39]
	v_mfma_f32_16x16x32_bf16 v[28:31], v[158:161], v[182:185], v[28:31]
	v_mfma_f32_16x16x32_bf16 v[20:23], v[166:169], v[182:185], v[20:23]
	v_mfma_f32_16x16x32_bf16 v[12:15], v[158:161], v[190:193], v[12:15]
	v_mfma_f32_16x16x32_bf16 v[8:11], v[166:169], v[190:193], v[8:11]
	v_mfma_f32_16x16x32_bf16 v[4:7], v[158:161], v[198:201], v[4:7]
	v_mfma_f32_16x16x32_bf16 v[0:3], v[166:169], v[198:201], v[0:3]
	v_mfma_f32_16x16x32_bf16 v[44:47], v[162:165], v[178:181], v[44:47]
	v_mfma_f32_16x16x32_bf16 v[36:39], v[170:173], v[178:181], v[36:39]
	v_mfma_f32_16x16x32_bf16 v[28:31], v[162:165], v[186:189], v[28:31]
	v_mfma_f32_16x16x32_bf16 v[20:23], v[170:173], v[186:189], v[20:23]
	v_mfma_f32_16x16x32_bf16 v[12:15], v[162:165], v[194:197], v[12:15]
	v_mfma_f32_16x16x32_bf16 v[8:11], v[170:173], v[194:197], v[8:11]
	v_mfma_f32_16x16x32_bf16 v[4:7], v[162:165], v[202:205], v[4:7]
	v_mfma_f32_16x16x32_bf16 v[0:3], v[170:173], v[202:205], v[0:3]
	s_setprio 0
	s_add_u32 vcc_lo, vcc_lo, 0x100
	s_addc_u32 vcc_hi, vcc_hi, 0
	s_cmp_ge_u32 s91, s80
	s_mov_b64 s[64:65], s[66:67]
	s_mov_b32 s46, s91
	s_barrier
	s_cbranch_scc0 .LBB0_621
	s_and_b64 vcc, exec, s[42:43]
	s_cbranch_vccz .LBB0_624
	s_barrier

; #define PG8_STAGE(bufoff, gbase, voff) do { _Pragma("unroll") for (int _i = 0; _i < 2; ++_i) \
;         __builtin_amdgcn_global_load_lds((const unsigned*)((const char*)(gbase) + (voff)[_i]), (PG8_LAS unsigned*)(lds + (bufoff) + ldsw + _i * 8192), 16, 0, 0); } while (0)
; #define PG8_LDA(dst, b, h) do { _Pragma("unroll") for (int m = 0; m < 4; ++m) _Pragma("unroll") for (int k = 0; k < 2; ++k) dst[m][k] = *(const PG8_LAS bf16x8*)(lds + PG8_SA(b, h) + aoff + m * 2048 + k * 1024); } while (0)
; #define PG8_LDB(dst, b, h) do { _Pragma("unroll") for (int n = 0; n < 2; ++n) _Pragma("unroll") for (int k = 0; k < 2; ++k) dst[n][k] = *(const PG8_LAS bf16x8*)(lds + PG8_SB(b, h) + boff + n * 2048 + k * 1024); } while (0)
; #define PG8_MMA(ai, bj, At, Bt) do { __builtin_amdgcn_s_setprio(1); _Pragma("unroll") for (int m = 0; m < 4; ++m) _Pragma("unroll") for (int n = 0; n < 2; ++n) _Pragma("unroll") for (int k = 0; k < 2; ++k) \
;         acc[ai][bj][m][n] = __builtin_amdgcn_mfma_f32_16x16x32_bf16(Bt[n][k], At[m][k], acc[ai][bj][m][n], 0, 0, 0); __builtin_amdgcn_s_setprio(0); } while (0)
; #define PG8_WAIT_V(n) asm volatile("s_waitcnt vmcnt(" #n ")" ::: "memory")
; #define PG8_WAIT_L(n) asm volatile("s_waitcnt lgkmcnt(" #n ")" ::: "memory")
; template <class Epi, class Sched, bool ALIGN_EPI = false, bool SP2 = false>
; __device__ __forceinline__ void gemm_phase(PG8_LAS unsigned char* lds, const Gemm g, const Sched& S, const Epi& E) {
;     ...
;             const bool last = (t == nt - 2);
;             const char* a1 = cA + (size_t)(t + 1) * kstep;
;             const char* a2 = last ? nA : cA + (size_t)(t + 2) * kstep; const char* b2 = last ? nB : cB + (size_t)(t + 2) * kstep;
;             const char* a3 = a2 + kstep; const char* b3 = b2 + kstep;
;             if (last && has_next) S.a_ready(nxt);
;             if constexpr (SP2) {
;             PG8_LDB(B0, 0, 0); PG8_LDB(B1, 0, 1); PG8_SCHED; PG8_LDA(At, 0, 0); PG8_STAGE(PG8_SA(1, 1), a1 + hstep, voffA);
;             PG8_WAIT_V(8); PG8_WAIT_L(0); PG8_BAR; PG8_MMA(0, 0, At, B0); PG8_MMA(0, 1, At, B1); PG8_BAR; PG8_SCHED;
;             PG8_LDA(At, 0, 1); PG8_STAGE(PG8_SB(0, 0), b2, voffB); PG8_STAGE(PG8_SB(0, 1), b2 + hstep, voffB); PG8_STAGE(PG8_SA(0, 0), a2, voffA);
;             PG8_WAIT_V(8); PG8_WAIT_L(0); PG8_BAR; PG8_MMA(1, 0, At, B0); PG8_MMA(1, 1, At, B1); PG8_BAR; PG8_SCHED;
.LBB0_700:
	s_add_u32 s3, s60, 0xfffc0080
	s_addc_u32 s28, s61, -1
	s_add_i32 s29, 0, 0x10000
	s_cmp_eq_u32 s92, 12
	s_cselect_b32 s47, s30, s28
	s_cselect_b32 s46, s45, s3
	s_cselect_b32 s63, s49, s87
	s_cselect_b32 s62, s51, s86
	s_add_i32 s3, 0, 0x14000
	v_add_u32_e32 v140, s29, v155
	v_add_u32_e32 v154, s3, v155
	ds_read_b128 v[128:131], v140
	ds_read_b128 v[132:135], v140 offset:1024
	ds_read_b128 v[136:139], v140 offset:2048
	ds_read_b128 v[140:143], v140 offset:3072
	ds_read_b128 v[158:161], v154
	ds_read_b128 v[162:165], v154 offset:1024
	ds_read_b128 v[166:169], v154 offset:2048
	ds_read_b128 v[170:173], v154 offset:3072
	v_lshl_add_u64 v[206:207], s[60:61], 0, v[150:151]
	s_add_i32 m0, s59, 0xc000
	ds_read_b128 v[174:177], v157
	ds_read_b128 v[178:181], v157 offset:1024
	ds_read_b128 v[182:185], v157 offset:2048
	ds_read_b128 v[186:189], v157 offset:3072
	ds_read_b128 v[190:193], v157 offset:4096
	ds_read_b128 v[194:197], v157 offset:5120
	ds_read_b128 v[198:201], v157 offset:6144
	ds_read_b128 v[202:205], v157 offset:7168
	global_load_lds_dwordx4 v[206:207], off
	v_lshl_add_u64 v[206:207], s[60:61], 0, v[152:153]
	s_add_i32 m0, s59, 0xe000
	s_nop 0
	global_load_lds_dwordx4 v[206:207], off
	s_waitcnt vmcnt(8)
	s_waitcnt lgkmcnt(0)
	s_barrier
	s_setprio 1
	s_waitcnt lgkmcnt(0)
	v_mfma_f32_16x16x32_bf16 v[124:127], v[128:131], v[174:177], v[124:127]
	v_mfma_f32_16x16x32_bf16 v[120:123], v[136:139], v[174:177], v[120:123]
	v_mfma_f32_16x16x32_bf16 v[108:111], v[128:131], v[182:185], v[108:111]
	v_mfma_f32_16x16x32_bf16 v[104:107], v[136:139], v[182:185], v[104:107]
	v_mfma_f32_16x16x32_bf16 v[92:95], v[128:131], v[190:193], v[92:95]
	v_mfma_f32_16x16x32_bf16 v[88:91], v[136:139], v[190:193], v[88:91]
	v_mfma_f32_16x16x32_bf16 v[76:79], v[128:131], v[198:201], v[76:79]
	v_mfma_f32_16x16x32_bf16 v[72:75], v[136:139], v[198:201], v[72:75]
	v_mfma_f32_16x16x32_bf16 v[124:127], v[132:135], v[178:181], v[124:127]
	v_mfma_f32_16x16x32_bf16 v[120:123], v[140:143], v[178:181], v[120:123]
	v_mfma_f32_16x16x32_bf16 v[108:111], v[132:135], v[186:189], v[108:111]
	v_mfma_f32_16x16x32_bf16 v[104:107], v[140:143], v[186:189], v[104:107]
	v_mfma_f32_16x16x32_bf16 v[92:95], v[132:135], v[194:197], v[92:95]
	v_mfma_f32_16x16x32_bf16 v[88:91], v[140:143], v[194:197], v[88:91]
	v_mfma_f32_16x16x32_bf16 v[76:79], v[132:135], v[202:205], v[76:79]
	v_mfma_f32_16x16x32_bf16 v[72:75], v[140:143], v[202:205], v[72:75]
	s_setprio 0
	s_setprio 1
	v_mfma_f32_16x16x32_bf16 v[116:119], v[158:161], v[174:177], v[116:119]
	v_mfma_f32_16x16x32_bf16 v[112:115], v[166:169], v[174:177], v[112:115]
	v_mfma_f32_16x16x32_bf16 v[100:103], v[158:161], v[182:185], v[100:103]
	v_mfma_f32_16x16x32_bf16 v[96:99], v[166:169], v[182:185], v[96:99]
	v_mfma_f32_16x16x32_bf16 v[84:87], v[158:161], v[190:193], v[84:87]
	v_mfma_f32_16x16x32_bf16 v[80:83], v[166:169], v[190:193], v[80:83]
	v_mfma_f32_16x16x32_bf16 v[68:71], v[158:161], v[198:201], v[68:71]
	v_mfma_f32_16x16x32_bf16 v[64:67], v[166:169], v[198:201], v[64:67]
	v_mfma_f32_16x16x32_bf16 v[116:119], v[162:165], v[178:181], v[116:119]
	v_mfma_f32_16x16x32_bf16 v[112:115], v[170:173], v[178:181], v[112:115]
	v_mfma_f32_16x16x32_bf16 v[100:103], v[162:165], v[186:189], v[100:103]
	v_mfma_f32_16x16x32_bf16 v[96:99], v[170:173], v[186:189], v[96:99]
	v_mfma_f32_16x16x32_bf16 v[84:87], v[162:165], v[194:197], v[84:87]
	v_mfma_f32_16x16x32_bf16 v[80:83], v[170:173], v[194:197], v[80:83]
	v_mfma_f32_16x16x32_bf16 v[68:71], v[162:165], v[202:205], v[68:71]
	v_mfma_f32_16x16x32_bf16 v[64:67], v[170:173], v[202:205], v[64:67]
	s_setprio 0
	s_barrier
	s_add_i32 s28, s29, s35
	v_lshl_add_u64 v[206:207], s[62:63], 0, v[208:209]
	s_mov_b32 m0, s28
	ds_read_b128 v[174:177], v157 offset:16384
	ds_read_b128 v[178:181], v157 offset:17408
	ds_read_b128 v[182:185], v157 offset:18432
	ds_read_b128 v[186:189], v157 offset:19456
	ds_read_b128 v[190:193], v157 offset:20480
	ds_read_b128 v[194:197], v157 offset:21504
	ds_read_b128 v[198:201], v157 offset:22528
	ds_read_b128 v[202:205], v157 offset:23552
	global_load_lds_dwordx4 v[206:207], off
	s_add_i32 m0, s28, 0x2000
	s_add_u32 s28, s62, 0x40000
	v_lshl_add_u64 v[214:215], s[62:63], 0, v[144:145]
	s_addc_u32 s29, s63, 0
	s_add_i32 s3, s3, s35
	global_load_lds_dwordx4 v[214:215], off
	v_lshl_add_u64 v[222:223], s[28:29], 0, v[208:209]
	s_mov_b32 m0, s3
	v_lshl_add_u64 v[224:225], s[46:47], 0, v[146:147]
	global_load_lds_dwordx4 v[222:223], off
	v_lshl_add_u64 v[222:223], s[28:29], 0, v[144:145]
	s_add_i32 m0, s3, 0x2000
	s_nop 0
	global_load_lds_dwordx4 v[222:223], off
	v_lshl_add_u64 v[222:223], s[46:47], 0, v[148:149]
	s_mov_b32 m0, s59
	s_nop 0
	global_load_lds_dwordx4 v[222:223], off
	s_mov_b32 m0, s69
	s_nop 0
	global_load_lds_dwordx4 v[224:225], off
	s_waitcnt vmcnt(8)
	s_waitcnt lgkmcnt(0)
	s_barrier
; #define PG8_STAGE(bufoff, gbase, voff) do { _Pragma("unroll") for (int _i = 0; _i < 2; ++_i) \
;         __builtin_amdgcn_global_load_lds((const unsigned*)((const char*)(gbase) + (voff)[_i]), (PG8_LAS unsigned*)(lds + (bufoff) + ldsw + _i * 8192), 16, 0, 0); } while (0)
; #define PG8_LDA(dst, b, h) do { _Pragma("unroll") for (int m = 0; m < 4; ++m) _Pragma("unroll") for (int k = 0; k < 2; ++k) dst[m][k] = *(const PG8_LAS bf16x8*)(lds + PG8_SA(b, h) + aoff + m * 2048 + k * 1024); } while (0)
; #define PG8_LDB(dst, b, h) do { _Pragma("unroll") for (int n = 0; n < 2; ++n) _Pragma("unroll") for (int k = 0; k < 2; ++k) dst[n][k] = *(const PG8_LAS bf16x8*)(lds + PG8_SB(b, h) + boff + n * 2048 + k * 1024); } while (0)
; #define PG8_MMA(ai, bj, At, Bt) do { __builtin_amdgcn_s_setprio(1); _Pragma("unroll") for (int m = 0; m < 4; ++m) _Pragma("unroll") for (int n = 0; n < 2; ++n) _Pragma("unroll") for (int k = 0; k < 2; ++k) \
;         acc[ai][bj][m][n] = __builtin_amdgcn_mfma_f32_16x16x32_bf16(Bt[n][k], At[m][k], acc[ai][bj][m][n], 0, 0, 0); __builtin_amdgcn_s_setprio(0); } while (0)
; #define PG8_WAIT_V(n) asm volatile("s_waitcnt vmcnt(" #n ")" ::: "memory")
; #define PG8_WAIT_L(n) asm volatile("s_waitcnt lgkmcnt(" #n ")" ::: "memory")
; #define PG8_BAR __builtin_amdgcn_s_barrier()
; #define PG8_SCHED __builtin_amdgcn_sched_barrier(0)
; template <class Epi, class Sched, bool ALIGN_EPI = false, bool SP2 = false>
; __device__ __forceinline__ void gemm_phase(PG8_LAS unsigned char* lds, const Gemm g, const Sched& S, const Epi& E) {
;     ...
;             PG8_WAIT_V(8); PG8_WAIT_L(0); PG8_BAR; PG8_MMA(1, 0, At, B0); PG8_MMA(1, 1, At, B1); PG8_BAR; PG8_SCHED;
;             PG8_LDB(B0, 1, 0); PG8_LDB(B1, 1, 1); PG8_SCHED; PG8_LDA(At, 1, 0); PG8_STAGE(PG8_SA(0, 1), a2 + hstep, voffA);
;             PG8_WAIT_V(8); PG8_WAIT_L(0); PG8_BAR; PG8_MMA(0, 0, At, B0); PG8_MMA(0, 1, At, B1); PG8_BAR; PG8_SCHED;
	s_setprio 1
	s_waitcnt lgkmcnt(0)
	v_mfma_f32_16x16x32_bf16 v[60:63], v[128:131], v[174:177], v[60:63]
	v_mfma_f32_16x16x32_bf16 v[56:59], v[136:139], v[174:177], v[56:59]
	v_mfma_f32_16x16x32_bf16 v[44:47], v[128:131], v[182:185], v[44:47]
	v_mfma_f32_16x16x32_bf16 v[40:43], v[136:139], v[182:185], v[40:43]
	v_mfma_f32_16x16x32_bf16 v[28:31], v[128:131], v[190:193], v[28:31]
	v_mfma_f32_16x16x32_bf16 v[24:27], v[136:139], v[190:193], v[24:27]
	v_mfma_f32_16x16x32_bf16 v[12:15], v[128:131], v[198:201], v[12:15]
	v_mfma_f32_16x16x32_bf16 v[8:11], v[136:139], v[198:201], v[8:11]
	v_mfma_f32_16x16x32_bf16 v[60:63], v[132:135], v[178:181], v[60:63]
	v_mfma_f32_16x16x32_bf16 v[56:59], v[140:143], v[178:181], v[56:59]
	v_mfma_f32_16x16x32_bf16 v[44:47], v[132:135], v[186:189], v[44:47]
	v_mfma_f32_16x16x32_bf16 v[40:43], v[140:143], v[186:189], v[40:43]
	v_mfma_f32_16x16x32_bf16 v[28:31], v[132:135], v[194:197], v[28:31]
	v_mfma_f32_16x16x32_bf16 v[24:27], v[140:143], v[194:197], v[24:27]
	v_mfma_f32_16x16x32_bf16 v[12:15], v[132:135], v[202:205], v[12:15]
	v_mfma_f32_16x16x32_bf16 v[8:11], v[140:143], v[202:205], v[8:11]
	s_setprio 0
	s_setprio 1
	v_mfma_f32_16x16x32_bf16 v[52:55], v[158:161], v[174:177], v[52:55]
	v_mfma_f32_16x16x32_bf16 v[48:51], v[166:169], v[174:177], v[48:51]
	v_mfma_f32_16x16x32_bf16 v[36:39], v[158:161], v[182:185], v[36:39]
	v_mfma_f32_16x16x32_bf16 v[32:35], v[166:169], v[182:185], v[32:35]
	v_mfma_f32_16x16x32_bf16 v[20:23], v[158:161], v[190:193], v[20:23]
	v_mfma_f32_16x16x32_bf16 v[16:19], v[166:169], v[190:193], v[16:19]
	v_mfma_f32_16x16x32_bf16 v[4:7], v[158:161], v[198:201], v[4:7]
	v_mfma_f32_16x16x32_bf16 v[0:3], v[166:169], v[198:201], v[0:3]
	v_mfma_f32_16x16x32_bf16 v[52:55], v[162:165], v[178:181], v[52:55]
	v_mfma_f32_16x16x32_bf16 v[48:51], v[170:173], v[178:181], v[48:51]
	v_mfma_f32_16x16x32_bf16 v[36:39], v[162:165], v[186:189], v[36:39]
	v_mfma_f32_16x16x32_bf16 v[32:35], v[170:173], v[186:189], v[32:35]
	v_mfma_f32_16x16x32_bf16 v[20:23], v[162:165], v[194:197], v[20:23]
	v_mfma_f32_16x16x32_bf16 v[16:19], v[170:173], v[194:197], v[16:19]
	v_mfma_f32_16x16x32_bf16 v[4:7], v[162:165], v[202:205], v[4:7]
	v_mfma_f32_16x16x32_bf16 v[0:3], v[170:173], v[202:205], v[0:3]
	s_setprio 0
	s_barrier
	s_add_i32 s3, 0, 0x18000
	s_add_i32 s44, 0, 0x1c000
	v_add_u32_e32 v140, s3, v155
	v_add_u32_e32 v154, s44, v155
	ds_read_b128 v[128:131], v140
	ds_read_b128 v[132:135], v140 offset:1024
	ds_read_b128 v[136:139], v140 offset:2048
	ds_read_b128 v[140:143], v140 offset:3072
	ds_read_b128 v[158:161], v154
	ds_read_b128 v[162:165], v154 offset:1024
	ds_read_b128 v[166:169], v154 offset:2048
	ds_read_b128 v[170:173], v154 offset:3072
	s_add_u32 s28, s46, 0x40000
	s_addc_u32 s29, s47, 0
	s_mov_b32 m0, s74
	v_lshl_add_u64 v[226:227], s[28:29], 0, v[148:149]
	ds_read_b128 v[174:177], v157 offset:32768
	ds_read_b128 v[178:181], v157 offset:33792
	ds_read_b128 v[182:185], v157 offset:34816
	ds_read_b128 v[186:189], v157 offset:35840
	ds_read_b128 v[190:193], v157 offset:36864
	ds_read_b128 v[194:197], v157 offset:37888
	ds_read_b128 v[198:201], v157 offset:38912
	ds_read_b128 v[202:205], v157 offset:39936
	global_load_lds_dwordx4 v[226:227], off
	v_lshl_add_u64 v[226:227], s[28:29], 0, v[146:147]
	s_mov_b32 m0, s75
	s_nop 0
	global_load_lds_dwordx4 v[226:227], off
	s_waitcnt vmcnt(8)
	s_waitcnt lgkmcnt(0)
	s_barrier
	s_setprio 1
	s_waitcnt lgkmcnt(0)
	v_mfma_f32_16x16x32_bf16 v[124:127], v[128:131], v[174:177], v[124:127]
	v_mfma_f32_16x16x32_bf16 v[120:123], v[136:139], v[174:177], v[120:123]
	v_mfma_f32_16x16x32_bf16 v[108:111], v[128:131], v[182:185], v[108:111]
	v_mfma_f32_16x16x32_bf16 v[104:107], v[136:139], v[182:185], v[104:107]
	v_mfma_f32_16x16x32_bf16 v[92:95], v[128:131], v[190:193], v[92:95]
	v_mfma_f32_16x16x32_bf16 v[88:91], v[136:139], v[190:193], v[88:91]
	v_mfma_f32_16x16x32_bf16 v[76:79], v[128:131], v[198:201], v[76:79]
	v_mfma_f32_16x16x32_bf16 v[72:75], v[136:139], v[198:201], v[72:75]
	v_mfma_f32_16x16x32_bf16 v[124:127], v[132:135], v[178:181], v[124:127]
	v_mfma_f32_16x16x32_bf16 v[120:123], v[140:143], v[178:181], v[120:123]
	v_mfma_f32_16x16x32_bf16 v[108:111], v[132:135], v[186:189], v[108:111]
	v_mfma_f32_16x16x32_bf16 v[104:107], v[140:143], v[186:189], v[104:107]
	v_mfma_f32_16x16x32_bf16 v[92:95], v[132:135], v[194:197], v[92:95]
	v_mfma_f32_16x16x32_bf16 v[88:91], v[140:143], v[194:197], v[88:91]
	v_mfma_f32_16x16x32_bf16 v[76:79], v[132:135], v[202:205], v[76:79]
	v_mfma_f32_16x16x32_bf16 v[72:75], v[140:143], v[202:205], v[72:75]
	s_setprio 0
	s_setprio 1
	v_mfma_f32_16x16x32_bf16 v[116:119], v[158:161], v[174:177], v[116:119]
	v_mfma_f32_16x16x32_bf16 v[112:115], v[166:169], v[174:177], v[112:115]
	v_mfma_f32_16x16x32_bf16 v[100:103], v[158:161], v[182:185], v[100:103]
	v_mfma_f32_16x16x32_bf16 v[96:99], v[166:169], v[182:185], v[96:99]
	v_mfma_f32_16x16x32_bf16 v[84:87], v[158:161], v[190:193], v[84:87]
	v_mfma_f32_16x16x32_bf16 v[80:83], v[166:169], v[190:193], v[80:83]
	v_mfma_f32_16x16x32_bf16 v[68:71], v[158:161], v[198:201], v[68:71]
	v_mfma_f32_16x16x32_bf16 v[64:67], v[166:169], v[198:201], v[64:67]
	v_mfma_f32_16x16x32_bf16 v[116:119], v[162:165], v[178:181], v[116:119]
	v_mfma_f32_16x16x32_bf16 v[112:115], v[170:173], v[178:181], v[112:115]
	v_mfma_f32_16x16x32_bf16 v[100:103], v[162:165], v[186:189], v[100:103]
	v_mfma_f32_16x16x32_bf16 v[96:99], v[170:173], v[186:189], v[96:99]
	v_mfma_f32_16x16x32_bf16 v[84:87], v[162:165], v[194:197], v[84:87]
	v_mfma_f32_16x16x32_bf16 v[80:83], v[170:173], v[194:197], v[80:83]
	v_mfma_f32_16x16x32_bf16 v[68:71], v[162:165], v[202:205], v[68:71]
	v_mfma_f32_16x16x32_bf16 v[64:67], v[170:173], v[202:205], v[64:67]
	s_setprio 0
	s_barrier
; #define PG8_STAGE(bufoff, gbase, voff) do { _Pragma("unroll") for (int _i = 0; _i < 2; ++_i) \
;         __builtin_amdgcn_global_load_lds((const unsigned*)((const char*)(gbase) + (voff)[_i]), (PG8_LAS unsigned*)(lds + (bufoff) + ldsw + _i * 8192), 16, 0, 0); } while (0)
; #define PG8_LDA(dst, b, h) do { _Pragma("unroll") for (int m = 0; m < 4; ++m) _Pragma("unroll") for (int k = 0; k < 2; ++k) dst[m][k] = *(const PG8_LAS bf16x8*)(lds + PG8_SA(b, h) + aoff + m * 2048 + k * 1024); } while (0)
; #define PG8_MMA(ai, bj, At, Bt) do { __builtin_amdgcn_s_setprio(1); _Pragma("unroll") for (int m = 0; m < 4; ++m) _Pragma("unroll") for (int n = 0; n < 2; ++n) _Pragma("unroll") for (int k = 0; k < 2; ++k) \
;         acc[ai][bj][m][n] = __builtin_amdgcn_mfma_f32_16x16x32_bf16(Bt[n][k], At[m][k], acc[ai][bj][m][n], 0, 0, 0); __builtin_amdgcn_s_setprio(0); } while (0)
; #define PG8_WAIT_V(n) asm volatile("s_waitcnt vmcnt(" #n ")" ::: "memory")
; #define PG8_WAIT_L(n) asm volatile("s_waitcnt lgkmcnt(" #n ")" ::: "memory")
; #define PG8_BAR __builtin_amdgcn_s_barrier()
; #define PG8_SCHED __builtin_amdgcn_sched_barrier(0)
; template <class Epi, class Sched, bool ALIGN_EPI = false, bool SP2 = false>
; __device__ __forceinline__ void gemm_phase(PG8_LAS unsigned char* lds, const Gemm g, const Sched& S, const Epi& E) {
;     ...
;         for (int t = 0; t < nt; t += 2) {
;     ...
;             PG8_LDA(At, 1, 1); PG8_STAGE(PG8_SB(1, 0), b3, voffB); PG8_STAGE(PG8_SB(1, 1), b3 + hstep, voffB); PG8_STAGE(PG8_SA(1, 0), a3, voffA);
;             PG8_WAIT_V(8); PG8_WAIT_L(0); PG8_BAR; PG8_MMA(1, 0, At, B0); PG8_MMA(1, 1, At, B1); PG8_BAR; PG8_SCHED;
	s_add_i32 s3, s3, s35
	v_lshl_add_u64 v[206:207], v[206:207], 0, s[36:37]
	s_mov_b32 m0, s3
	ds_read_b128 v[174:177], v157 offset:49152
	ds_read_b128 v[178:181], v157 offset:50176
	ds_read_b128 v[182:185], v157 offset:51200
	ds_read_b128 v[186:189], v157 offset:52224
	ds_read_b128 v[190:193], v157 offset:53248
	ds_read_b128 v[194:197], v157 offset:54272
	ds_read_b128 v[198:201], v157 offset:55296
	ds_read_b128 v[202:205], v157 offset:56320
	global_load_lds_dwordx4 v[206:207], off
	s_add_i32 m0, s3, 0x2000
	s_add_u32 s28, s62, 0x40080
	v_lshl_add_u64 v[206:207], v[214:215], 0, s[36:37]
	s_addc_u32 s29, s63, 0
	s_add_i32 s3, s44, s35
	global_load_lds_dwordx4 v[206:207], off
	v_lshl_add_u64 v[206:207], s[28:29], 0, v[208:209]
	s_mov_b32 m0, s3
	s_nop 0
	global_load_lds_dwordx4 v[206:207], off
	v_lshl_add_u64 v[206:207], s[28:29], 0, v[144:145]
	s_add_i32 m0, s3, 0x2000
	s_nop 0
	global_load_lds_dwordx4 v[206:207], off
	v_lshl_add_u64 v[206:207], v[222:223], 0, s[36:37]
	s_mov_b32 m0, s80
	s_nop 0
	global_load_lds_dwordx4 v[206:207], off
	v_lshl_add_u64 v[206:207], v[224:225], 0, s[36:37]
	s_mov_b32 m0, s81
	s_nop 0
	global_load_lds_dwordx4 v[206:207], off
	s_waitcnt vmcnt(8)
	s_waitcnt lgkmcnt(0)
	s_barrier
	s_setprio 1
	s_waitcnt lgkmcnt(0)
	v_mfma_f32_16x16x32_bf16 v[60:63], v[128:131], v[174:177], v[60:63]
	v_mfma_f32_16x16x32_bf16 v[56:59], v[136:139], v[174:177], v[56:59]
	v_mfma_f32_16x16x32_bf16 v[44:47], v[128:131], v[182:185], v[44:47]
	v_mfma_f32_16x16x32_bf16 v[40:43], v[136:139], v[182:185], v[40:43]
	v_mfma_f32_16x16x32_bf16 v[28:31], v[128:131], v[190:193], v[28:31]
	v_mfma_f32_16x16x32_bf16 v[24:27], v[136:139], v[190:193], v[24:27]
	v_mfma_f32_16x16x32_bf16 v[12:15], v[128:131], v[198:201], v[12:15]
	v_mfma_f32_16x16x32_bf16 v[8:11], v[136:139], v[198:201], v[8:11]
	v_mfma_f32_16x16x32_bf16 v[60:63], v[132:135], v[178:181], v[60:63]
	v_mfma_f32_16x16x32_bf16 v[56:59], v[140:143], v[178:181], v[56:59]
	v_mfma_f32_16x16x32_bf16 v[44:47], v[132:135], v[186:189], v[44:47]
	v_mfma_f32_16x16x32_bf16 v[40:43], v[140:143], v[186:189], v[40:43]
	v_mfma_f32_16x16x32_bf16 v[28:31], v[132:135], v[194:197], v[28:31]
	v_mfma_f32_16x16x32_bf16 v[24:27], v[140:143], v[194:197], v[24:27]
	v_mfma_f32_16x16x32_bf16 v[12:15], v[132:135], v[202:205], v[12:15]
	v_mfma_f32_16x16x32_bf16 v[8:11], v[140:143], v[202:205], v[8:11]
	s_setprio 0
	s_setprio 1
	v_mfma_f32_16x16x32_bf16 v[52:55], v[158:161], v[174:177], v[52:55]
	v_mfma_f32_16x16x32_bf16 v[48:51], v[166:169], v[174:177], v[48:51]
	v_mfma_f32_16x16x32_bf16 v[36:39], v[158:161], v[182:185], v[36:39]
	v_mfma_f32_16x16x32_bf16 v[32:35], v[166:169], v[182:185], v[32:35]
	v_mfma_f32_16x16x32_bf16 v[20:23], v[158:161], v[190:193], v[20:23]
	v_mfma_f32_16x16x32_bf16 v[16:19], v[166:169], v[190:193], v[16:19]
	v_mfma_f32_16x16x32_bf16 v[4:7], v[158:161], v[198:201], v[4:7]
	v_mfma_f32_16x16x32_bf16 v[0:3], v[166:169], v[198:201], v[0:3]
	v_mfma_f32_16x16x32_bf16 v[52:55], v[162:165], v[178:181], v[52:55]
	v_mfma_f32_16x16x32_bf16 v[48:51], v[170:173], v[178:181], v[48:51]
	v_mfma_f32_16x16x32_bf16 v[36:39], v[162:165], v[186:189], v[36:39]
	v_mfma_f32_16x16x32_bf16 v[32:35], v[170:173], v[186:189], v[32:35]
	v_mfma_f32_16x16x32_bf16 v[20:23], v[162:165], v[194:197], v[20:23]
	v_mfma_f32_16x16x32_bf16 v[16:19], v[170:173], v[194:197], v[16:19]
	v_mfma_f32_16x16x32_bf16 v[4:7], v[162:165], v[202:205], v[4:7]
	v_mfma_f32_16x16x32_bf16 v[0:3], v[170:173], v[202:205], v[0:3]
	s_setprio 0
	s_add_i32 s92, s92, 2
	s_add_u32 s60, s60, 0x100
	s_addc_u32 s61, s61, 0
	s_add_u32 s86, s86, 0x100
	s_addc_u32 s87, s87, 0
	s_cmp_gt_u32 s92, 13
	s_barrier
	s_cbranch_scc0 .LBB0_700
	s_and_b64 vcc, exec, s[42:43]
	s_cbranch_vccz .LBB0_703
	s_barrier

; #define PG8_STAGE(bufoff, gbase, voff) do { _Pragma("unroll") for (int _i = 0; _i < 2; ++_i) \
;         __builtin_amdgcn_global_load_lds((const unsigned*)((const char*)(gbase) + (voff)[_i]), (PG8_LAS unsigned*)(lds + (bufoff) + ldsw + _i * 8192), 16, 0, 0); } while (0)
; #define PG8_LDA(dst, b, h) do { _Pragma("unroll") for (int m = 0; m < 4; ++m) _Pragma("unroll") for (int k = 0; k < 2; ++k) dst[m][k] = *(const PG8_LAS bf16x8*)(lds + PG8_SA(b, h) + aoff + m * 2048 + k * 1024); } while (0)
; #define PG8_LDB(dst, b, h) do { _Pragma("unroll") for (int n = 0; n < 2; ++n) _Pragma("unroll") for (int k = 0; k < 2; ++k) dst[n][k] = *(const PG8_LAS bf16x8*)(lds + PG8_SB(b, h) + boff + n * 2048 + k * 1024); } while (0)
; #define PG8_BAR __builtin_amdgcn_s_barrier()
; template <class Epi, class Sched, bool ALIGN_EPI = false, bool SP2 = false>
; __device__ __forceinline__ void gemm_phase(PG8_LAS unsigned char* lds, const Gemm g, const Sched& S, const Epi& E) {
;     ...
;             const bool last = (t == nt - 2);
;             const char* a1 = cA + (size_t)(t + 1) * kstep;
;             const char* a2 = last ? nA : cA + (size_t)(t + 2) * kstep; const char* b2 = last ? nB : cB + (size_t)(t + 2) * kstep;
;             const char* a3 = a2 + kstep; const char* b3 = b2 + kstep;
;             if (last && has_next) S.a_ready(nxt);
;             if constexpr (SP2) {
;             PG8_LDB(B0, 0, 0); PG8_LDB(B1, 0, 1); PG8_SCHED; PG8_LDA(At, 0, 0); PG8_STAGE(PG8_SA(1, 1), a1 + hstep, voffA);
;             PG8_WAIT_V(8); PG8_WAIT_L(0); PG8_BAR; PG8_MMA(0, 0, At, B0); PG8_MMA(0, 1, At, B1); PG8_BAR; PG8_SCHED;
;             PG8_LDA(At, 0, 1); PG8_STAGE(PG8_SB(0, 0), b2, voffB); PG8_STAGE(PG8_SB(0, 1), b2 + hstep, voffB); PG8_STAGE(PG8_SA(0, 0), a2, voffA);
;             PG8_WAIT_V(8); PG8_WAIT_L(0); PG8_BAR; PG8_MMA(1, 0, At, B0); PG8_MMA(1, 1, At, B1); PG8_BAR; PG8_SCHED;
;             PG8_LDB(B0, 1, 0); PG8_LDB(B1, 1, 1); PG8_SCHED; PG8_LDA(At, 1, 0); PG8_STAGE(PG8_SA(0, 1), a2 + hstep, voffA);
;             PG8_WAIT_V(8); PG8_WAIT_L(0); PG8_BAR; PG8_MMA(0, 0, At, B0); PG8_MMA(0, 1, At, B1); PG8_BAR; PG8_SCHED;
;             PG8_LDA(At, 1, 1); PG8_STAGE(PG8_SB(1, 0), b3, voffB); PG8_STAGE(PG8_SB(1, 1), b3 + hstep, voffB); PG8_STAGE(PG8_SA(1, 0), a3, voffA);
;             PG8_WAIT_V(8); PG8_WAIT_L(0); PG8_BAR; PG8_MMA(1, 0, At, B0); PG8_MMA(1, 1, At, B1); PG8_BAR; PG8_SCHED;
.LBB0_771:
	s_add_u32 s28, s64, 0xfffc0080
	s_addc_u32 s29, s65, -1
	s_add_i32 s3, 0, 0x10000
	s_cmp_eq_u32 s44, 12
	s_cselect_b32 s67, s43, s29
	s_cselect_b32 s66, s57, s28
	s_cselect_b32 s63, s55, vcc_hi
	s_cselect_b32 s62, s97, vcc_lo
	s_add_i32 s90, 0, 0x14000
	v_add_u32_e32 v38, s3, v24
	v_add_u32_e32 v54, s90, v24
	ds_read_b128 v[26:29], v38
	ds_read_b128 v[30:33], v38 offset:1024
	ds_read_b128 v[34:37], v38 offset:2048
	ds_read_b128 v[38:41], v38 offset:3072
	ds_read_b128 v[42:45], v54
	ds_read_b128 v[46:49], v54 offset:1024
	ds_read_b128 v[50:53], v54 offset:2048
	ds_read_b128 v[54:57], v54 offset:3072
	v_lshl_add_u64 v[66:67], s[64:65], 0, v[20:21]
	s_add_i32 m0, s83, 0xc000
	ds_read_b128 v[58:61], v25
	ds_read_b128 v[62:65], v25 offset:1024
	global_load_lds_dwordx4 v[66:67], off
	v_lshl_add_u64 v[66:67], s[64:65], 0, v[22:23]
	s_add_i32 m0, s83, 0xe000
	s_nop 0
	global_load_lds_dwordx4 v[66:67], off
	s_waitcnt vmcnt(8)
	s_waitcnt lgkmcnt(0)
	s_barrier
	s_setprio 1
	s_waitcnt lgkmcnt(0)
	v_mfma_f32_16x16x32_bf16 v[12:15], v[26:29], v[58:61], v[12:15]
	v_mfma_f32_16x16x32_bf16 v[8:11], v[34:37], v[58:61], v[8:11]
	v_mfma_f32_16x16x32_bf16 v[12:15], v[30:33], v[62:65], v[12:15]
	v_mfma_f32_16x16x32_bf16 v[8:11], v[38:41], v[62:65], v[8:11]
	s_setprio 0
	s_setprio 1
	v_mfma_f32_16x16x32_bf16 v[4:7], v[42:45], v[58:61], v[4:7]
	v_mfma_f32_16x16x32_bf16 v[0:3], v[50:53], v[58:61], v[0:3]
	v_mfma_f32_16x16x32_bf16 v[4:7], v[46:49], v[62:65], v[4:7]
	v_mfma_f32_16x16x32_bf16 v[0:3], v[54:57], v[62:65], v[0:3]
	s_setprio 0
	s_barrier
	s_add_i32 s3, s3, s80
	v_lshl_add_u64 v[66:67], s[62:63], 0, v[16:17]
	s_mov_b32 m0, s3
	v_lshl_add_u64 v[68:69], s[62:63], 0, v[18:19]
	global_load_lds_dwordx4 v[66:67], off
	s_add_i32 m0, s3, 0x2000
	s_add_u32 s28, s62, 0x40000
	s_addc_u32 s29, s63, 0
	s_add_i32 s3, s90, s80
	global_load_lds_dwordx4 v[68:69], off
	v_lshl_add_u64 v[26:27], s[28:29], 0, v[16:17]
	s_mov_b32 m0, s3
	v_lshl_add_u64 v[70:71], s[66:67], 0, v[16:17]
	global_load_lds_dwordx4 v[26:27], off
	v_lshl_add_u64 v[26:27], s[28:29], 0, v[18:19]
	s_add_i32 m0, s3, 0x2000
	v_lshl_add_u64 v[72:73], s[66:67], 0, v[18:19]
	global_load_lds_dwordx4 v[26:27], off
	s_mov_b32 m0, s83
	s_nop 0
	global_load_lds_dwordx4 v[70:71], off
	s_mov_b32 m0, s84
	s_nop 0
	global_load_lds_dwordx4 v[72:73], off
	s_waitcnt vmcnt(8)
	s_waitcnt lgkmcnt(0)
	s_barrier
	s_setprio 1
	s_setprio 0
	s_setprio 1
	s_setprio 0
	s_barrier
	s_add_i32 s3, 0, 0x18000
	s_add_i32 s90, 0, 0x1c000
	v_add_u32_e32 v38, s3, v24
	v_add_u32_e32 v54, s90, v24
	ds_read_b128 v[26:29], v38
	ds_read_b128 v[30:33], v38 offset:1024
	ds_read_b128 v[34:37], v38 offset:2048
	ds_read_b128 v[38:41], v38 offset:3072
	ds_read_b128 v[42:45], v54
	ds_read_b128 v[46:49], v54 offset:1024
	ds_read_b128 v[50:53], v54 offset:2048
	ds_read_b128 v[54:57], v54 offset:3072
	s_add_u32 s28, s66, 0x40000
	s_addc_u32 s29, s67, 0
	s_mov_b32 m0, s85
	v_lshl_add_u64 v[74:75], s[28:29], 0, v[16:17]
	ds_read_b128 v[58:61], v25 offset:32768
	ds_read_b128 v[62:65], v25 offset:33792
	global_load_lds_dwordx4 v[74:75], off
	v_lshl_add_u64 v[74:75], s[28:29], 0, v[18:19]
	s_mov_b32 m0, s86
	s_nop 0
	global_load_lds_dwordx4 v[74:75], off
	s_waitcnt vmcnt(8)
	s_waitcnt lgkmcnt(0)
	s_barrier
	s_setprio 1
	s_waitcnt lgkmcnt(0)
	v_mfma_f32_16x16x32_bf16 v[12:15], v[26:29], v[58:61], v[12:15]
	v_mfma_f32_16x16x32_bf16 v[8:11], v[34:37], v[58:61], v[8:11]
	v_mfma_f32_16x16x32_bf16 v[12:15], v[30:33], v[62:65], v[12:15]
	v_mfma_f32_16x16x32_bf16 v[8:11], v[38:41], v[62:65], v[8:11]
	s_setprio 0
	s_setprio 1
	v_mfma_f32_16x16x32_bf16 v[4:7], v[42:45], v[58:61], v[4:7]
	v_mfma_f32_16x16x32_bf16 v[0:3], v[50:53], v[58:61], v[0:3]
	v_mfma_f32_16x16x32_bf16 v[4:7], v[46:49], v[62:65], v[4:7]
	v_mfma_f32_16x16x32_bf16 v[0:3], v[54:57], v[62:65], v[0:3]
	s_setprio 0
	s_barrier
	s_add_i32 s3, s3, s80
	v_lshl_add_u64 v[26:27], v[66:67], 0, s[36:37]
	s_mov_b32 m0, s3
	s_nop 0
	global_load_lds_dwordx4 v[26:27], off
	s_add_i32 m0, s3, 0x2000
	s_add_u32 s28, s62, 0x40080
	v_lshl_add_u64 v[26:27], v[68:69], 0, s[36:37]
	s_addc_u32 s29, s63, 0
	s_add_i32 s3, s90, s80
	global_load_lds_dwordx4 v[26:27], off
	v_lshl_add_u64 v[26:27], s[28:29], 0, v[16:17]
	s_mov_b32 m0, s3
	s_nop 0
	global_load_lds_dwordx4 v[26:27], off
	v_lshl_add_u64 v[26:27], s[28:29], 0, v[18:19]
	s_add_i32 m0, s3, 0x2000
	s_nop 0
	global_load_lds_dwordx4 v[26:27], off
	v_lshl_add_u64 v[26:27], v[70:71], 0, s[36:37]
	s_mov_b32 m0, s87
	s_nop 0
	global_load_lds_dwordx4 v[26:27], off
	v_lshl_add_u64 v[26:27], v[72:73], 0, s[36:37]
	s_mov_b32 m0, s92
	s_nop 0
	global_load_lds_dwordx4 v[26:27], off
	s_waitcnt vmcnt(8)
	s_waitcnt lgkmcnt(0)
	s_barrier
	s_setprio 1
	s_setprio 0
	s_setprio 1
	s_setprio 0
	s_add_i32 s44, s44, 2
	s_add_u32 s64, s64, 0x100
	s_addc_u32 s65, s65, 0
	s_add_u32 vcc_lo, vcc_lo, 0x100
	s_addc_u32 vcc_hi, vcc_hi, 0
	s_cmp_gt_u32 s44, 13
	s_barrier
	s_cbranch_scc0 .LBB0_771
	s_and_b64 vcc, exec, s[48:49]
	s_cbranch_vccz .LBB0_774
	s_barrier
